# byte-phase pinning: every barrier-delimited GEMM K-loop block of back-to-back 8-byte MFMAs starts on an 8-byte boundary (22 s_nop 0 pads placed in the load segments ahead of their closing waits); on t
# baseline (speedup 1.0000x reference)
; template <class Epi, class Sched, bool ALIGN_EPI = false, bool SP2 = false>
; __device__ __forceinline__ void gemm_phase(PG8_LAS unsigned char* lds, const Gemm g, const Sched& S, const Epi& E, const int wid) {
;     ...
;         const bool has_next = S.next(ui + 1, nxt);
;         const char* nA = has_next ? (const char*)g.A + (size_t)nxt.pm * tstep : cA; const char* nB = has_next ? (const char*)g.Bt + (size_t)nxt.pn * tstep : cB;
;         for (int t = 0; t < nt; t += 2) {
;             const bool last = (t == nt - 2);
;             const char* a1 = cA + (size_t)(t + 1) * kstep;
;             const char* a2 = last ? nA : cA + (size_t)(t + 2) * kstep; const char* b2 = last ? nB : cB + (size_t)(t + 2) * kstep;
;             const char* a3 = a2 + kstep; const char* b3 = b2 + kstep;
.LBB0_268:
	s_ashr_i32 s15, s14, 31
	s_lshl_b64 s[16:17], s[14:15], 19
	s_add_u32 s16, s80, s16
	s_addc_u32 s17, s81, s17
	s_and_b64 s[18:19], s[4:5], exec
	s_cselect_b32 s15, s17, s23
	s_cselect_b32 s44, s16, s22
	s_ashr_i32 s13, s12, 31
	s_lshl_b64 s[18:19], s[12:13], 19
	s_add_u32 s18, s10, s18
	s_addc_u32 s19, s11, s19
	s_and_b64 s[26:27], s[4:5], exec
	s_cselect_b32 s13, s19, s25
	s_cselect_b32 s45, s18, s24
	s_add_u32 s22, s22, 0x40080
	s_addc_u32 s23, s23, 0
	s_add_u32 s46, s24, 0x100

; template <class Epi, class Sched, bool ALIGN_EPI = false, bool SP2 = false>
; __device__ __forceinline__ void gemm_phase(PG8_LAS unsigned char* lds, const Gemm g, const Sched& S, const Epi& E, const int wid) {
;     ...
;         for (int t = 0; t < nt; t += 2) {
;             const bool last = (t == nt - 2);
;             const char* a1 = cA + (size_t)(t + 1) * kstep;
;             const char* a2 = last ? nA : cA + (size_t)(t + 2) * kstep; const char* b2 = last ? nB : cB + (size_t)(t + 2) * kstep;
;             const char* a3 = a2 + kstep; const char* b3 = b2 + kstep;
	s_addc_u32 s47, s25, 0
	s_mov_b32 s48, -2


; #define PG8_STAGE(bufoff, gbase, voff) do { _Pragma("unroll") for (int _i = 0; _i < 2; ++_i) \
;         __builtin_amdgcn_global_load_lds((const unsigned*)((const char*)(gbase) + (voff)[_i]), (PG8_LAS unsigned*)(lds + (bufoff) + ldsw + _i * 8192), 16, 0, 0); } while (0)
; #define PG8_LDA(dst, b, h) do { _Pragma("unroll") for (int m = 0; m < 4; ++m) _Pragma("unroll") for (int k = 0; k < 2; ++k) dst[m][k] = *(const PG8_LAS bf16x8*)(lds + PG8_SA(b, h) + aoff + m * 2048 + k * 1024); } while (0)
; #define PG8_LDB(dst, b, h) do { _Pragma("unroll") for (int n = 0; n < 2; ++n) _Pragma("unroll") for (int k = 0; k < 2; ++k) dst[n][k] = *(const PG8_LAS bf16x8*)(lds + PG8_SB(b, h) + boff + n * 2048 + k * 1024); } while (0)
; #define PG8_MMA(ai, bj, At, Bt) do { __builtin_amdgcn_s_setprio(1); _Pragma("unroll") for (int m = 0; m < 4; ++m) _Pragma("unroll") for (int n = 0; n < 2; ++n) _Pragma("unroll") for (int k = 0; k < 2; ++k) \
;         acc[ai][bj][m][n] = __builtin_amdgcn_mfma_f32_16x16x32_bf16(Bt[n][k], At[m][k], acc[ai][bj][m][n], 0, 0, 0); __builtin_amdgcn_s_setprio(0); } while (0)
; #define PG8_WAIT_V(n) asm volatile("s_waitcnt vmcnt(" #n ")" ::: "memory")
; #define PG8_WAIT_L(n) asm volatile("s_waitcnt lgkmcnt(" #n ")" ::: "memory")
; #define PG8_BAR __builtin_amdgcn_s_barrier()
; #define PG8_SCHED __builtin_amdgcn_sched_barrier(0)
; template <class Epi, class Sched, bool ALIGN_EPI = false, bool SP2 = false>
; __device__ __forceinline__ void gemm_phase(PG8_LAS unsigned char* lds, const Gemm g, const Sched& S, const Epi& E, const int wid) {
;     ...
;             PG8_LDB(B0, 0, 0); PG8_LDB(B1, 0, 1); PG8_SCHED; PG8_LDA(At, 0, 0); PG8_STAGE(PG8_SA(1, 1), a1 + hstep, voffA);
;             PG8_WAIT_V(8); PG8_WAIT_L(0); PG8_BAR; PG8_MMA(0, 0, At, B0); PG8_MMA(0, 1, At, B1); PG8_BAR; PG8_SCHED;
;             PG8_LDA(At, 0, 1); PG8_STAGE(PG8_SB(0, 0), b2, voffB); PG8_STAGE(PG8_SB(0, 1), b2 + hstep, voffB); PG8_STAGE(PG8_SA(0, 0), a2, voffA);
;             PG8_WAIT_V(8); PG8_WAIT_L(0); PG8_BAR; PG8_MMA(1, 0, At, B0); PG8_MMA(1, 1, At, B1); PG8_BAR; PG8_SCHED;
	ds_read_b128 v[144:147], v151
	ds_read_b128 v[154:157], v151 offset:1024
	ds_read_b128 v[158:161], v151 offset:2048
	ds_read_b128 v[162:165], v151 offset:3072
	ds_read_b128 v[166:169], v152
	ds_read_b128 v[170:173], v152 offset:1024
	ds_read_b128 v[174:177], v152 offset:2048
	ds_read_b128 v[178:181], v152 offset:3072
	s_add_u32 s24, s22, 0xfffc0080
	s_addc_u32 s25, s23, -1
	s_cmp_eq_u32 s48, 12
	s_cselect_b32 s27, s15, s25
	s_cselect_b32 s26, s44, s24
	s_cselect_b32 s25, s13, s47
	s_cselect_b32 s24, s45, s46
	v_lshl_add_u64 v[206:207], s[22:23], 0, v[136:137]
	s_add_i32 m0, s21, 0xc000
	ds_read_b128 v[182:185], v153
	ds_read_b128 v[186:189], v153 offset:1024
	ds_read_b128 v[190:193], v153 offset:2048
	ds_read_b128 v[194:197], v153 offset:3072
	ds_read_b128 v[198:201], v153 offset:4096
	ds_read_b128 v[202:205], v153 offset:5120
	ds_read_b128 v[212:215], v153 offset:6144
	ds_read_b128 v[216:219], v153 offset:7168
	global_load_lds_dwordx4 v[206:207], off
	v_lshl_add_u64 v[206:207], s[22:23], 0, v[138:139]
	s_add_i32 m0, s21, 0xe000
	s_nop 0
	global_load_lds_dwordx4 v[206:207], off
	s_nop 0
	s_waitcnt vmcnt(8)
	s_waitcnt lgkmcnt(0)
	s_barrier
	s_waitcnt lgkmcnt(0)
	v_mfma_f32_16x16x32_bf16 v[124:127], v[144:147], v[182:185], 0
	v_mfma_f32_16x16x32_bf16 v[116:119], v[158:161], v[182:185], 0
	v_mfma_f32_16x16x32_bf16 v[108:111], v[144:147], v[190:193], 0
	v_mfma_f32_16x16x32_bf16 v[100:103], v[158:161], v[190:193], 0
	v_mfma_f32_16x16x32_bf16 v[92:95], v[144:147], v[198:201], 0
	v_mfma_f32_16x16x32_bf16 v[84:87], v[158:161], v[198:201], 0
	v_mfma_f32_16x16x32_bf16 v[76:79], v[144:147], v[212:215], 0
	v_mfma_f32_16x16x32_bf16 v[68:71], v[158:161], v[212:215], 0
	v_mfma_f32_16x16x32_bf16 v[124:127], v[154:157], v[186:189], v[124:127]
	v_mfma_f32_16x16x32_bf16 v[116:119], v[162:165], v[186:189], v[116:119]
	v_mfma_f32_16x16x32_bf16 v[108:111], v[154:157], v[194:197], v[108:111]
	v_mfma_f32_16x16x32_bf16 v[100:103], v[162:165], v[194:197], v[100:103]
	v_mfma_f32_16x16x32_bf16 v[92:95], v[154:157], v[202:205], v[92:95]
	v_mfma_f32_16x16x32_bf16 v[84:87], v[162:165], v[202:205], v[84:87]
	v_mfma_f32_16x16x32_bf16 v[76:79], v[154:157], v[216:219], v[76:79]
	v_mfma_f32_16x16x32_bf16 v[68:71], v[162:165], v[216:219], v[68:71]
	v_mfma_f32_16x16x32_bf16 v[120:123], v[166:169], v[182:185], 0
	v_mfma_f32_16x16x32_bf16 v[112:115], v[174:177], v[182:185], 0
	v_mfma_f32_16x16x32_bf16 v[104:107], v[166:169], v[190:193], 0
	v_mfma_f32_16x16x32_bf16 v[96:99], v[174:177], v[190:193], 0
	v_mfma_f32_16x16x32_bf16 v[88:91], v[166:169], v[198:201], 0
	v_mfma_f32_16x16x32_bf16 v[80:83], v[174:177], v[198:201], 0
	v_mfma_f32_16x16x32_bf16 v[72:75], v[166:169], v[212:215], 0
	v_mfma_f32_16x16x32_bf16 v[64:67], v[174:177], v[212:215], 0
	v_mfma_f32_16x16x32_bf16 v[120:123], v[170:173], v[186:189], v[120:123]
	v_mfma_f32_16x16x32_bf16 v[112:115], v[178:181], v[186:189], v[112:115]
	v_mfma_f32_16x16x32_bf16 v[104:107], v[170:173], v[194:197], v[104:107]
	v_mfma_f32_16x16x32_bf16 v[96:99], v[178:181], v[194:197], v[96:99]
	v_mfma_f32_16x16x32_bf16 v[88:91], v[170:173], v[202:205], v[88:91]
	v_mfma_f32_16x16x32_bf16 v[80:83], v[178:181], v[202:205], v[80:83]
	v_mfma_f32_16x16x32_bf16 v[72:75], v[170:173], v[216:219], v[72:75]
	v_mfma_f32_16x16x32_bf16 v[64:67], v[178:181], v[216:219], v[64:67]
	s_barrier
	s_add_i32 s49, s40, s9
	v_lshl_add_u64 v[206:207], s[24:25], 0, v[132:133]
	s_mov_b32 m0, s49
	ds_read_b128 v[182:185], v153 offset:16384
	ds_read_b128 v[186:189], v153 offset:17408
	ds_read_b128 v[190:193], v153 offset:18432
	ds_read_b128 v[194:197], v153 offset:19456
	ds_read_b128 v[198:201], v153 offset:20480
	ds_read_b128 v[202:205], v153 offset:21504
	ds_read_b128 v[212:215], v153 offset:22528
	ds_read_b128 v[216:219], v153 offset:23552
	global_load_lds_dwordx4 v[206:207], off
	s_add_i32 m0, s49, 0x2000
	s_add_u32 s50, s24, 0x40000
	v_lshl_add_u64 v[220:221], s[24:25], 0, v[128:129]
	s_addc_u32 s51, s25, 0
	s_add_i32 s49, s41, s9
	global_load_lds_dwordx4 v[220:221], off
	v_lshl_add_u64 v[222:223], s[50:51], 0, v[132:133]
	s_mov_b32 m0, s49
	v_lshl_add_u64 v[224:225], s[26:27], 0, v[130:131]
	global_load_lds_dwordx4 v[222:223], off
	v_lshl_add_u64 v[222:223], s[50:51], 0, v[128:129]
	s_add_i32 m0, s49, 0x2000
	s_nop 0
	global_load_lds_dwordx4 v[222:223], off
	v_lshl_add_u64 v[222:223], s[26:27], 0, v[134:135]
	s_mov_b32 m0, s21
	s_nop 0
	global_load_lds_dwordx4 v[222:223], off
	s_mov_b32 m0, s30
	s_nop 0
	global_load_lds_dwordx4 v[224:225], off
	s_nop 0
	s_waitcnt vmcnt(8)
	s_waitcnt lgkmcnt(0)
	s_barrier
	s_waitcnt lgkmcnt(0)
	v_mfma_f32_16x16x32_bf16 v[60:63], v[144:147], v[182:185], 0
	v_mfma_f32_16x16x32_bf16 v[52:55], v[158:161], v[182:185], 0
	v_mfma_f32_16x16x32_bf16 v[44:47], v[144:147], v[190:193], 0
	v_mfma_f32_16x16x32_bf16 v[36:39], v[158:161], v[190:193], 0
	v_mfma_f32_16x16x32_bf16 v[28:31], v[144:147], v[198:201], 0
	v_mfma_f32_16x16x32_bf16 v[20:23], v[158:161], v[198:201], 0
	v_mfma_f32_16x16x32_bf16 v[12:15], v[144:147], v[212:215], 0
	v_mfma_f32_16x16x32_bf16 v[4:7], v[158:161], v[212:215], 0
	v_mfma_f32_16x16x32_bf16 v[60:63], v[154:157], v[186:189], v[60:63]
	v_mfma_f32_16x16x32_bf16 v[52:55], v[162:165], v[186:189], v[52:55]
	v_mfma_f32_16x16x32_bf16 v[44:47], v[154:157], v[194:197], v[44:47]
	v_mfma_f32_16x16x32_bf16 v[36:39], v[162:165], v[194:197], v[36:39]
	v_mfma_f32_16x16x32_bf16 v[28:31], v[154:157], v[202:205], v[28:31]
	v_mfma_f32_16x16x32_bf16 v[20:23], v[162:165], v[202:205], v[20:23]
	v_mfma_f32_16x16x32_bf16 v[12:15], v[154:157], v[216:219], v[12:15]
	v_mfma_f32_16x16x32_bf16 v[4:7], v[162:165], v[216:219], v[4:7]
	v_mfma_f32_16x16x32_bf16 v[56:59], v[166:169], v[182:185], 0
	v_mfma_f32_16x16x32_bf16 v[48:51], v[174:177], v[182:185], 0
	v_mfma_f32_16x16x32_bf16 v[40:43], v[166:169], v[190:193], 0
	v_mfma_f32_16x16x32_bf16 v[32:35], v[174:177], v[190:193], 0
	v_mfma_f32_16x16x32_bf16 v[24:27], v[166:169], v[198:201], 0
	v_mfma_f32_16x16x32_bf16 v[16:19], v[174:177], v[198:201], 0
	v_mfma_f32_16x16x32_bf16 v[8:11], v[166:169], v[212:215], 0
	v_mfma_f32_16x16x32_bf16 v[0:3], v[174:177], v[212:215], 0
	v_mfma_f32_16x16x32_bf16 v[56:59], v[170:173], v[186:189], v[56:59]
	v_mfma_f32_16x16x32_bf16 v[48:51], v[178:181], v[186:189], v[48:51]
	v_mfma_f32_16x16x32_bf16 v[40:43], v[170:173], v[194:197], v[40:43]
	v_mfma_f32_16x16x32_bf16 v[32:35], v[178:181], v[194:197], v[32:35]
	v_mfma_f32_16x16x32_bf16 v[24:27], v[170:173], v[202:205], v[24:27]
	v_mfma_f32_16x16x32_bf16 v[16:19], v[178:181], v[202:205], v[16:19]
	v_mfma_f32_16x16x32_bf16 v[8:11], v[170:173], v[216:219], v[8:11]
	v_mfma_f32_16x16x32_bf16 v[0:3], v[178:181], v[216:219], v[0:3]
	s_barrier
; #define PG8_STAGE(bufoff, gbase, voff) do { _Pragma("unroll") for (int _i = 0; _i < 2; ++_i) \
;         __builtin_amdgcn_global_load_lds((const unsigned*)((const char*)(gbase) + (voff)[_i]), (PG8_LAS unsigned*)(lds + (bufoff) + ldsw + _i * 8192), 16, 0, 0); } while (0)
; #define PG8_LDA(dst, b, h) do { _Pragma("unroll") for (int m = 0; m < 4; ++m) _Pragma("unroll") for (int k = 0; k < 2; ++k) dst[m][k] = *(const PG8_LAS bf16x8*)(lds + PG8_SA(b, h) + aoff + m * 2048 + k * 1024); } while (0)
; #define PG8_LDB(dst, b, h) do { _Pragma("unroll") for (int n = 0; n < 2; ++n) _Pragma("unroll") for (int k = 0; k < 2; ++k) dst[n][k] = *(const PG8_LAS bf16x8*)(lds + PG8_SB(b, h) + boff + n * 2048 + k * 1024); } while (0)
; #define PG8_MMA(ai, bj, At, Bt) do { __builtin_amdgcn_s_setprio(1); _Pragma("unroll") for (int m = 0; m < 4; ++m) _Pragma("unroll") for (int n = 0; n < 2; ++n) _Pragma("unroll") for (int k = 0; k < 2; ++k) \
;         acc[ai][bj][m][n] = __builtin_amdgcn_mfma_f32_16x16x32_bf16(Bt[n][k], At[m][k], acc[ai][bj][m][n], 0, 0, 0); __builtin_amdgcn_s_setprio(0); } while (0)
; #define PG8_WAIT_V(n) asm volatile("s_waitcnt vmcnt(" #n ")" ::: "memory")
; #define PG8_WAIT_L(n) asm volatile("s_waitcnt lgkmcnt(" #n ")" ::: "memory")
; #define PG8_BAR __builtin_amdgcn_s_barrier()
; #define PG8_SCHED __builtin_amdgcn_sched_barrier(0)
; template <class Epi, class Sched, bool ALIGN_EPI = false, bool SP2 = false>
; __device__ __forceinline__ void gemm_phase(PG8_LAS unsigned char* lds, const Gemm g, const Sched& S, const Epi& E, const int wid) {
;     ...
;             PG8_LDB(B0, 1, 0); PG8_LDB(B1, 1, 1); PG8_SCHED; PG8_LDA(At, 1, 0); PG8_STAGE(PG8_SA(0, 1), a2 + hstep, voffA);
;             PG8_WAIT_V(8); PG8_WAIT_L(0); PG8_BAR; PG8_MMA(0, 0, At, B0); PG8_MMA(0, 1, At, B1); PG8_BAR; PG8_SCHED;
;             PG8_LDA(At, 1, 1); PG8_STAGE(PG8_SB(1, 0), b3, voffB); PG8_STAGE(PG8_SB(1, 1), b3 + hstep, voffB); PG8_STAGE(PG8_SA(1, 0), a3, voffA);
;             PG8_WAIT_V(8); PG8_WAIT_L(0); PG8_BAR; PG8_MMA(1, 0, At, B0); PG8_MMA(1, 1, At, B1); PG8_BAR; PG8_SCHED;
	s_add_i32 s49, 0, 0x18000
	s_add_i32 s50, 0, 0x1c000
	v_add_u32_e32 v162, s49, v149
	v_add_u32_e32 v178, s50, v149
	ds_read_b128 v[144:147], v162
	ds_read_b128 v[154:157], v162 offset:1024
	ds_read_b128 v[158:161], v162 offset:2048
	ds_read_b128 v[162:165], v162 offset:3072
	ds_read_b128 v[166:169], v178
	ds_read_b128 v[170:173], v178 offset:1024
	ds_read_b128 v[174:177], v178 offset:2048
	ds_read_b128 v[178:181], v178 offset:3072
	s_add_u32 s26, s26, 0x40000
	s_addc_u32 s27, s27, 0
	s_mov_b32 m0, s31
	v_lshl_add_u64 v[226:227], s[26:27], 0, v[134:135]
	ds_read_b128 v[182:185], v153 offset:32768
	ds_read_b128 v[186:189], v153 offset:33792
	ds_read_b128 v[190:193], v153 offset:34816
	ds_read_b128 v[194:197], v153 offset:35840
	ds_read_b128 v[198:201], v153 offset:36864
	ds_read_b128 v[202:205], v153 offset:37888
	ds_read_b128 v[212:215], v153 offset:38912
	ds_read_b128 v[216:219], v153 offset:39936
	global_load_lds_dwordx4 v[226:227], off
	v_lshl_add_u64 v[226:227], s[26:27], 0, v[130:131]
	s_mov_b32 m0, s33
	s_nop 0
	global_load_lds_dwordx4 v[226:227], off
	s_nop 0
	s_waitcnt vmcnt(8)
	s_waitcnt lgkmcnt(0)
	s_barrier
	s_waitcnt lgkmcnt(0)
	v_mfma_f32_16x16x32_bf16 v[124:127], v[144:147], v[182:185], v[124:127]
	v_mfma_f32_16x16x32_bf16 v[116:119], v[158:161], v[182:185], v[116:119]
	v_mfma_f32_16x16x32_bf16 v[108:111], v[144:147], v[190:193], v[108:111]
	v_mfma_f32_16x16x32_bf16 v[100:103], v[158:161], v[190:193], v[100:103]
	v_mfma_f32_16x16x32_bf16 v[92:95], v[144:147], v[198:201], v[92:95]
	v_mfma_f32_16x16x32_bf16 v[84:87], v[158:161], v[198:201], v[84:87]
	v_mfma_f32_16x16x32_bf16 v[76:79], v[144:147], v[212:215], v[76:79]
	v_mfma_f32_16x16x32_bf16 v[68:71], v[158:161], v[212:215], v[68:71]
	v_mfma_f32_16x16x32_bf16 v[124:127], v[154:157], v[186:189], v[124:127]
	v_mfma_f32_16x16x32_bf16 v[116:119], v[162:165], v[186:189], v[116:119]
	v_mfma_f32_16x16x32_bf16 v[108:111], v[154:157], v[194:197], v[108:111]
	v_mfma_f32_16x16x32_bf16 v[100:103], v[162:165], v[194:197], v[100:103]
	v_mfma_f32_16x16x32_bf16 v[92:95], v[154:157], v[202:205], v[92:95]
	v_mfma_f32_16x16x32_bf16 v[84:87], v[162:165], v[202:205], v[84:87]
	v_mfma_f32_16x16x32_bf16 v[76:79], v[154:157], v[216:219], v[76:79]
	v_mfma_f32_16x16x32_bf16 v[68:71], v[162:165], v[216:219], v[68:71]
	v_mfma_f32_16x16x32_bf16 v[120:123], v[166:169], v[182:185], v[120:123]
	v_mfma_f32_16x16x32_bf16 v[112:115], v[174:177], v[182:185], v[112:115]
	v_mfma_f32_16x16x32_bf16 v[104:107], v[166:169], v[190:193], v[104:107]
	v_mfma_f32_16x16x32_bf16 v[96:99], v[174:177], v[190:193], v[96:99]
	v_mfma_f32_16x16x32_bf16 v[88:91], v[166:169], v[198:201], v[88:91]
	v_mfma_f32_16x16x32_bf16 v[80:83], v[174:177], v[198:201], v[80:83]
	v_mfma_f32_16x16x32_bf16 v[72:75], v[166:169], v[212:215], v[72:75]
	v_mfma_f32_16x16x32_bf16 v[64:67], v[174:177], v[212:215], v[64:67]
	v_mfma_f32_16x16x32_bf16 v[120:123], v[170:173], v[186:189], v[120:123]
	v_mfma_f32_16x16x32_bf16 v[112:115], v[178:181], v[186:189], v[112:115]
	v_mfma_f32_16x16x32_bf16 v[104:107], v[170:173], v[194:197], v[104:107]
	v_mfma_f32_16x16x32_bf16 v[96:99], v[178:181], v[194:197], v[96:99]
	v_mfma_f32_16x16x32_bf16 v[88:91], v[170:173], v[202:205], v[88:91]
	v_mfma_f32_16x16x32_bf16 v[80:83], v[178:181], v[202:205], v[80:83]
	v_mfma_f32_16x16x32_bf16 v[72:75], v[170:173], v[216:219], v[72:75]
	v_mfma_f32_16x16x32_bf16 v[64:67], v[178:181], v[216:219], v[64:67]
	s_barrier
	s_add_i32 s26, s49, s9
	v_lshl_add_u64 v[206:207], v[206:207], 0, s[6:7]
	s_mov_b32 m0, s26
	ds_read_b128 v[182:185], v153 offset:49152
	ds_read_b128 v[186:189], v153 offset:50176
	ds_read_b128 v[190:193], v153 offset:51200
	ds_read_b128 v[194:197], v153 offset:52224
	ds_read_b128 v[198:201], v153 offset:53248
	ds_read_b128 v[202:205], v153 offset:54272
	ds_read_b128 v[212:215], v153 offset:55296
	ds_read_b128 v[216:219], v153 offset:56320
	global_load_lds_dwordx4 v[206:207], off
	s_add_i32 m0, s26, 0x2000
	s_add_u32 s24, s24, 0x40080
	v_lshl_add_u64 v[206:207], v[220:221], 0, s[6:7]
	s_addc_u32 s25, s25, 0
	s_add_i32 s26, s50, s9
	global_load_lds_dwordx4 v[206:207], off
	v_lshl_add_u64 v[206:207], s[24:25], 0, v[132:133]
	s_mov_b32 m0, s26
	s_nop 0
	global_load_lds_dwordx4 v[206:207], off
	v_lshl_add_u64 v[206:207], s[24:25], 0, v[128:129]
	s_add_i32 m0, s26, 0x2000
	s_nop 0
	global_load_lds_dwordx4 v[206:207], off
	v_lshl_add_u64 v[206:207], v[222:223], 0, s[6:7]
	s_mov_b32 m0, s38
	s_nop 0
	global_load_lds_dwordx4 v[206:207], off
	v_lshl_add_u64 v[206:207], v[224:225], 0, s[6:7]
	s_mov_b32 m0, s39
	s_nop 0
	global_load_lds_dwordx4 v[206:207], off
	s_waitcnt vmcnt(8)
	s_waitcnt lgkmcnt(0)
	s_barrier
; #define PG8_STAGE(bufoff, gbase, voff) do { _Pragma("unroll") for (int _i = 0; _i < 2; ++_i) \
;         __builtin_amdgcn_global_load_lds((const unsigned*)((const char*)(gbase) + (voff)[_i]), (PG8_LAS unsigned*)(lds + (bufoff) + ldsw + _i * 8192), 16, 0, 0); } while (0)
; #define PG8_LDA(dst, b, h) do { _Pragma("unroll") for (int m = 0; m < 4; ++m) _Pragma("unroll") for (int k = 0; k < 2; ++k) dst[m][k] = *(const PG8_LAS bf16x8*)(lds + PG8_SA(b, h) + aoff + m * 2048 + k * 1024); } while (0)
; #define PG8_WAIT_V(n) asm volatile("s_waitcnt vmcnt(" #n ")" ::: "memory")
; #define PG8_WAIT_L(n) asm volatile("s_waitcnt lgkmcnt(" #n ")" ::: "memory")
; #define PG8_BAR __builtin_amdgcn_s_barrier()
; template <class Epi, class Sched, bool ALIGN_EPI = false, bool SP2 = false>
; __device__ __forceinline__ void gemm_phase(PG8_LAS unsigned char* lds, const Gemm g, const Sched& S, const Epi& E, const int wid) {
;     ...
;         for (int t = 0; t < nt; t += 2) {
;             const bool last = (t == nt - 2);
;             const char* a1 = cA + (size_t)(t + 1) * kstep;
;             const char* a2 = last ? nA : cA + (size_t)(t + 2) * kstep; const char* b2 = last ? nB : cB + (size_t)(t + 2) * kstep;
;             const char* a3 = a2 + kstep; const char* b3 = b2 + kstep;
;             if (last && has_next) S.a_ready(nxt);
;             if constexpr (SP2) {
;             PG8_LDB(B0, 0, 0); PG8_LDB(B1, 0, 1); PG8_SCHED; PG8_LDA(At, 0, 0); PG8_STAGE(PG8_SA(1, 1), a1 + hstep, voffA);
;             PG8_WAIT_V(8); PG8_WAIT_L(0); PG8_BAR; PG8_MMA(0, 0, At, B0); PG8_MMA(0, 1, At, B1); PG8_BAR; PG8_SCHED;
;             PG8_LDA(At, 0, 1); PG8_STAGE(PG8_SB(0, 0), b2, voffB); PG8_STAGE(PG8_SB(0, 1), b2 + hstep, voffB); PG8_STAGE(PG8_SA(0, 0), a2, voffA);
;             PG8_WAIT_V(8); PG8_WAIT_L(0); PG8_BAR; PG8_MMA(1, 0, At, B0); PG8_MMA(1, 1, At, B1); PG8_BAR; PG8_SCHED;
;             PG8_LDB(B0, 1, 0); PG8_LDB(B1, 1, 1); PG8_SCHED; PG8_LDA(At, 1, 0); PG8_STAGE(PG8_SA(0, 1), a2 + hstep, voffA);
;             PG8_WAIT_V(8); PG8_WAIT_L(0); PG8_BAR; PG8_MMA(0, 0, At, B0); PG8_MMA(0, 1, At, B1); PG8_BAR; PG8_SCHED;
;             PG8_LDA(At, 1, 1); PG8_STAGE(PG8_SB(1, 0), b3, voffB); PG8_STAGE(PG8_SB(1, 1), b3 + hstep, voffB); PG8_STAGE(PG8_SA(1, 0), a3, voffA);
;             PG8_WAIT_V(8); PG8_WAIT_L(0); PG8_BAR; PG8_MMA(1, 0, At, B0); PG8_MMA(1, 1, At, B1); PG8_BAR; PG8_SCHED;
	s_waitcnt lgkmcnt(0)
	v_mfma_f32_16x16x32_bf16 v[60:63], v[144:147], v[182:185], v[60:63]
	v_mfma_f32_16x16x32_bf16 v[52:55], v[158:161], v[182:185], v[52:55]
	v_mfma_f32_16x16x32_bf16 v[44:47], v[144:147], v[190:193], v[44:47]
	v_mfma_f32_16x16x32_bf16 v[36:39], v[158:161], v[190:193], v[36:39]
	v_mfma_f32_16x16x32_bf16 v[28:31], v[144:147], v[198:201], v[28:31]
	v_mfma_f32_16x16x32_bf16 v[20:23], v[158:161], v[198:201], v[20:23]
	v_mfma_f32_16x16x32_bf16 v[12:15], v[144:147], v[212:215], v[12:15]
	v_mfma_f32_16x16x32_bf16 v[4:7], v[158:161], v[212:215], v[4:7]
	v_mfma_f32_16x16x32_bf16 v[60:63], v[154:157], v[186:189], v[60:63]
	v_mfma_f32_16x16x32_bf16 v[52:55], v[162:165], v[186:189], v[52:55]
	v_mfma_f32_16x16x32_bf16 v[44:47], v[154:157], v[194:197], v[44:47]
	v_mfma_f32_16x16x32_bf16 v[36:39], v[162:165], v[194:197], v[36:39]
	v_mfma_f32_16x16x32_bf16 v[28:31], v[154:157], v[202:205], v[28:31]
	v_mfma_f32_16x16x32_bf16 v[20:23], v[162:165], v[202:205], v[20:23]
	v_mfma_f32_16x16x32_bf16 v[12:15], v[154:157], v[216:219], v[12:15]
	v_mfma_f32_16x16x32_bf16 v[4:7], v[162:165], v[216:219], v[4:7]
	v_mfma_f32_16x16x32_bf16 v[56:59], v[166:169], v[182:185], v[56:59]
	v_mfma_f32_16x16x32_bf16 v[48:51], v[174:177], v[182:185], v[48:51]
	v_mfma_f32_16x16x32_bf16 v[40:43], v[166:169], v[190:193], v[40:43]
	v_mfma_f32_16x16x32_bf16 v[32:35], v[174:177], v[190:193], v[32:35]
	v_mfma_f32_16x16x32_bf16 v[24:27], v[166:169], v[198:201], v[24:27]
	v_mfma_f32_16x16x32_bf16 v[16:19], v[174:177], v[198:201], v[16:19]
	v_mfma_f32_16x16x32_bf16 v[8:11], v[166:169], v[212:215], v[8:11]
	v_mfma_f32_16x16x32_bf16 v[0:3], v[174:177], v[212:215], v[0:3]
	v_mfma_f32_16x16x32_bf16 v[56:59], v[170:173], v[186:189], v[56:59]
	v_mfma_f32_16x16x32_bf16 v[48:51], v[178:181], v[186:189], v[48:51]
	v_mfma_f32_16x16x32_bf16 v[40:43], v[170:173], v[194:197], v[40:43]
	v_mfma_f32_16x16x32_bf16 v[32:35], v[178:181], v[194:197], v[32:35]
	v_mfma_f32_16x16x32_bf16 v[24:27], v[170:173], v[202:205], v[24:27]
	v_mfma_f32_16x16x32_bf16 v[16:19], v[178:181], v[202:205], v[16:19]
	v_mfma_f32_16x16x32_bf16 v[8:11], v[170:173], v[216:219], v[8:11]
	v_mfma_f32_16x16x32_bf16 v[0:3], v[178:181], v[216:219], v[0:3]
	s_barrier
	s_add_i32 s48, s48, 2
	s_add_u32 s22, s22, 0x100
	s_addc_u32 s23, s23, 0
	s_add_u32 s46, s46, 0x100
	s_addc_u32 s47, s47, 0
	s_cmp_gt_u32 s48, 13
	s_cbranch_scc0 .LBB0_269
	s_branch .Lkp_exit_0
.LBB0_269:
	ds_read_b128 v[144:147], v151
	ds_read_b128 v[154:157], v151 offset:1024
	ds_read_b128 v[158:161], v151 offset:2048
	ds_read_b128 v[162:165], v151 offset:3072
	ds_read_b128 v[166:169], v152
	ds_read_b128 v[170:173], v152 offset:1024
	ds_read_b128 v[174:177], v152 offset:2048
	ds_read_b128 v[178:181], v152 offset:3072
	s_add_u32 s24, s22, 0xfffc0080
	s_addc_u32 s25, s23, -1
	s_cmp_eq_u32 s48, 12
	s_cselect_b32 s27, s15, s25
	s_cselect_b32 s26, s44, s24
	s_cselect_b32 s25, s13, s47
	s_cselect_b32 s24, s45, s46
	v_lshl_add_u64 v[206:207], s[22:23], 0, v[136:137]
	s_add_i32 m0, s21, 0xc000
	ds_read_b128 v[182:185], v153
	ds_read_b128 v[186:189], v153 offset:1024
	ds_read_b128 v[190:193], v153 offset:2048
	ds_read_b128 v[194:197], v153 offset:3072
	ds_read_b128 v[198:201], v153 offset:4096
	ds_read_b128 v[202:205], v153 offset:5120
	ds_read_b128 v[212:215], v153 offset:6144
	ds_read_b128 v[216:219], v153 offset:7168
	global_load_lds_dwordx4 v[206:207], off
	v_lshl_add_u64 v[206:207], s[22:23], 0, v[138:139]
	s_add_i32 m0, s21, 0xe000
	s_nop 0
	global_load_lds_dwordx4 v[206:207], off
	s_waitcnt vmcnt(8)
	s_waitcnt lgkmcnt(0)
	s_barrier
	s_waitcnt lgkmcnt(0)
	v_mfma_f32_16x16x32_bf16 v[124:127], v[144:147], v[182:185], v[124:127]
	v_mfma_f32_16x16x32_bf16 v[116:119], v[158:161], v[182:185], v[116:119]
	v_mfma_f32_16x16x32_bf16 v[108:111], v[144:147], v[190:193], v[108:111]
	v_mfma_f32_16x16x32_bf16 v[100:103], v[158:161], v[190:193], v[100:103]
	v_mfma_f32_16x16x32_bf16 v[92:95], v[144:147], v[198:201], v[92:95]
	v_mfma_f32_16x16x32_bf16 v[84:87], v[158:161], v[198:201], v[84:87]
	v_mfma_f32_16x16x32_bf16 v[76:79], v[144:147], v[212:215], v[76:79]
	v_mfma_f32_16x16x32_bf16 v[68:71], v[158:161], v[212:215], v[68:71]
	v_mfma_f32_16x16x32_bf16 v[124:127], v[154:157], v[186:189], v[124:127]
	v_mfma_f32_16x16x32_bf16 v[116:119], v[162:165], v[186:189], v[116:119]
	v_mfma_f32_16x16x32_bf16 v[108:111], v[154:157], v[194:197], v[108:111]
	v_mfma_f32_16x16x32_bf16 v[100:103], v[162:165], v[194:197], v[100:103]
	v_mfma_f32_16x16x32_bf16 v[92:95], v[154:157], v[202:205], v[92:95]
	v_mfma_f32_16x16x32_bf16 v[84:87], v[162:165], v[202:205], v[84:87]
	v_mfma_f32_16x16x32_bf16 v[76:79], v[154:157], v[216:219], v[76:79]
	v_mfma_f32_16x16x32_bf16 v[68:71], v[162:165], v[216:219], v[68:71]
	v_mfma_f32_16x16x32_bf16 v[120:123], v[166:169], v[182:185], v[120:123]
	v_mfma_f32_16x16x32_bf16 v[112:115], v[174:177], v[182:185], v[112:115]
	v_mfma_f32_16x16x32_bf16 v[104:107], v[166:169], v[190:193], v[104:107]
	v_mfma_f32_16x16x32_bf16 v[96:99], v[174:177], v[190:193], v[96:99]
	v_mfma_f32_16x16x32_bf16 v[88:91], v[166:169], v[198:201], v[88:91]
	v_mfma_f32_16x16x32_bf16 v[80:83], v[174:177], v[198:201], v[80:83]
	v_mfma_f32_16x16x32_bf16 v[72:75], v[166:169], v[212:215], v[72:75]
	v_mfma_f32_16x16x32_bf16 v[64:67], v[174:177], v[212:215], v[64:67]
	v_mfma_f32_16x16x32_bf16 v[120:123], v[170:173], v[186:189], v[120:123]
	v_mfma_f32_16x16x32_bf16 v[112:115], v[178:181], v[186:189], v[112:115]
	v_mfma_f32_16x16x32_bf16 v[104:107], v[170:173], v[194:197], v[104:107]
	v_mfma_f32_16x16x32_bf16 v[96:99], v[178:181], v[194:197], v[96:99]
	v_mfma_f32_16x16x32_bf16 v[88:91], v[170:173], v[202:205], v[88:91]
	v_mfma_f32_16x16x32_bf16 v[80:83], v[178:181], v[202:205], v[80:83]
	v_mfma_f32_16x16x32_bf16 v[72:75], v[170:173], v[216:219], v[72:75]
	v_mfma_f32_16x16x32_bf16 v[64:67], v[178:181], v[216:219], v[64:67]
	s_barrier
; #define PG8_STAGE(bufoff, gbase, voff) do { _Pragma("unroll") for (int _i = 0; _i < 2; ++_i) \
;         __builtin_amdgcn_global_load_lds((const unsigned*)((const char*)(gbase) + (voff)[_i]), (PG8_LAS unsigned*)(lds + (bufoff) + ldsw + _i * 8192), 16, 0, 0); } while (0)
; #define PG8_LDA(dst, b, h) do { _Pragma("unroll") for (int m = 0; m < 4; ++m) _Pragma("unroll") for (int k = 0; k < 2; ++k) dst[m][k] = *(const PG8_LAS bf16x8*)(lds + PG8_SA(b, h) + aoff + m * 2048 + k * 1024); } while (0)
; #define PG8_LDB(dst, b, h) do { _Pragma("unroll") for (int n = 0; n < 2; ++n) _Pragma("unroll") for (int k = 0; k < 2; ++k) dst[n][k] = *(const PG8_LAS bf16x8*)(lds + PG8_SB(b, h) + boff + n * 2048 + k * 1024); } while (0)
; #define PG8_MMA(ai, bj, At, Bt) do { __builtin_amdgcn_s_setprio(1); _Pragma("unroll") for (int m = 0; m < 4; ++m) _Pragma("unroll") for (int n = 0; n < 2; ++n) _Pragma("unroll") for (int k = 0; k < 2; ++k) \
;         acc[ai][bj][m][n] = __builtin_amdgcn_mfma_f32_16x16x32_bf16(Bt[n][k], At[m][k], acc[ai][bj][m][n], 0, 0, 0); __builtin_amdgcn_s_setprio(0); } while (0)
; #define PG8_WAIT_V(n) asm volatile("s_waitcnt vmcnt(" #n ")" ::: "memory")
; #define PG8_WAIT_L(n) asm volatile("s_waitcnt lgkmcnt(" #n ")" ::: "memory")
; #define PG8_BAR __builtin_amdgcn_s_barrier()
; #define PG8_SCHED __builtin_amdgcn_sched_barrier(0)
; template <class Epi, class Sched, bool ALIGN_EPI = false, bool SP2 = false>
; __device__ __forceinline__ void gemm_phase(PG8_LAS unsigned char* lds, const Gemm g, const Sched& S, const Epi& E, const int wid) {
;     ...
;             PG8_LDA(At, 0, 1); PG8_STAGE(PG8_SB(0, 0), b2, voffB); PG8_STAGE(PG8_SB(0, 1), b2 + hstep, voffB); PG8_STAGE(PG8_SA(0, 0), a2, voffA);
;             PG8_WAIT_V(8); PG8_WAIT_L(0); PG8_BAR; PG8_MMA(1, 0, At, B0); PG8_MMA(1, 1, At, B1); PG8_BAR; PG8_SCHED;
;             PG8_LDB(B0, 1, 0); PG8_LDB(B1, 1, 1); PG8_SCHED; PG8_LDA(At, 1, 0); PG8_STAGE(PG8_SA(0, 1), a2 + hstep, voffA);
;             PG8_WAIT_V(8); PG8_WAIT_L(0); PG8_BAR; PG8_MMA(0, 0, At, B0); PG8_MMA(0, 1, At, B1); PG8_BAR; PG8_SCHED;
	s_add_i32 s49, s40, s9
	v_lshl_add_u64 v[206:207], s[24:25], 0, v[132:133]
	s_mov_b32 m0, s49
	ds_read_b128 v[182:185], v153 offset:16384
	ds_read_b128 v[186:189], v153 offset:17408
	ds_read_b128 v[190:193], v153 offset:18432
	ds_read_b128 v[194:197], v153 offset:19456
	ds_read_b128 v[198:201], v153 offset:20480
	ds_read_b128 v[202:205], v153 offset:21504
	ds_read_b128 v[212:215], v153 offset:22528
	ds_read_b128 v[216:219], v153 offset:23552
	global_load_lds_dwordx4 v[206:207], off
	s_add_i32 m0, s49, 0x2000
	s_add_u32 s50, s24, 0x40000
	v_lshl_add_u64 v[220:221], s[24:25], 0, v[128:129]
	s_addc_u32 s51, s25, 0
	s_add_i32 s49, s41, s9
	global_load_lds_dwordx4 v[220:221], off
	v_lshl_add_u64 v[222:223], s[50:51], 0, v[132:133]
	s_mov_b32 m0, s49
	v_lshl_add_u64 v[224:225], s[26:27], 0, v[130:131]
	global_load_lds_dwordx4 v[222:223], off
	v_lshl_add_u64 v[222:223], s[50:51], 0, v[128:129]
	s_add_i32 m0, s49, 0x2000
	s_nop 0
	global_load_lds_dwordx4 v[222:223], off
	v_lshl_add_u64 v[222:223], s[26:27], 0, v[134:135]
	s_mov_b32 m0, s21
	s_nop 0
	global_load_lds_dwordx4 v[222:223], off
	s_mov_b32 m0, s30
	s_nop 0
	global_load_lds_dwordx4 v[224:225], off
	s_nop 0
	s_waitcnt vmcnt(8)
	s_waitcnt lgkmcnt(0)
	s_barrier
	s_waitcnt lgkmcnt(0)
	v_mfma_f32_16x16x32_bf16 v[60:63], v[144:147], v[182:185], v[60:63]
	v_mfma_f32_16x16x32_bf16 v[52:55], v[158:161], v[182:185], v[52:55]
	v_mfma_f32_16x16x32_bf16 v[44:47], v[144:147], v[190:193], v[44:47]
	v_mfma_f32_16x16x32_bf16 v[36:39], v[158:161], v[190:193], v[36:39]
	v_mfma_f32_16x16x32_bf16 v[28:31], v[144:147], v[198:201], v[28:31]
	v_mfma_f32_16x16x32_bf16 v[20:23], v[158:161], v[198:201], v[20:23]
	v_mfma_f32_16x16x32_bf16 v[12:15], v[144:147], v[212:215], v[12:15]
	v_mfma_f32_16x16x32_bf16 v[4:7], v[158:161], v[212:215], v[4:7]
	v_mfma_f32_16x16x32_bf16 v[60:63], v[154:157], v[186:189], v[60:63]
	v_mfma_f32_16x16x32_bf16 v[52:55], v[162:165], v[186:189], v[52:55]
	v_mfma_f32_16x16x32_bf16 v[44:47], v[154:157], v[194:197], v[44:47]
	v_mfma_f32_16x16x32_bf16 v[36:39], v[162:165], v[194:197], v[36:39]
	v_mfma_f32_16x16x32_bf16 v[28:31], v[154:157], v[202:205], v[28:31]
	v_mfma_f32_16x16x32_bf16 v[20:23], v[162:165], v[202:205], v[20:23]
	v_mfma_f32_16x16x32_bf16 v[12:15], v[154:157], v[216:219], v[12:15]
	v_mfma_f32_16x16x32_bf16 v[4:7], v[162:165], v[216:219], v[4:7]
	v_mfma_f32_16x16x32_bf16 v[56:59], v[166:169], v[182:185], v[56:59]
	v_mfma_f32_16x16x32_bf16 v[48:51], v[174:177], v[182:185], v[48:51]
	v_mfma_f32_16x16x32_bf16 v[40:43], v[166:169], v[190:193], v[40:43]
	v_mfma_f32_16x16x32_bf16 v[32:35], v[174:177], v[190:193], v[32:35]
	v_mfma_f32_16x16x32_bf16 v[24:27], v[166:169], v[198:201], v[24:27]
	v_mfma_f32_16x16x32_bf16 v[16:19], v[174:177], v[198:201], v[16:19]
	v_mfma_f32_16x16x32_bf16 v[8:11], v[166:169], v[212:215], v[8:11]
	v_mfma_f32_16x16x32_bf16 v[0:3], v[174:177], v[212:215], v[0:3]
	v_mfma_f32_16x16x32_bf16 v[56:59], v[170:173], v[186:189], v[56:59]
	v_mfma_f32_16x16x32_bf16 v[48:51], v[178:181], v[186:189], v[48:51]
	v_mfma_f32_16x16x32_bf16 v[40:43], v[170:173], v[194:197], v[40:43]
	v_mfma_f32_16x16x32_bf16 v[32:35], v[178:181], v[194:197], v[32:35]
	v_mfma_f32_16x16x32_bf16 v[24:27], v[170:173], v[202:205], v[24:27]
	v_mfma_f32_16x16x32_bf16 v[16:19], v[178:181], v[202:205], v[16:19]
	v_mfma_f32_16x16x32_bf16 v[8:11], v[170:173], v[216:219], v[8:11]
	v_mfma_f32_16x16x32_bf16 v[0:3], v[178:181], v[216:219], v[0:3]
	s_barrier
	s_add_i32 s49, 0, 0x18000
	s_add_i32 s50, 0, 0x1c000
	v_add_u32_e32 v162, s49, v149
	v_add_u32_e32 v178, s50, v149
	ds_read_b128 v[144:147], v162
	ds_read_b128 v[154:157], v162 offset:1024
	ds_read_b128 v[158:161], v162 offset:2048
	ds_read_b128 v[162:165], v162 offset:3072
	ds_read_b128 v[166:169], v178
	ds_read_b128 v[170:173], v178 offset:1024
	ds_read_b128 v[174:177], v178 offset:2048
	ds_read_b128 v[178:181], v178 offset:3072
	s_add_u32 s26, s26, 0x40000
	s_addc_u32 s27, s27, 0
	s_mov_b32 m0, s31
	v_lshl_add_u64 v[226:227], s[26:27], 0, v[134:135]
	ds_read_b128 v[182:185], v153 offset:32768
	ds_read_b128 v[186:189], v153 offset:33792
	ds_read_b128 v[190:193], v153 offset:34816
	ds_read_b128 v[194:197], v153 offset:35840
	ds_read_b128 v[198:201], v153 offset:36864
	ds_read_b128 v[202:205], v153 offset:37888
	ds_read_b128 v[212:215], v153 offset:38912
	ds_read_b128 v[216:219], v153 offset:39936
	global_load_lds_dwordx4 v[226:227], off
	v_lshl_add_u64 v[226:227], s[26:27], 0, v[130:131]
	s_mov_b32 m0, s33
	s_nop 0
	global_load_lds_dwordx4 v[226:227], off
	s_nop 0
	s_waitcnt vmcnt(8)
	s_waitcnt lgkmcnt(0)
	s_barrier
; #define PG8_STAGE(bufoff, gbase, voff) do { _Pragma("unroll") for (int _i = 0; _i < 2; ++_i) \
;         __builtin_amdgcn_global_load_lds((const unsigned*)((const char*)(gbase) + (voff)[_i]), (PG8_LAS unsigned*)(lds + (bufoff) + ldsw + _i * 8192), 16, 0, 0); } while (0)
; #define PG8_LDA(dst, b, h) do { _Pragma("unroll") for (int m = 0; m < 4; ++m) _Pragma("unroll") for (int k = 0; k < 2; ++k) dst[m][k] = *(const PG8_LAS bf16x8*)(lds + PG8_SA(b, h) + aoff + m * 2048 + k * 1024); } while (0)
; #define PG8_LDB(dst, b, h) do { _Pragma("unroll") for (int n = 0; n < 2; ++n) _Pragma("unroll") for (int k = 0; k < 2; ++k) dst[n][k] = *(const PG8_LAS bf16x8*)(lds + PG8_SB(b, h) + boff + n * 2048 + k * 1024); } while (0)
; #define PG8_MMA(ai, bj, At, Bt) do { __builtin_amdgcn_s_setprio(1); _Pragma("unroll") for (int m = 0; m < 4; ++m) _Pragma("unroll") for (int n = 0; n < 2; ++n) _Pragma("unroll") for (int k = 0; k < 2; ++k) \
;         acc[ai][bj][m][n] = __builtin_amdgcn_mfma_f32_16x16x32_bf16(Bt[n][k], At[m][k], acc[ai][bj][m][n], 0, 0, 0); __builtin_amdgcn_s_setprio(0); } while (0)
; #define PG8_WAIT_V(n) asm volatile("s_waitcnt vmcnt(" #n ")" ::: "memory")
; #define PG8_WAIT_L(n) asm volatile("s_waitcnt lgkmcnt(" #n ")" ::: "memory")
; #define PG8_BAR __builtin_amdgcn_s_barrier()
; #define PG8_SCHED __builtin_amdgcn_sched_barrier(0)
; template <class Epi, class Sched, bool ALIGN_EPI = false, bool SP2 = false>
; __device__ __forceinline__ void gemm_phase(PG8_LAS unsigned char* lds, const Gemm g, const Sched& S, const Epi& E, const int wid) {
;     ...
;             PG8_LDB(B0, 1, 0); PG8_LDB(B1, 1, 1); PG8_SCHED; PG8_LDA(At, 1, 0); PG8_STAGE(PG8_SA(0, 1), a2 + hstep, voffA);
;             PG8_WAIT_V(8); PG8_WAIT_L(0); PG8_BAR; PG8_MMA(0, 0, At, B0); PG8_MMA(0, 1, At, B1); PG8_BAR; PG8_SCHED;
;             PG8_LDA(At, 1, 1); PG8_STAGE(PG8_SB(1, 0), b3, voffB); PG8_STAGE(PG8_SB(1, 1), b3 + hstep, voffB); PG8_STAGE(PG8_SA(1, 0), a3, voffA);
;             PG8_WAIT_V(8); PG8_WAIT_L(0); PG8_BAR; PG8_MMA(1, 0, At, B0); PG8_MMA(1, 1, At, B1); PG8_BAR; PG8_SCHED;
	s_waitcnt lgkmcnt(0)
	v_mfma_f32_16x16x32_bf16 v[124:127], v[144:147], v[182:185], v[124:127]
	v_mfma_f32_16x16x32_bf16 v[116:119], v[158:161], v[182:185], v[116:119]
	v_mfma_f32_16x16x32_bf16 v[108:111], v[144:147], v[190:193], v[108:111]
	v_mfma_f32_16x16x32_bf16 v[100:103], v[158:161], v[190:193], v[100:103]
	v_mfma_f32_16x16x32_bf16 v[92:95], v[144:147], v[198:201], v[92:95]
	v_mfma_f32_16x16x32_bf16 v[84:87], v[158:161], v[198:201], v[84:87]
	v_mfma_f32_16x16x32_bf16 v[76:79], v[144:147], v[212:215], v[76:79]
	v_mfma_f32_16x16x32_bf16 v[68:71], v[158:161], v[212:215], v[68:71]
	v_mfma_f32_16x16x32_bf16 v[124:127], v[154:157], v[186:189], v[124:127]
	v_mfma_f32_16x16x32_bf16 v[116:119], v[162:165], v[186:189], v[116:119]
	v_mfma_f32_16x16x32_bf16 v[108:111], v[154:157], v[194:197], v[108:111]
	v_mfma_f32_16x16x32_bf16 v[100:103], v[162:165], v[194:197], v[100:103]
	v_mfma_f32_16x16x32_bf16 v[92:95], v[154:157], v[202:205], v[92:95]
	v_mfma_f32_16x16x32_bf16 v[84:87], v[162:165], v[202:205], v[84:87]
	v_mfma_f32_16x16x32_bf16 v[76:79], v[154:157], v[216:219], v[76:79]
	v_mfma_f32_16x16x32_bf16 v[68:71], v[162:165], v[216:219], v[68:71]
	v_mfma_f32_16x16x32_bf16 v[120:123], v[166:169], v[182:185], v[120:123]
	v_mfma_f32_16x16x32_bf16 v[112:115], v[174:177], v[182:185], v[112:115]
	v_mfma_f32_16x16x32_bf16 v[104:107], v[166:169], v[190:193], v[104:107]
	v_mfma_f32_16x16x32_bf16 v[96:99], v[174:177], v[190:193], v[96:99]
	v_mfma_f32_16x16x32_bf16 v[88:91], v[166:169], v[198:201], v[88:91]
	v_mfma_f32_16x16x32_bf16 v[80:83], v[174:177], v[198:201], v[80:83]
	v_mfma_f32_16x16x32_bf16 v[72:75], v[166:169], v[212:215], v[72:75]
	v_mfma_f32_16x16x32_bf16 v[64:67], v[174:177], v[212:215], v[64:67]
	v_mfma_f32_16x16x32_bf16 v[120:123], v[170:173], v[186:189], v[120:123]
	v_mfma_f32_16x16x32_bf16 v[112:115], v[178:181], v[186:189], v[112:115]
	v_mfma_f32_16x16x32_bf16 v[104:107], v[170:173], v[194:197], v[104:107]
	v_mfma_f32_16x16x32_bf16 v[96:99], v[178:181], v[194:197], v[96:99]
	v_mfma_f32_16x16x32_bf16 v[88:91], v[170:173], v[202:205], v[88:91]
	v_mfma_f32_16x16x32_bf16 v[80:83], v[178:181], v[202:205], v[80:83]
	v_mfma_f32_16x16x32_bf16 v[72:75], v[170:173], v[216:219], v[72:75]
	v_mfma_f32_16x16x32_bf16 v[64:67], v[178:181], v[216:219], v[64:67]
	s_barrier
	s_add_i32 s26, s49, s9
	v_lshl_add_u64 v[206:207], v[206:207], 0, s[6:7]
	s_mov_b32 m0, s26
	ds_read_b128 v[182:185], v153 offset:49152
	ds_read_b128 v[186:189], v153 offset:50176
	ds_read_b128 v[190:193], v153 offset:51200
	ds_read_b128 v[194:197], v153 offset:52224
	ds_read_b128 v[198:201], v153 offset:53248
	ds_read_b128 v[202:205], v153 offset:54272
	ds_read_b128 v[212:215], v153 offset:55296
	ds_read_b128 v[216:219], v153 offset:56320
	global_load_lds_dwordx4 v[206:207], off
	s_add_i32 m0, s26, 0x2000
	s_add_u32 s24, s24, 0x40080
	v_lshl_add_u64 v[206:207], v[220:221], 0, s[6:7]
	s_addc_u32 s25, s25, 0
	s_add_i32 s26, s50, s9
	global_load_lds_dwordx4 v[206:207], off
	v_lshl_add_u64 v[206:207], s[24:25], 0, v[132:133]
	s_mov_b32 m0, s26
	s_nop 0
	global_load_lds_dwordx4 v[206:207], off
	v_lshl_add_u64 v[206:207], s[24:25], 0, v[128:129]
	s_add_i32 m0, s26, 0x2000
	s_nop 0
	global_load_lds_dwordx4 v[206:207], off
	v_lshl_add_u64 v[206:207], v[222:223], 0, s[6:7]
	s_mov_b32 m0, s38
	s_nop 0
	global_load_lds_dwordx4 v[206:207], off
	v_lshl_add_u64 v[206:207], v[224:225], 0, s[6:7]
	s_mov_b32 m0, s39
	s_nop 0
	global_load_lds_dwordx4 v[206:207], off
	s_waitcnt vmcnt(8)
	s_waitcnt lgkmcnt(0)
	s_barrier
	s_waitcnt lgkmcnt(0)
	v_mfma_f32_16x16x32_bf16 v[60:63], v[144:147], v[182:185], v[60:63]
	v_mfma_f32_16x16x32_bf16 v[52:55], v[158:161], v[182:185], v[52:55]
	v_mfma_f32_16x16x32_bf16 v[44:47], v[144:147], v[190:193], v[44:47]
	v_mfma_f32_16x16x32_bf16 v[36:39], v[158:161], v[190:193], v[36:39]
	v_mfma_f32_16x16x32_bf16 v[28:31], v[144:147], v[198:201], v[28:31]
	v_mfma_f32_16x16x32_bf16 v[20:23], v[158:161], v[198:201], v[20:23]
	v_mfma_f32_16x16x32_bf16 v[12:15], v[144:147], v[212:215], v[12:15]
	v_mfma_f32_16x16x32_bf16 v[4:7], v[158:161], v[212:215], v[4:7]
	v_mfma_f32_16x16x32_bf16 v[60:63], v[154:157], v[186:189], v[60:63]
	v_mfma_f32_16x16x32_bf16 v[52:55], v[162:165], v[186:189], v[52:55]
	v_mfma_f32_16x16x32_bf16 v[44:47], v[154:157], v[194:197], v[44:47]
	v_mfma_f32_16x16x32_bf16 v[36:39], v[162:165], v[194:197], v[36:39]
	v_mfma_f32_16x16x32_bf16 v[28:31], v[154:157], v[202:205], v[28:31]
	v_mfma_f32_16x16x32_bf16 v[20:23], v[162:165], v[202:205], v[20:23]
	v_mfma_f32_16x16x32_bf16 v[12:15], v[154:157], v[216:219], v[12:15]
	v_mfma_f32_16x16x32_bf16 v[4:7], v[162:165], v[216:219], v[4:7]
	v_mfma_f32_16x16x32_bf16 v[56:59], v[166:169], v[182:185], v[56:59]
	v_mfma_f32_16x16x32_bf16 v[48:51], v[174:177], v[182:185], v[48:51]
	v_mfma_f32_16x16x32_bf16 v[40:43], v[166:169], v[190:193], v[40:43]
	v_mfma_f32_16x16x32_bf16 v[32:35], v[174:177], v[190:193], v[32:35]
	v_mfma_f32_16x16x32_bf16 v[24:27], v[166:169], v[198:201], v[24:27]
	v_mfma_f32_16x16x32_bf16 v[16:19], v[174:177], v[198:201], v[16:19]
	v_mfma_f32_16x16x32_bf16 v[8:11], v[166:169], v[212:215], v[8:11]
	v_mfma_f32_16x16x32_bf16 v[0:3], v[174:177], v[212:215], v[0:3]
	v_mfma_f32_16x16x32_bf16 v[56:59], v[170:173], v[186:189], v[56:59]
	v_mfma_f32_16x16x32_bf16 v[48:51], v[178:181], v[186:189], v[48:51]
	v_mfma_f32_16x16x32_bf16 v[40:43], v[170:173], v[194:197], v[40:43]
	v_mfma_f32_16x16x32_bf16 v[32:35], v[178:181], v[194:197], v[32:35]
	v_mfma_f32_16x16x32_bf16 v[24:27], v[170:173], v[202:205], v[24:27]
	v_mfma_f32_16x16x32_bf16 v[16:19], v[178:181], v[202:205], v[16:19]
	v_mfma_f32_16x16x32_bf16 v[8:11], v[170:173], v[216:219], v[8:11]
	v_mfma_f32_16x16x32_bf16 v[0:3], v[178:181], v[216:219], v[0:3]
	s_barrier
	s_add_i32 s48, s48, 2
	s_add_u32 s22, s22, 0x100
	s_addc_u32 s23, s23, 0
	s_add_u32 s46, s46, 0x100
	s_addc_u32 s47, s47, 0
	s_cmp_gt_u32 s48, 13
	s_cbranch_scc0 .LBB0_269

; #define PG8_STAGE(bufoff, gbase, voff) do { _Pragma("unroll") for (int _i = 0; _i < 2; ++_i) \
;         __builtin_amdgcn_global_load_lds((const unsigned*)((const char*)(gbase) + (voff)[_i]), (PG8_LAS unsigned*)(lds + (bufoff) + ldsw + _i * 8192), 16, 0, 0); } while (0)
; #define PG8_LDA(dst, b, h) do { _Pragma("unroll") for (int m = 0; m < 4; ++m) _Pragma("unroll") for (int k = 0; k < 2; ++k) dst[m][k] = *(const PG8_LAS bf16x8*)(lds + PG8_SA(b, h) + aoff + m * 2048 + k * 1024); } while (0)
; #define PG8_LDB(dst, b, h) do { _Pragma("unroll") for (int n = 0; n < 2; ++n) _Pragma("unroll") for (int k = 0; k < 2; ++k) dst[n][k] = *(const PG8_LAS bf16x8*)(lds + PG8_SB(b, h) + boff + n * 2048 + k * 1024); } while (0)
; #define PG8_MMA(ai, bj, At, Bt) do { __builtin_amdgcn_s_setprio(1); _Pragma("unroll") for (int m = 0; m < 4; ++m) _Pragma("unroll") for (int n = 0; n < 2; ++n) _Pragma("unroll") for (int k = 0; k < 2; ++k) \
;         acc[ai][bj][m][n] = __builtin_amdgcn_mfma_f32_16x16x32_bf16(Bt[n][k], At[m][k], acc[ai][bj][m][n], 0, 0, 0); __builtin_amdgcn_s_setprio(0); } while (0)
; #define PG8_WAIT_V(n) asm volatile("s_waitcnt vmcnt(" #n ")" ::: "memory")
; #define PG8_WAIT_L(n) asm volatile("s_waitcnt lgkmcnt(" #n ")" ::: "memory")
; #define PG8_BAR __builtin_amdgcn_s_barrier()
; #define PG8_SCHED __builtin_amdgcn_sched_barrier(0)
; template <class Epi, class Sched, bool ALIGN_EPI = false, bool SP2 = false>
; __device__ __forceinline__ void gemm_phase(PG8_LAS unsigned char* lds, const Gemm g, const Sched& S, const Epi& E, const int wid) {
;     ...
;             PG8_LDB(B0, 0, 0); PG8_LDB(B1, 0, 1); PG8_SCHED; PG8_LDA(At, 0, 0); PG8_STAGE(PG8_SA(1, 1), a1 + hstep, voffA);
;             PG8_WAIT_V(8); PG8_WAIT_L(0); PG8_BAR; PG8_MMA(0, 0, At, B0); PG8_MMA(0, 1, At, B1); PG8_BAR; PG8_SCHED;
;             PG8_LDA(At, 0, 1); PG8_STAGE(PG8_SB(0, 0), b2, voffB); PG8_STAGE(PG8_SB(0, 1), b2 + hstep, voffB); PG8_STAGE(PG8_SA(0, 0), a2, voffA);
.LBB0_756:
	v_add_u32_e32 v151, s35, v149
	ds_read_b128 v[152:155], v151
	ds_read_b128 v[156:159], v151 offset:1024
	ds_read_b128 v[160:163], v151 offset:2048
	ds_read_b128 v[164:167], v151 offset:3072
	v_add_u32_e32 v151, s38, v149
	s_add_u32 s16, s2, s14
	ds_read_b128 v[168:171], v151
	ds_read_b128 v[172:175], v151 offset:1024
	ds_read_b128 v[176:179], v151 offset:2048
	ds_read_b128 v[180:183], v151 offset:3072
	s_addc_u32 s17, s3, s15
	s_add_u32 s16, s16, 0x100
	s_addc_u32 s17, s17, 0
	s_add_u32 s45, s42, s14
	s_addc_u32 s46, s43, s15
	s_cmpk_eq_i32 s14, 0x1500
	s_cselect_b32 s19, s13, s17
	s_cselect_b32 s18, s12, s16
	s_cselect_b32 s17, s9, s46
	s_cselect_b32 s16, s8, s45
	v_lshl_add_u64 v[206:207], v[144:145], 0, s[14:15]
	s_add_i32 m0, s25, 0xc000
	ds_read_b128 v[184:187], v150
	ds_read_b128 v[188:191], v150 offset:1024
	ds_read_b128 v[194:197], v150 offset:2048
	ds_read_b128 v[198:201], v150 offset:3072
	ds_read_b128 v[202:205], v150 offset:4096
	ds_read_b128 v[212:215], v150 offset:5120
	ds_read_b128 v[216:219], v150 offset:6144
	ds_read_b128 v[220:223], v150 offset:7168
	global_load_lds_dwordx4 v[206:207], off
	v_lshl_add_u64 v[206:207], v[146:147], 0, s[14:15]
	s_add_i32 m0, s25, 0xe000
	s_nop 0
	global_load_lds_dwordx4 v[206:207], off
	s_nop 0
	s_waitcnt vmcnt(8)
	s_waitcnt lgkmcnt(0)
	s_barrier
	s_waitcnt lgkmcnt(0)
	v_mfma_f32_16x16x32_bf16 v[120:123], v[152:155], v[184:187], v[120:123]
	v_mfma_f32_16x16x32_bf16 v[124:127], v[160:163], v[184:187], v[124:127]
	v_mfma_f32_16x16x32_bf16 v[108:111], v[152:155], v[194:197], v[108:111]
	v_mfma_f32_16x16x32_bf16 v[116:119], v[160:163], v[194:197], v[116:119]
	v_mfma_f32_16x16x32_bf16 v[92:95], v[152:155], v[202:205], v[92:95]
	v_mfma_f32_16x16x32_bf16 v[112:115], v[160:163], v[202:205], v[112:115]
	v_mfma_f32_16x16x32_bf16 v[72:75], v[152:155], v[216:219], v[72:75]
	v_mfma_f32_16x16x32_bf16 v[100:103], v[160:163], v[216:219], v[100:103]
	v_mfma_f32_16x16x32_bf16 v[120:123], v[156:159], v[188:191], v[120:123]
	v_mfma_f32_16x16x32_bf16 v[124:127], v[164:167], v[188:191], v[124:127]
	v_mfma_f32_16x16x32_bf16 v[108:111], v[156:159], v[198:201], v[108:111]
	v_mfma_f32_16x16x32_bf16 v[116:119], v[164:167], v[198:201], v[116:119]
	v_mfma_f32_16x16x32_bf16 v[92:95], v[156:159], v[212:215], v[92:95]
	v_mfma_f32_16x16x32_bf16 v[112:115], v[164:167], v[212:215], v[112:115]
	v_mfma_f32_16x16x32_bf16 v[72:75], v[156:159], v[220:223], v[72:75]
	v_mfma_f32_16x16x32_bf16 v[100:103], v[164:167], v[220:223], v[100:103]
	v_mfma_f32_16x16x32_bf16 v[104:107], v[168:171], v[184:187], v[104:107]
	v_mfma_f32_16x16x32_bf16 v[88:91], v[176:179], v[184:187], v[88:91]
	v_mfma_f32_16x16x32_bf16 v[96:99], v[168:171], v[194:197], v[96:99]
	v_mfma_f32_16x16x32_bf16 v[76:79], v[176:179], v[194:197], v[76:79]
	v_mfma_f32_16x16x32_bf16 v[84:87], v[168:171], v[202:205], v[84:87]
	v_mfma_f32_16x16x32_bf16 v[68:71], v[176:179], v[202:205], v[68:71]
	v_mfma_f32_16x16x32_bf16 v[80:83], v[168:171], v[216:219], v[80:83]
	v_mfma_f32_16x16x32_bf16 v[64:67], v[176:179], v[216:219], v[64:67]
	v_mfma_f32_16x16x32_bf16 v[104:107], v[172:175], v[188:191], v[104:107]
	v_mfma_f32_16x16x32_bf16 v[88:91], v[180:183], v[188:191], v[88:91]
	v_mfma_f32_16x16x32_bf16 v[96:99], v[172:175], v[198:201], v[96:99]
	v_mfma_f32_16x16x32_bf16 v[76:79], v[180:183], v[198:201], v[76:79]
	v_mfma_f32_16x16x32_bf16 v[84:87], v[172:175], v[212:215], v[84:87]
	v_mfma_f32_16x16x32_bf16 v[68:71], v[180:183], v[212:215], v[68:71]
	v_mfma_f32_16x16x32_bf16 v[80:83], v[172:175], v[220:223], v[80:83]
	v_mfma_f32_16x16x32_bf16 v[64:67], v[180:183], v[220:223], v[64:67]
	s_barrier
	s_add_i32 s45, s35, s23
	v_lshl_add_u64 v[206:207], s[16:17], 0, v[132:133]
	s_mov_b32 m0, s45
	ds_read_b128 v[184:187], v150 offset:16384
	ds_read_b128 v[188:191], v150 offset:17408
	ds_read_b128 v[194:197], v150 offset:18432
	ds_read_b128 v[198:201], v150 offset:19456
	ds_read_b128 v[202:205], v150 offset:20480
	ds_read_b128 v[212:215], v150 offset:21504
	ds_read_b128 v[216:219], v150 offset:22528
	ds_read_b128 v[220:223], v150 offset:23552
	global_load_lds_dwordx4 v[206:207], off
	s_add_i32 m0, s45, 0x2000
	s_add_u32 s46, s16, 0xb0000
	v_lshl_add_u64 v[224:225], s[16:17], 0, v[128:129]
	s_addc_u32 s47, s17, 0
	s_add_i32 s45, s38, s23
	global_load_lds_dwordx4 v[224:225], off
	v_lshl_add_u64 v[226:227], s[46:47], 0, v[132:133]
	s_mov_b32 m0, s45
	v_lshl_add_u64 v[228:229], s[18:19], 0, v[130:131]
	global_load_lds_dwordx4 v[226:227], off
	v_lshl_add_u64 v[226:227], s[46:47], 0, v[128:129]
	s_add_i32 m0, s45, 0x2000
	s_nop 0
	global_load_lds_dwordx4 v[226:227], off
	v_lshl_add_u64 v[226:227], s[18:19], 0, v[134:135]
	s_mov_b32 m0, s25
	s_nop 0
	global_load_lds_dwordx4 v[226:227], off
	s_mov_b32 m0, s27
	s_nop 0
	global_load_lds_dwordx4 v[228:229], off
	s_nop 0
	s_waitcnt vmcnt(8)
	s_waitcnt lgkmcnt(0)
	s_barrier
; #define PG8_STAGE(bufoff, gbase, voff) do { _Pragma("unroll") for (int _i = 0; _i < 2; ++_i) \
;         __builtin_amdgcn_global_load_lds((const unsigned*)((const char*)(gbase) + (voff)[_i]), (PG8_LAS unsigned*)(lds + (bufoff) + ldsw + _i * 8192), 16, 0, 0); } while (0)
; #define PG8_LDA(dst, b, h) do { _Pragma("unroll") for (int m = 0; m < 4; ++m) _Pragma("unroll") for (int k = 0; k < 2; ++k) dst[m][k] = *(const PG8_LAS bf16x8*)(lds + PG8_SA(b, h) + aoff + m * 2048 + k * 1024); } while (0)
; #define PG8_LDB(dst, b, h) do { _Pragma("unroll") for (int n = 0; n < 2; ++n) _Pragma("unroll") for (int k = 0; k < 2; ++k) dst[n][k] = *(const PG8_LAS bf16x8*)(lds + PG8_SB(b, h) + boff + n * 2048 + k * 1024); } while (0)
; #define PG8_MMA(ai, bj, At, Bt) do { __builtin_amdgcn_s_setprio(1); _Pragma("unroll") for (int m = 0; m < 4; ++m) _Pragma("unroll") for (int n = 0; n < 2; ++n) _Pragma("unroll") for (int k = 0; k < 2; ++k) \
;         acc[ai][bj][m][n] = __builtin_amdgcn_mfma_f32_16x16x32_bf16(Bt[n][k], At[m][k], acc[ai][bj][m][n], 0, 0, 0); __builtin_amdgcn_s_setprio(0); } while (0)
; #define PG8_WAIT_V(n) asm volatile("s_waitcnt vmcnt(" #n ")" ::: "memory")
; #define PG8_WAIT_L(n) asm volatile("s_waitcnt lgkmcnt(" #n ")" ::: "memory")
; #define PG8_BAR __builtin_amdgcn_s_barrier()
; #define PG8_SCHED __builtin_amdgcn_sched_barrier(0)
; template <class Epi, class Sched, bool ALIGN_EPI = false, bool SP2 = false>
; __device__ __forceinline__ void gemm_phase(PG8_LAS unsigned char* lds, const Gemm g, const Sched& S, const Epi& E, const int wid) {
;     ...
;             PG8_WAIT_V(8); PG8_WAIT_L(0); PG8_BAR; PG8_MMA(1, 0, At, B0); PG8_MMA(1, 1, At, B1); PG8_BAR; PG8_SCHED;
;             PG8_LDB(B0, 1, 0); PG8_LDB(B1, 1, 1); PG8_SCHED; PG8_LDA(At, 1, 0); PG8_STAGE(PG8_SA(0, 1), a2 + hstep, voffA);
;             PG8_WAIT_V(8); PG8_WAIT_L(0); PG8_BAR; PG8_MMA(0, 0, At, B0); PG8_MMA(0, 1, At, B1); PG8_BAR; PG8_SCHED;
	s_waitcnt lgkmcnt(0)
	v_mfma_f32_16x16x32_bf16 v[60:63], v[152:155], v[184:187], v[60:63]
	v_mfma_f32_16x16x32_bf16 v[56:59], v[160:163], v[184:187], v[56:59]
	v_mfma_f32_16x16x32_bf16 v[44:47], v[152:155], v[194:197], v[44:47]
	v_mfma_f32_16x16x32_bf16 v[40:43], v[160:163], v[194:197], v[40:43]
	v_mfma_f32_16x16x32_bf16 v[28:31], v[152:155], v[202:205], v[28:31]
	v_mfma_f32_16x16x32_bf16 v[24:27], v[160:163], v[202:205], v[24:27]
	v_mfma_f32_16x16x32_bf16 v[4:7], v[152:155], v[216:219], v[4:7]
	v_mfma_f32_16x16x32_bf16 v[12:15], v[160:163], v[216:219], v[12:15]
	v_mfma_f32_16x16x32_bf16 v[60:63], v[156:159], v[188:191], v[60:63]
	v_mfma_f32_16x16x32_bf16 v[56:59], v[164:167], v[188:191], v[56:59]
	v_mfma_f32_16x16x32_bf16 v[44:47], v[156:159], v[198:201], v[44:47]
	v_mfma_f32_16x16x32_bf16 v[40:43], v[164:167], v[198:201], v[40:43]
	v_mfma_f32_16x16x32_bf16 v[28:31], v[156:159], v[212:215], v[28:31]
	v_mfma_f32_16x16x32_bf16 v[24:27], v[164:167], v[212:215], v[24:27]
	v_mfma_f32_16x16x32_bf16 v[4:7], v[156:159], v[220:223], v[4:7]
	v_mfma_f32_16x16x32_bf16 v[12:15], v[164:167], v[220:223], v[12:15]
	v_mfma_f32_16x16x32_bf16 v[52:55], v[168:171], v[184:187], v[52:55]
	v_mfma_f32_16x16x32_bf16 v[48:51], v[176:179], v[184:187], v[48:51]
	v_mfma_f32_16x16x32_bf16 v[36:39], v[168:171], v[194:197], v[36:39]
	v_mfma_f32_16x16x32_bf16 v[32:35], v[176:179], v[194:197], v[32:35]
	v_mfma_f32_16x16x32_bf16 v[20:23], v[168:171], v[202:205], v[20:23]
	v_mfma_f32_16x16x32_bf16 v[16:19], v[176:179], v[202:205], v[16:19]
	v_mfma_f32_16x16x32_bf16 v[8:11], v[168:171], v[216:219], v[8:11]
	v_mfma_f32_16x16x32_bf16 v[0:3], v[176:179], v[216:219], v[0:3]
	v_mfma_f32_16x16x32_bf16 v[52:55], v[172:175], v[188:191], v[52:55]
	v_mfma_f32_16x16x32_bf16 v[48:51], v[180:183], v[188:191], v[48:51]
	v_mfma_f32_16x16x32_bf16 v[36:39], v[172:175], v[198:201], v[36:39]
	v_mfma_f32_16x16x32_bf16 v[32:35], v[180:183], v[198:201], v[32:35]
	v_mfma_f32_16x16x32_bf16 v[20:23], v[172:175], v[212:215], v[20:23]
	v_mfma_f32_16x16x32_bf16 v[16:19], v[180:183], v[212:215], v[16:19]
	v_mfma_f32_16x16x32_bf16 v[8:11], v[172:175], v[220:223], v[8:11]
	v_mfma_f32_16x16x32_bf16 v[0:3], v[180:183], v[220:223], v[0:3]
	s_barrier
	s_add_i32 s45, 0, 0x18000
	v_add_u32_e32 v151, s45, v149
	s_add_i32 s46, 0, 0x1c000
	ds_read_b128 v[152:155], v151
	ds_read_b128 v[156:159], v151 offset:1024
	ds_read_b128 v[160:163], v151 offset:2048
	ds_read_b128 v[164:167], v151 offset:3072
	v_add_u32_e32 v151, s46, v149
	ds_read_b128 v[168:171], v151
	ds_read_b128 v[172:175], v151 offset:1024
	ds_read_b128 v[176:179], v151 offset:2048
	ds_read_b128 v[180:183], v151 offset:3072
	s_add_u32 s18, s18, 0xb0000
	s_addc_u32 s19, s19, 0
	s_mov_b32 m0, s28
	v_lshl_add_u64 v[230:231], s[18:19], 0, v[134:135]
	ds_read_b128 v[184:187], v150 offset:32768
	ds_read_b128 v[188:191], v150 offset:33792
	ds_read_b128 v[194:197], v150 offset:34816
	ds_read_b128 v[198:201], v150 offset:35840
	ds_read_b128 v[202:205], v150 offset:36864
	ds_read_b128 v[212:215], v150 offset:37888
	ds_read_b128 v[216:219], v150 offset:38912
	ds_read_b128 v[220:223], v150 offset:39936
	global_load_lds_dwordx4 v[230:231], off
	v_lshl_add_u64 v[230:231], s[18:19], 0, v[130:131]
	s_mov_b32 m0, s29
	s_nop 0
	global_load_lds_dwordx4 v[230:231], off
	s_nop 0
	s_waitcnt vmcnt(8)
	s_waitcnt lgkmcnt(0)
	s_barrier
	s_waitcnt lgkmcnt(0)
	v_mfma_f32_16x16x32_bf16 v[120:123], v[152:155], v[184:187], v[120:123]
	v_mfma_f32_16x16x32_bf16 v[124:127], v[160:163], v[184:187], v[124:127]
	v_mfma_f32_16x16x32_bf16 v[108:111], v[152:155], v[194:197], v[108:111]
	v_mfma_f32_16x16x32_bf16 v[116:119], v[160:163], v[194:197], v[116:119]
	v_mfma_f32_16x16x32_bf16 v[92:95], v[152:155], v[202:205], v[92:95]
	v_mfma_f32_16x16x32_bf16 v[112:115], v[160:163], v[202:205], v[112:115]
	v_mfma_f32_16x16x32_bf16 v[72:75], v[152:155], v[216:219], v[72:75]
	v_mfma_f32_16x16x32_bf16 v[100:103], v[160:163], v[216:219], v[100:103]
	v_mfma_f32_16x16x32_bf16 v[120:123], v[156:159], v[188:191], v[120:123]
	v_mfma_f32_16x16x32_bf16 v[124:127], v[164:167], v[188:191], v[124:127]
	v_mfma_f32_16x16x32_bf16 v[108:111], v[156:159], v[198:201], v[108:111]
	v_mfma_f32_16x16x32_bf16 v[116:119], v[164:167], v[198:201], v[116:119]
	v_mfma_f32_16x16x32_bf16 v[92:95], v[156:159], v[212:215], v[92:95]
	v_mfma_f32_16x16x32_bf16 v[112:115], v[164:167], v[212:215], v[112:115]
	v_mfma_f32_16x16x32_bf16 v[72:75], v[156:159], v[220:223], v[72:75]
	v_mfma_f32_16x16x32_bf16 v[100:103], v[164:167], v[220:223], v[100:103]
	v_mfma_f32_16x16x32_bf16 v[104:107], v[168:171], v[184:187], v[104:107]
	v_mfma_f32_16x16x32_bf16 v[88:91], v[176:179], v[184:187], v[88:91]
	v_mfma_f32_16x16x32_bf16 v[96:99], v[168:171], v[194:197], v[96:99]
	v_mfma_f32_16x16x32_bf16 v[76:79], v[176:179], v[194:197], v[76:79]
	v_mfma_f32_16x16x32_bf16 v[84:87], v[168:171], v[202:205], v[84:87]
	v_mfma_f32_16x16x32_bf16 v[68:71], v[176:179], v[202:205], v[68:71]
	v_mfma_f32_16x16x32_bf16 v[80:83], v[168:171], v[216:219], v[80:83]
	v_mfma_f32_16x16x32_bf16 v[64:67], v[176:179], v[216:219], v[64:67]
	v_mfma_f32_16x16x32_bf16 v[104:107], v[172:175], v[188:191], v[104:107]
	v_mfma_f32_16x16x32_bf16 v[88:91], v[180:183], v[188:191], v[88:91]
	v_mfma_f32_16x16x32_bf16 v[96:99], v[172:175], v[198:201], v[96:99]
	v_mfma_f32_16x16x32_bf16 v[76:79], v[180:183], v[198:201], v[76:79]
	v_mfma_f32_16x16x32_bf16 v[84:87], v[172:175], v[212:215], v[84:87]
	v_mfma_f32_16x16x32_bf16 v[68:71], v[180:183], v[212:215], v[68:71]
	v_mfma_f32_16x16x32_bf16 v[80:83], v[172:175], v[220:223], v[80:83]
	v_mfma_f32_16x16x32_bf16 v[64:67], v[180:183], v[220:223], v[64:67]
	s_barrier
; #define PG8_STAGE(bufoff, gbase, voff) do { _Pragma("unroll") for (int _i = 0; _i < 2; ++_i) \
;         __builtin_amdgcn_global_load_lds((const unsigned*)((const char*)(gbase) + (voff)[_i]), (PG8_LAS unsigned*)(lds + (bufoff) + ldsw + _i * 8192), 16, 0, 0); } while (0)
; #define PG8_LDA(dst, b, h) do { _Pragma("unroll") for (int m = 0; m < 4; ++m) _Pragma("unroll") for (int k = 0; k < 2; ++k) dst[m][k] = *(const PG8_LAS bf16x8*)(lds + PG8_SA(b, h) + aoff + m * 2048 + k * 1024); } while (0)
; #define PG8_MMA(ai, bj, At, Bt) do { __builtin_amdgcn_s_setprio(1); _Pragma("unroll") for (int m = 0; m < 4; ++m) _Pragma("unroll") for (int n = 0; n < 2; ++n) _Pragma("unroll") for (int k = 0; k < 2; ++k) \
;         acc[ai][bj][m][n] = __builtin_amdgcn_mfma_f32_16x16x32_bf16(Bt[n][k], At[m][k], acc[ai][bj][m][n], 0, 0, 0); __builtin_amdgcn_s_setprio(0); } while (0)
; #define PG8_WAIT_V(n) asm volatile("s_waitcnt vmcnt(" #n ")" ::: "memory")
; #define PG8_WAIT_L(n) asm volatile("s_waitcnt lgkmcnt(" #n ")" ::: "memory")
; #define PG8_BAR __builtin_amdgcn_s_barrier()
; #define PG8_SCHED __builtin_amdgcn_sched_barrier(0)
; template <class Epi, class Sched, bool ALIGN_EPI = false, bool SP2 = false>
; __device__ __forceinline__ void gemm_phase(PG8_LAS unsigned char* lds, const Gemm g, const Sched& S, const Epi& E, const int wid) {
;     ...
;             PG8_LDA(At, 1, 1); PG8_STAGE(PG8_SB(1, 0), b3, voffB); PG8_STAGE(PG8_SB(1, 1), b3 + hstep, voffB); PG8_STAGE(PG8_SA(1, 0), a3, voffA);
;             PG8_WAIT_V(8); PG8_WAIT_L(0); PG8_BAR; PG8_MMA(1, 0, At, B0); PG8_MMA(1, 1, At, B1); PG8_BAR; PG8_SCHED;
;     ...
;         if (!has_next) break;
; #pragma unroll
;         for (int a = 0; a < 2; ++a)
; #pragma unroll
;             for (int b = 0; b < 2; ++b)
; #pragma unroll
;                 for (int m = 0; m < 4; ++m)
; #pragma unroll
;                     for (int n = 0; n < 2; ++n) acc[a][b][m][n] = (f32x4){0.f, 0.f, 0.f, 0.f};
;         cur = nxt; cA = nA; cB = nB; ++ui;
	s_add_i32 s18, s45, s23
	v_lshl_add_u64 v[206:207], v[206:207], 0, s[10:11]
	s_mov_b32 m0, s18
	ds_read_b128 v[184:187], v150 offset:49152
	ds_read_b128 v[188:191], v150 offset:50176
	ds_read_b128 v[194:197], v150 offset:51200
	ds_read_b128 v[198:201], v150 offset:52224
	ds_read_b128 v[202:205], v150 offset:53248
	ds_read_b128 v[212:215], v150 offset:54272
	ds_read_b128 v[216:219], v150 offset:55296
	ds_read_b128 v[220:223], v150 offset:56320
	global_load_lds_dwordx4 v[206:207], off
	s_add_i32 m0, s18, 0x2000
	s_add_u32 s16, s16, 0xb0080
	v_lshl_add_u64 v[206:207], v[224:225], 0, s[10:11]
	s_addc_u32 s17, s17, 0
	s_add_i32 s18, s46, s23
	global_load_lds_dwordx4 v[206:207], off
	v_lshl_add_u64 v[206:207], s[16:17], 0, v[132:133]
	s_mov_b32 m0, s18
	s_nop 0
	global_load_lds_dwordx4 v[206:207], off
	v_lshl_add_u64 v[206:207], s[16:17], 0, v[128:129]
	s_add_i32 m0, s18, 0x2000
	s_nop 0
	global_load_lds_dwordx4 v[206:207], off
	v_lshl_add_u64 v[206:207], v[226:227], 0, s[10:11]
	s_mov_b32 m0, s31
	s_nop 0
	global_load_lds_dwordx4 v[206:207], off
	v_lshl_add_u64 v[206:207], v[228:229], 0, s[10:11]
	s_mov_b32 m0, s33
	s_nop 0
	global_load_lds_dwordx4 v[206:207], off
	s_waitcnt vmcnt(8)
	s_waitcnt lgkmcnt(0)
	s_barrier
	s_waitcnt lgkmcnt(0)
	v_mfma_f32_16x16x32_bf16 v[60:63], v[152:155], v[184:187], v[60:63]
	v_mfma_f32_16x16x32_bf16 v[56:59], v[160:163], v[184:187], v[56:59]
	v_mfma_f32_16x16x32_bf16 v[44:47], v[152:155], v[194:197], v[44:47]
	v_mfma_f32_16x16x32_bf16 v[40:43], v[160:163], v[194:197], v[40:43]
	v_mfma_f32_16x16x32_bf16 v[28:31], v[152:155], v[202:205], v[28:31]
	v_mfma_f32_16x16x32_bf16 v[24:27], v[160:163], v[202:205], v[24:27]
	v_mfma_f32_16x16x32_bf16 v[4:7], v[152:155], v[216:219], v[4:7]
	v_mfma_f32_16x16x32_bf16 v[12:15], v[160:163], v[216:219], v[12:15]
	v_mfma_f32_16x16x32_bf16 v[60:63], v[156:159], v[188:191], v[60:63]
	v_mfma_f32_16x16x32_bf16 v[56:59], v[164:167], v[188:191], v[56:59]
	v_mfma_f32_16x16x32_bf16 v[44:47], v[156:159], v[198:201], v[44:47]
	v_mfma_f32_16x16x32_bf16 v[40:43], v[164:167], v[198:201], v[40:43]
	v_mfma_f32_16x16x32_bf16 v[28:31], v[156:159], v[212:215], v[28:31]
	v_mfma_f32_16x16x32_bf16 v[24:27], v[164:167], v[212:215], v[24:27]
	v_mfma_f32_16x16x32_bf16 v[4:7], v[156:159], v[220:223], v[4:7]
	v_mfma_f32_16x16x32_bf16 v[12:15], v[164:167], v[220:223], v[12:15]
	v_mfma_f32_16x16x32_bf16 v[52:55], v[168:171], v[184:187], v[52:55]
	v_mfma_f32_16x16x32_bf16 v[48:51], v[176:179], v[184:187], v[48:51]
	v_mfma_f32_16x16x32_bf16 v[36:39], v[168:171], v[194:197], v[36:39]
	v_mfma_f32_16x16x32_bf16 v[32:35], v[176:179], v[194:197], v[32:35]
	v_mfma_f32_16x16x32_bf16 v[20:23], v[168:171], v[202:205], v[20:23]
	v_mfma_f32_16x16x32_bf16 v[16:19], v[176:179], v[202:205], v[16:19]
	v_mfma_f32_16x16x32_bf16 v[8:11], v[168:171], v[216:219], v[8:11]
	v_mfma_f32_16x16x32_bf16 v[0:3], v[176:179], v[216:219], v[0:3]
	v_mfma_f32_16x16x32_bf16 v[52:55], v[172:175], v[188:191], v[52:55]
	v_mfma_f32_16x16x32_bf16 v[48:51], v[180:183], v[188:191], v[48:51]
	v_mfma_f32_16x16x32_bf16 v[36:39], v[172:175], v[198:201], v[36:39]
	v_mfma_f32_16x16x32_bf16 v[32:35], v[180:183], v[198:201], v[32:35]
	v_mfma_f32_16x16x32_bf16 v[20:23], v[172:175], v[212:215], v[20:23]
	v_mfma_f32_16x16x32_bf16 v[16:19], v[180:183], v[212:215], v[16:19]
	v_mfma_f32_16x16x32_bf16 v[8:11], v[172:175], v[220:223], v[8:11]
	v_mfma_f32_16x16x32_bf16 v[0:3], v[180:183], v[220:223], v[0:3]
	s_barrier
	s_add_i32 s44, s44, 2
	s_add_u32 s14, s14, 0x100
	s_addc_u32 s15, s15, 0
	s_cmp_gt_u32 s44, 41
	s_cbranch_scc0 .LBB0_756
	s_add_u32 s14, s42, 0xffffff00
	s_addc_u32 s15, s43, -1
	s_and_b64 vcc, exec, s[6:7]
	s_cbranch_vccnz .LBB0_743
	v_mov_b32_e32 v0, 0
	s_mov_b32 s0, s39
	s_mov_b32 s20, s40
	s_mov_b64 s[2:3], s[12:13]
	s_mov_b32 s34, s41
	v_mov_b32_e32 v1, v0
	v_mov_b32_e32 v2, v0
	v_mov_b32_e32 v3, v0
	v_mov_b32_e32 v8, v0
	v_mov_b32_e32 v9, v0
	v_mov_b32_e32 v10, v0
	v_mov_b32_e32 v11, v0
	v_mov_b32_e32 v16, v0
	v_mov_b32_e32 v17, v0
	v_mov_b32_e32 v18, v0
	v_mov_b32_e32 v19, v0
	v_mov_b32_e32 v20, v0
	v_mov_b32_e32 v21, v0
	v_mov_b32_e32 v22, v0
	v_mov_b32_e32 v23, v0
	v_mov_b32_e32 v32, v0
	v_mov_b32_e32 v33, v0
	v_mov_b32_e32 v34, v0
	v_mov_b32_e32 v35, v0
	v_mov_b32_e32 v36, v0
	v_mov_b32_e32 v37, v0
	v_mov_b32_e32 v38, v0
	v_mov_b32_e32 v39, v0
	v_mov_b32_e32 v48, v0
	v_mov_b32_e32 v49, v0
	v_mov_b32_e32 v50, v0
	v_mov_b32_e32 v51, v0
	v_mov_b32_e32 v52, v0
	v_mov_b32_e32 v53, v0
	v_mov_b32_e32 v54, v0
	v_mov_b32_e32 v55, v0
	v_mov_b32_e32 v12, v0
	v_mov_b32_e32 v13, v0
	v_mov_b32_e32 v14, v0
	v_mov_b32_e32 v15, v0
	v_mov_b32_e32 v4, v0
	v_mov_b32_e32 v5, v0
	v_mov_b32_e32 v6, v0
	v_mov_b32_e32 v7, v0
	v_mov_b32_e32 v24, v0
	v_mov_b32_e32 v25, v0
	v_mov_b32_e32 v26, v0
	v_mov_b32_e32 v27, v0
	v_mov_b32_e32 v28, v0
	v_mov_b32_e32 v29, v0
	v_mov_b32_e32 v30, v0
	v_mov_b32_e32 v31, v0
	v_mov_b32_e32 v40, v0
	v_mov_b32_e32 v41, v0
	v_mov_b32_e32 v42, v0
	v_mov_b32_e32 v43, v0
	v_mov_b32_e32 v44, v0
	v_mov_b32_e32 v45, v0
	v_mov_b32_e32 v46, v0
	v_mov_b32_e32 v47, v0
	v_mov_b32_e32 v56, v0
	v_mov_b32_e32 v57, v0
	v_mov_b32_e32 v58, v0
	v_mov_b32_e32 v59, v0
	v_mov_b32_e32 v60, v0
	v_mov_b32_e32 v61, v0
	v_mov_b32_e32 v62, v0
	v_mov_b32_e32 v63, v0
	v_mov_b32_e32 v64, v0
	v_mov_b32_e32 v65, v0
	v_mov_b32_e32 v66, v0
	v_mov_b32_e32 v67, v0
	v_mov_b32_e32 v80, v0
	v_mov_b32_e32 v81, v0
	v_mov_b32_e32 v82, v0
	v_mov_b32_e32 v83, v0
	v_mov_b32_e32 v68, v0
	v_mov_b32_e32 v69, v0
	v_mov_b32_e32 v70, v0
	v_mov_b32_e32 v71, v0
	v_mov_b32_e32 v84, v0
	v_mov_b32_e32 v85, v0
	v_mov_b32_e32 v86, v0
	v_mov_b32_e32 v87, v0
	v_mov_b32_e32 v76, v0
	v_mov_b32_e32 v77, v0
	v_mov_b32_e32 v78, v0
	v_mov_b32_e32 v79, v0
	v_mov_b32_e32 v96, v0
	v_mov_b32_e32 v97, v0
	v_mov_b32_e32 v98, v0
	v_mov_b32_e32 v99, v0
	v_mov_b32_e32 v88, v0
	v_mov_b32_e32 v89, v0
	v_mov_b32_e32 v90, v0
	v_mov_b32_e32 v91, v0
	v_mov_b32_e32 v104, v0
	v_mov_b32_e32 v105, v0
	v_mov_b32_e32 v106, v0
	v_mov_b32_e32 v107, v0
	v_mov_b32_e32 v100, v0
	v_mov_b32_e32 v101, v0
	v_mov_b32_e32 v102, v0
	v_mov_b32_e32 v103, v0
	v_mov_b32_e32 v72, v0
	v_mov_b32_e32 v73, v0
	v_mov_b32_e32 v74, v0
	v_mov_b32_e32 v75, v0
	v_mov_b32_e32 v112, v0
	v_mov_b32_e32 v113, v0
	v_mov_b32_e32 v114, v0
	v_mov_b32_e32 v115, v0
	v_mov_b32_e32 v92, v0
	v_mov_b32_e32 v93, v0
	v_mov_b32_e32 v94, v0
	v_mov_b32_e32 v95, v0
	v_mov_b32_e32 v116, v0
	v_mov_b32_e32 v117, v0
	v_mov_b32_e32 v118, v0
	v_mov_b32_e32 v119, v0
	v_mov_b32_e32 v108, v0
	v_mov_b32_e32 v109, v0
	v_mov_b32_e32 v110, v0
	v_mov_b32_e32 v111, v0
	v_mov_b32_e32 v124, v0
	v_mov_b32_e32 v125, v0
	v_mov_b32_e32 v126, v0
	v_mov_b32_e32 v127, v0
	v_mov_b32_e32 v120, v0
	v_mov_b32_e32 v121, v0
	v_mov_b32_e32 v122, v0
	v_mov_b32_e32 v123, v0
	s_andn2_b64 vcc, exec, s[4:5]
	s_cbranch_vccnz .LBB0_744

; template <class Epi, class Sched, bool ALIGN_EPI = false, bool SP2 = false>
; __device__ __forceinline__ void gemm_phase(PG8_LAS unsigned char* lds, const Gemm g, const Sched& S, const Epi& E, const int wid) {
;     ...
;         const bool has_next = S.next(ui + 1, nxt);
;         const char* nA = has_next ? (const char*)g.A + (size_t)nxt.pm * tstep : cA; const char* nB = has_next ? (const char*)g.Bt + (size_t)nxt.pn * tstep : cB;
.LBB0_881:
	s_ashr_i32 s13, s12, 31
	s_lshl_b64 s[14:15], s[12:13], 19
	s_add_u32 s14, s80, s14
	s_addc_u32 s15, s81, s15
	s_and_b64 s[18:19], s[4:5], exec
	s_cselect_b32 s13, s15, s21
	s_cselect_b32 s43, s14, s20
	s_ashr_i32 s9, s8, 31
	s_lshl_b64 s[18:19], s[8:9], 19
	s_add_u32 s18, s10, s18
	s_addc_u32 s19, s11, s19
	s_and_b64 s[24:25], s[4:5], exec
	s_cselect_b32 s9, s19, s23
	s_cselect_b32 s44, s18, s22
	s_add_u32 s20, s20, 0x40080
	s_addc_u32 s21, s21, 0
	s_add_u32 s45, s22, 0x100

; template <class Epi, class Sched, bool ALIGN_EPI = false, bool SP2 = false>
; __device__ __forceinline__ void gemm_phase(PG8_LAS unsigned char* lds, const Gemm g, const Sched& S, const Epi& E, const int wid) {
;     ...
;         const char* nA = has_next ? (const char*)g.A + (size_t)nxt.pm * tstep : cA; const char* nB = has_next ? (const char*)g.Bt + (size_t)nxt.pn * tstep : cB;
;         for (int t = 0; t < nt; t += 2) {
	s_addc_u32 s46, s23, 0
	s_mov_b32 s47, -2


; #define PG8_STAGE(bufoff, gbase, voff) do { _Pragma("unroll") for (int _i = 0; _i < 2; ++_i) \
;         __builtin_amdgcn_global_load_lds((const unsigned*)((const char*)(gbase) + (voff)[_i]), (PG8_LAS unsigned*)(lds + (bufoff) + ldsw + _i * 8192), 16, 0, 0); } while (0)
; #define PG8_LDA(dst, b, h) do { _Pragma("unroll") for (int m = 0; m < 4; ++m) _Pragma("unroll") for (int k = 0; k < 2; ++k) dst[m][k] = *(const PG8_LAS bf16x8*)(lds + PG8_SA(b, h) + aoff + m * 2048 + k * 1024); } while (0)
; #define PG8_LDB(dst, b, h) do { _Pragma("unroll") for (int n = 0; n < 2; ++n) _Pragma("unroll") for (int k = 0; k < 2; ++k) dst[n][k] = *(const PG8_LAS bf16x8*)(lds + PG8_SB(b, h) + boff + n * 2048 + k * 1024); } while (0)
; #define PG8_MMA(ai, bj, At, Bt) do { __builtin_amdgcn_s_setprio(1); _Pragma("unroll") for (int m = 0; m < 4; ++m) _Pragma("unroll") for (int n = 0; n < 2; ++n) _Pragma("unroll") for (int k = 0; k < 2; ++k) \
;         acc[ai][bj][m][n] = __builtin_amdgcn_mfma_f32_16x16x32_bf16(Bt[n][k], At[m][k], acc[ai][bj][m][n], 0, 0, 0); __builtin_amdgcn_s_setprio(0); } while (0)
; #define PG8_WAIT_V(n) asm volatile("s_waitcnt vmcnt(" #n ")" ::: "memory")
; #define PG8_WAIT_L(n) asm volatile("s_waitcnt lgkmcnt(" #n ")" ::: "memory")
; #define PG8_BAR __builtin_amdgcn_s_barrier()
; #define PG8_SCHED __builtin_amdgcn_sched_barrier(0)
; template <class Epi, class Sched, bool ALIGN_EPI = false, bool SP2 = false>
; __device__ __forceinline__ void gemm_phase(PG8_LAS unsigned char* lds, const Gemm g, const Sched& S, const Epi& E, const int wid) {
;     ...
;             PG8_LDB(B0, 0, 0); PG8_LDB(B1, 0, 1); PG8_SCHED; PG8_LDA(At, 0, 0); PG8_STAGE(PG8_SA(1, 1), a1 + hstep, voffA);
;             PG8_WAIT_V(8); PG8_WAIT_L(0); PG8_BAR; PG8_MMA(0, 0, At, B0); PG8_MMA(0, 1, At, B1); PG8_BAR; PG8_SCHED;
;             PG8_LDA(At, 0, 1); PG8_STAGE(PG8_SB(0, 0), b2, voffB); PG8_STAGE(PG8_SB(0, 1), b2 + hstep, voffB); PG8_STAGE(PG8_SA(0, 0), a2, voffA);
;             PG8_WAIT_V(8); PG8_WAIT_L(0); PG8_BAR; PG8_MMA(1, 0, At, B0); PG8_MMA(1, 1, At, B1); PG8_BAR; PG8_SCHED;
	ds_read_b128 v[152:155], v149
	ds_read_b128 v[156:159], v149 offset:1024
	ds_read_b128 v[160:163], v149 offset:2048
	ds_read_b128 v[164:167], v149 offset:3072
	ds_read_b128 v[168:171], v150
	ds_read_b128 v[172:175], v150 offset:1024
	ds_read_b128 v[176:179], v150 offset:2048
	ds_read_b128 v[180:183], v150 offset:3072
	s_add_u32 s22, s20, 0xfffc0080
	s_addc_u32 s23, s21, -1
	s_cmp_eq_u32 s47, 12
	s_cselect_b32 s25, s13, s23
	s_cselect_b32 s24, s43, s22
	s_cselect_b32 s23, s9, s46
	s_cselect_b32 s22, s44, s45
	v_lshl_add_u64 v[144:145], s[20:21], 0, v[136:137]
	s_add_i32 m0, s17, 0xc000
	ds_read_b128 v[184:187], v151
	ds_read_b128 v[188:191], v151 offset:1024
	ds_read_b128 v[192:195], v151 offset:2048
	ds_read_b128 v[196:199], v151 offset:3072
	ds_read_b128 v[200:203], v151 offset:4096
	ds_read_b128 v[204:207], v151 offset:5120
	ds_read_b128 v[212:215], v151 offset:6144
	ds_read_b128 v[216:219], v151 offset:7168
	global_load_lds_dwordx4 v[144:145], off
	v_lshl_add_u64 v[144:145], s[20:21], 0, v[138:139]
	s_add_i32 m0, s17, 0xe000
	s_nop 0
	global_load_lds_dwordx4 v[144:145], off
	s_waitcnt vmcnt(8)
	s_waitcnt lgkmcnt(0)
	s_barrier
	s_waitcnt lgkmcnt(0)
	v_mfma_f32_16x16x32_bf16 v[124:127], v[152:155], v[184:187], 0
	v_mfma_f32_16x16x32_bf16 v[120:123], v[160:163], v[184:187], 0
	v_mfma_f32_16x16x32_bf16 v[116:119], v[152:155], v[192:195], 0
	v_mfma_f32_16x16x32_bf16 v[108:111], v[160:163], v[192:195], 0
	v_mfma_f32_16x16x32_bf16 v[100:103], v[152:155], v[200:203], 0
	v_mfma_f32_16x16x32_bf16 v[92:95], v[160:163], v[200:203], 0
	v_mfma_f32_16x16x32_bf16 v[84:87], v[152:155], v[212:215], 0
	v_mfma_f32_16x16x32_bf16 v[76:79], v[160:163], v[212:215], 0
	v_mfma_f32_16x16x32_bf16 v[124:127], v[156:159], v[188:191], v[124:127]
	v_mfma_f32_16x16x32_bf16 v[120:123], v[164:167], v[188:191], v[120:123]
	v_mfma_f32_16x16x32_bf16 v[116:119], v[156:159], v[196:199], v[116:119]
	v_mfma_f32_16x16x32_bf16 v[108:111], v[164:167], v[196:199], v[108:111]
	v_mfma_f32_16x16x32_bf16 v[100:103], v[156:159], v[204:207], v[100:103]
	v_mfma_f32_16x16x32_bf16 v[92:95], v[164:167], v[204:207], v[92:95]
	v_mfma_f32_16x16x32_bf16 v[84:87], v[156:159], v[216:219], v[84:87]
	v_mfma_f32_16x16x32_bf16 v[76:79], v[164:167], v[216:219], v[76:79]
	v_mfma_f32_16x16x32_bf16 v[112:115], v[168:171], v[184:187], 0
	v_mfma_f32_16x16x32_bf16 v[104:107], v[176:179], v[184:187], 0
	v_mfma_f32_16x16x32_bf16 v[96:99], v[168:171], v[192:195], 0
	v_mfma_f32_16x16x32_bf16 v[88:91], v[176:179], v[192:195], 0
	v_mfma_f32_16x16x32_bf16 v[80:83], v[168:171], v[200:203], 0
	v_mfma_f32_16x16x32_bf16 v[72:75], v[176:179], v[200:203], 0
	v_mfma_f32_16x16x32_bf16 v[68:71], v[168:171], v[212:215], 0
	v_mfma_f32_16x16x32_bf16 v[64:67], v[176:179], v[212:215], 0
	v_mfma_f32_16x16x32_bf16 v[112:115], v[172:175], v[188:191], v[112:115]
	v_mfma_f32_16x16x32_bf16 v[104:107], v[180:183], v[188:191], v[104:107]
	v_mfma_f32_16x16x32_bf16 v[96:99], v[172:175], v[196:199], v[96:99]
	v_mfma_f32_16x16x32_bf16 v[88:91], v[180:183], v[196:199], v[88:91]
	v_mfma_f32_16x16x32_bf16 v[80:83], v[172:175], v[204:207], v[80:83]
	v_mfma_f32_16x16x32_bf16 v[72:75], v[180:183], v[204:207], v[72:75]
	v_mfma_f32_16x16x32_bf16 v[68:71], v[172:175], v[216:219], v[68:71]
	v_mfma_f32_16x16x32_bf16 v[64:67], v[180:183], v[216:219], v[64:67]
	s_barrier
	s_add_i32 s48, s39, s26
	v_lshl_add_u64 v[144:145], s[22:23], 0, v[132:133]
	s_mov_b32 m0, s48
	ds_read_b128 v[184:187], v151 offset:16384
	ds_read_b128 v[188:191], v151 offset:17408
	ds_read_b128 v[192:195], v151 offset:18432
	ds_read_b128 v[196:199], v151 offset:19456
	ds_read_b128 v[200:203], v151 offset:20480
	ds_read_b128 v[204:207], v151 offset:21504
	ds_read_b128 v[212:215], v151 offset:22528
	ds_read_b128 v[216:219], v151 offset:23552
	global_load_lds_dwordx4 v[144:145], off
	s_add_i32 m0, s48, 0x2000
	s_add_u32 s48, s22, 0x40000
	v_lshl_add_u64 v[220:221], s[22:23], 0, v[128:129]
	s_addc_u32 s49, s23, 0
	s_add_i32 s50, s40, s26
	global_load_lds_dwordx4 v[220:221], off
	v_lshl_add_u64 v[222:223], s[48:49], 0, v[132:133]
	s_mov_b32 m0, s50
	v_lshl_add_u64 v[224:225], s[24:25], 0, v[130:131]
	global_load_lds_dwordx4 v[222:223], off
	v_lshl_add_u64 v[222:223], s[48:49], 0, v[128:129]
	s_add_i32 m0, s50, 0x2000
	s_nop 0
	global_load_lds_dwordx4 v[222:223], off
	v_lshl_add_u64 v[222:223], s[24:25], 0, v[134:135]
	s_mov_b32 m0, s17
	s_nop 0
	global_load_lds_dwordx4 v[222:223], off
	s_mov_b32 m0, s29
	s_nop 0
	global_load_lds_dwordx4 v[224:225], off
	s_nop 0
	s_waitcnt vmcnt(8)
	s_waitcnt lgkmcnt(0)
	s_barrier
	s_waitcnt lgkmcnt(0)
	v_mfma_f32_16x16x32_bf16 v[60:63], v[152:155], v[184:187], 0
	v_mfma_f32_16x16x32_bf16 v[56:59], v[160:163], v[184:187], 0
	v_mfma_f32_16x16x32_bf16 v[52:55], v[152:155], v[192:195], 0
	v_mfma_f32_16x16x32_bf16 v[44:47], v[160:163], v[192:195], 0
	v_mfma_f32_16x16x32_bf16 v[36:39], v[152:155], v[200:203], 0
	v_mfma_f32_16x16x32_bf16 v[28:31], v[160:163], v[200:203], 0
	v_mfma_f32_16x16x32_bf16 v[20:23], v[152:155], v[212:215], 0
	v_mfma_f32_16x16x32_bf16 v[12:15], v[160:163], v[212:215], 0
	v_mfma_f32_16x16x32_bf16 v[60:63], v[156:159], v[188:191], v[60:63]
	v_mfma_f32_16x16x32_bf16 v[56:59], v[164:167], v[188:191], v[56:59]
	v_mfma_f32_16x16x32_bf16 v[52:55], v[156:159], v[196:199], v[52:55]
	v_mfma_f32_16x16x32_bf16 v[44:47], v[164:167], v[196:199], v[44:47]
	v_mfma_f32_16x16x32_bf16 v[36:39], v[156:159], v[204:207], v[36:39]
	v_mfma_f32_16x16x32_bf16 v[28:31], v[164:167], v[204:207], v[28:31]
	v_mfma_f32_16x16x32_bf16 v[20:23], v[156:159], v[216:219], v[20:23]
	v_mfma_f32_16x16x32_bf16 v[12:15], v[164:167], v[216:219], v[12:15]
	v_mfma_f32_16x16x32_bf16 v[48:51], v[168:171], v[184:187], 0
	v_mfma_f32_16x16x32_bf16 v[40:43], v[176:179], v[184:187], 0
	v_mfma_f32_16x16x32_bf16 v[32:35], v[168:171], v[192:195], 0
	v_mfma_f32_16x16x32_bf16 v[24:27], v[176:179], v[192:195], 0
	v_mfma_f32_16x16x32_bf16 v[16:19], v[168:171], v[200:203], 0
	v_mfma_f32_16x16x32_bf16 v[8:11], v[176:179], v[200:203], 0
	v_mfma_f32_16x16x32_bf16 v[4:7], v[168:171], v[212:215], 0
	v_mfma_f32_16x16x32_bf16 v[0:3], v[176:179], v[212:215], 0
	v_mfma_f32_16x16x32_bf16 v[48:51], v[172:175], v[188:191], v[48:51]
	v_mfma_f32_16x16x32_bf16 v[40:43], v[180:183], v[188:191], v[40:43]
	v_mfma_f32_16x16x32_bf16 v[32:35], v[172:175], v[196:199], v[32:35]
	v_mfma_f32_16x16x32_bf16 v[24:27], v[180:183], v[196:199], v[24:27]
	v_mfma_f32_16x16x32_bf16 v[16:19], v[172:175], v[204:207], v[16:19]
	v_mfma_f32_16x16x32_bf16 v[8:11], v[180:183], v[204:207], v[8:11]
	v_mfma_f32_16x16x32_bf16 v[4:7], v[172:175], v[216:219], v[4:7]
	v_mfma_f32_16x16x32_bf16 v[0:3], v[180:183], v[216:219], v[0:3]
	s_barrier
; #define PG8_STAGE(bufoff, gbase, voff) do { _Pragma("unroll") for (int _i = 0; _i < 2; ++_i) \
;         __builtin_amdgcn_global_load_lds((const unsigned*)((const char*)(gbase) + (voff)[_i]), (PG8_LAS unsigned*)(lds + (bufoff) + ldsw + _i * 8192), 16, 0, 0); } while (0)
; #define PG8_LDA(dst, b, h) do { _Pragma("unroll") for (int m = 0; m < 4; ++m) _Pragma("unroll") for (int k = 0; k < 2; ++k) dst[m][k] = *(const PG8_LAS bf16x8*)(lds + PG8_SA(b, h) + aoff + m * 2048 + k * 1024); } while (0)
; #define PG8_LDB(dst, b, h) do { _Pragma("unroll") for (int n = 0; n < 2; ++n) _Pragma("unroll") for (int k = 0; k < 2; ++k) dst[n][k] = *(const PG8_LAS bf16x8*)(lds + PG8_SB(b, h) + boff + n * 2048 + k * 1024); } while (0)
; #define PG8_MMA(ai, bj, At, Bt) do { __builtin_amdgcn_s_setprio(1); _Pragma("unroll") for (int m = 0; m < 4; ++m) _Pragma("unroll") for (int n = 0; n < 2; ++n) _Pragma("unroll") for (int k = 0; k < 2; ++k) \
;         acc[ai][bj][m][n] = __builtin_amdgcn_mfma_f32_16x16x32_bf16(Bt[n][k], At[m][k], acc[ai][bj][m][n], 0, 0, 0); __builtin_amdgcn_s_setprio(0); } while (0)
; #define PG8_WAIT_V(n) asm volatile("s_waitcnt vmcnt(" #n ")" ::: "memory")
; #define PG8_WAIT_L(n) asm volatile("s_waitcnt lgkmcnt(" #n ")" ::: "memory")
; #define PG8_BAR __builtin_amdgcn_s_barrier()
; #define PG8_SCHED __builtin_amdgcn_sched_barrier(0)
; template <class Epi, class Sched, bool ALIGN_EPI = false, bool SP2 = false>
; __device__ __forceinline__ void gemm_phase(PG8_LAS unsigned char* lds, const Gemm g, const Sched& S, const Epi& E, const int wid) {
;     ...
;             PG8_LDB(B0, 1, 0); PG8_LDB(B1, 1, 1); PG8_SCHED; PG8_LDA(At, 1, 0); PG8_STAGE(PG8_SA(0, 1), a2 + hstep, voffA);
;             PG8_WAIT_V(8); PG8_WAIT_L(0); PG8_BAR; PG8_MMA(0, 0, At, B0); PG8_MMA(0, 1, At, B1); PG8_BAR; PG8_SCHED;
;             PG8_LDA(At, 1, 1); PG8_STAGE(PG8_SB(1, 0), b3, voffB); PG8_STAGE(PG8_SB(1, 1), b3 + hstep, voffB); PG8_STAGE(PG8_SA(1, 0), a3, voffA);
	s_add_i32 s48, 0, 0x18000
	s_add_i32 s49, 0, 0x1c000
	v_add_u32_e32 v164, s48, v147
	v_add_u32_e32 v180, s49, v147
	ds_read_b128 v[152:155], v164
	ds_read_b128 v[156:159], v164 offset:1024
	ds_read_b128 v[160:163], v164 offset:2048
	ds_read_b128 v[164:167], v164 offset:3072
	ds_read_b128 v[168:171], v180
	ds_read_b128 v[172:175], v180 offset:1024
	ds_read_b128 v[176:179], v180 offset:2048
	ds_read_b128 v[180:183], v180 offset:3072
	s_add_u32 s24, s24, 0x40000
	s_addc_u32 s25, s25, 0
	s_mov_b32 m0, s30
	v_lshl_add_u64 v[226:227], s[24:25], 0, v[134:135]
	ds_read_b128 v[184:187], v151 offset:32768
	ds_read_b128 v[188:191], v151 offset:33792
	ds_read_b128 v[192:195], v151 offset:34816
	ds_read_b128 v[196:199], v151 offset:35840
	ds_read_b128 v[200:203], v151 offset:36864
	ds_read_b128 v[204:207], v151 offset:37888
	ds_read_b128 v[212:215], v151 offset:38912
	ds_read_b128 v[216:219], v151 offset:39936
	global_load_lds_dwordx4 v[226:227], off
	v_lshl_add_u64 v[226:227], s[24:25], 0, v[130:131]
	s_mov_b32 m0, s31
	s_nop 0
	global_load_lds_dwordx4 v[226:227], off
	s_nop 0
	s_waitcnt vmcnt(8)
	s_waitcnt lgkmcnt(0)
	s_barrier
	s_waitcnt lgkmcnt(0)
	v_mfma_f32_16x16x32_bf16 v[124:127], v[152:155], v[184:187], v[124:127]
	v_mfma_f32_16x16x32_bf16 v[120:123], v[160:163], v[184:187], v[120:123]
	v_mfma_f32_16x16x32_bf16 v[116:119], v[152:155], v[192:195], v[116:119]
	v_mfma_f32_16x16x32_bf16 v[108:111], v[160:163], v[192:195], v[108:111]
	v_mfma_f32_16x16x32_bf16 v[100:103], v[152:155], v[200:203], v[100:103]
	v_mfma_f32_16x16x32_bf16 v[92:95], v[160:163], v[200:203], v[92:95]
	v_mfma_f32_16x16x32_bf16 v[84:87], v[152:155], v[212:215], v[84:87]
	v_mfma_f32_16x16x32_bf16 v[76:79], v[160:163], v[212:215], v[76:79]
	v_mfma_f32_16x16x32_bf16 v[124:127], v[156:159], v[188:191], v[124:127]
	v_mfma_f32_16x16x32_bf16 v[120:123], v[164:167], v[188:191], v[120:123]
	v_mfma_f32_16x16x32_bf16 v[116:119], v[156:159], v[196:199], v[116:119]
	v_mfma_f32_16x16x32_bf16 v[108:111], v[164:167], v[196:199], v[108:111]
	v_mfma_f32_16x16x32_bf16 v[100:103], v[156:159], v[204:207], v[100:103]
	v_mfma_f32_16x16x32_bf16 v[92:95], v[164:167], v[204:207], v[92:95]
	v_mfma_f32_16x16x32_bf16 v[84:87], v[156:159], v[216:219], v[84:87]
	v_mfma_f32_16x16x32_bf16 v[76:79], v[164:167], v[216:219], v[76:79]
	v_mfma_f32_16x16x32_bf16 v[112:115], v[168:171], v[184:187], v[112:115]
	v_mfma_f32_16x16x32_bf16 v[104:107], v[176:179], v[184:187], v[104:107]
	v_mfma_f32_16x16x32_bf16 v[96:99], v[168:171], v[192:195], v[96:99]
	v_mfma_f32_16x16x32_bf16 v[88:91], v[176:179], v[192:195], v[88:91]
	v_mfma_f32_16x16x32_bf16 v[80:83], v[168:171], v[200:203], v[80:83]
	v_mfma_f32_16x16x32_bf16 v[72:75], v[176:179], v[200:203], v[72:75]
	v_mfma_f32_16x16x32_bf16 v[68:71], v[168:171], v[212:215], v[68:71]
	v_mfma_f32_16x16x32_bf16 v[64:67], v[176:179], v[212:215], v[64:67]
	v_mfma_f32_16x16x32_bf16 v[112:115], v[172:175], v[188:191], v[112:115]
	v_mfma_f32_16x16x32_bf16 v[104:107], v[180:183], v[188:191], v[104:107]
	v_mfma_f32_16x16x32_bf16 v[96:99], v[172:175], v[196:199], v[96:99]
	v_mfma_f32_16x16x32_bf16 v[88:91], v[180:183], v[196:199], v[88:91]
	v_mfma_f32_16x16x32_bf16 v[80:83], v[172:175], v[204:207], v[80:83]
	v_mfma_f32_16x16x32_bf16 v[72:75], v[180:183], v[204:207], v[72:75]
	v_mfma_f32_16x16x32_bf16 v[68:71], v[172:175], v[216:219], v[68:71]
	v_mfma_f32_16x16x32_bf16 v[64:67], v[180:183], v[216:219], v[64:67]
	s_barrier
	s_add_i32 s24, s48, s26
	v_lshl_add_u64 v[144:145], v[144:145], 0, s[6:7]
	s_mov_b32 m0, s24
	ds_read_b128 v[184:187], v151 offset:49152
	ds_read_b128 v[188:191], v151 offset:50176
	ds_read_b128 v[192:195], v151 offset:51200
	ds_read_b128 v[196:199], v151 offset:52224
	ds_read_b128 v[200:203], v151 offset:53248
	ds_read_b128 v[204:207], v151 offset:54272
	ds_read_b128 v[212:215], v151 offset:55296
	ds_read_b128 v[216:219], v151 offset:56320
	global_load_lds_dwordx4 v[144:145], off
	s_add_i32 m0, s24, 0x2000
	s_add_u32 s22, s22, 0x40080
	v_lshl_add_u64 v[144:145], v[220:221], 0, s[6:7]
	s_addc_u32 s23, s23, 0
	s_add_i32 s24, s49, s26
	global_load_lds_dwordx4 v[144:145], off
	v_lshl_add_u64 v[144:145], s[22:23], 0, v[132:133]
	s_mov_b32 m0, s24
	s_nop 0
	global_load_lds_dwordx4 v[144:145], off
	v_lshl_add_u64 v[144:145], s[22:23], 0, v[128:129]
	s_add_i32 m0, s24, 0x2000
	s_nop 0
	global_load_lds_dwordx4 v[144:145], off
	v_lshl_add_u64 v[144:145], v[222:223], 0, s[6:7]
	s_mov_b32 m0, s37
	s_nop 0
	global_load_lds_dwordx4 v[144:145], off
	v_lshl_add_u64 v[144:145], v[224:225], 0, s[6:7]
	s_mov_b32 m0, s38
	s_nop 0
	global_load_lds_dwordx4 v[144:145], off
	s_waitcnt vmcnt(8)
	s_waitcnt lgkmcnt(0)
	s_barrier
; #define PG8_STAGE(bufoff, gbase, voff) do { _Pragma("unroll") for (int _i = 0; _i < 2; ++_i) \
;         __builtin_amdgcn_global_load_lds((const unsigned*)((const char*)(gbase) + (voff)[_i]), (PG8_LAS unsigned*)(lds + (bufoff) + ldsw + _i * 8192), 16, 0, 0); } while (0)
; #define PG8_LDA(dst, b, h) do { _Pragma("unroll") for (int m = 0; m < 4; ++m) _Pragma("unroll") for (int k = 0; k < 2; ++k) dst[m][k] = *(const PG8_LAS bf16x8*)(lds + PG8_SA(b, h) + aoff + m * 2048 + k * 1024); } while (0)
; #define PG8_WAIT_V(n) asm volatile("s_waitcnt vmcnt(" #n ")" ::: "memory")
; #define PG8_WAIT_L(n) asm volatile("s_waitcnt lgkmcnt(" #n ")" ::: "memory")
; #define PG8_BAR __builtin_amdgcn_s_barrier()
; template <class Epi, class Sched, bool ALIGN_EPI = false, bool SP2 = false>
; __device__ __forceinline__ void gemm_phase(PG8_LAS unsigned char* lds, const Gemm g, const Sched& S, const Epi& E, const int wid) {
;     ...
;         for (int t = 0; t < nt; t += 2) {
;             const bool last = (t == nt - 2);
;             const char* a1 = cA + (size_t)(t + 1) * kstep;
;             const char* a2 = last ? nA : cA + (size_t)(t + 2) * kstep; const char* b2 = last ? nB : cB + (size_t)(t + 2) * kstep;
;             const char* a3 = a2 + kstep; const char* b3 = b2 + kstep;
;             if (last && has_next) S.a_ready(nxt);
;             if constexpr (SP2) {
;             PG8_LDB(B0, 0, 0); PG8_LDB(B1, 0, 1); PG8_SCHED; PG8_LDA(At, 0, 0); PG8_STAGE(PG8_SA(1, 1), a1 + hstep, voffA);
;             PG8_WAIT_V(8); PG8_WAIT_L(0); PG8_BAR; PG8_MMA(0, 0, At, B0); PG8_MMA(0, 1, At, B1); PG8_BAR; PG8_SCHED;
;             PG8_LDA(At, 0, 1); PG8_STAGE(PG8_SB(0, 0), b2, voffB); PG8_STAGE(PG8_SB(0, 1), b2 + hstep, voffB); PG8_STAGE(PG8_SA(0, 0), a2, voffA);
;             PG8_WAIT_V(8); PG8_WAIT_L(0); PG8_BAR; PG8_MMA(1, 0, At, B0); PG8_MMA(1, 1, At, B1); PG8_BAR; PG8_SCHED;
;             PG8_LDB(B0, 1, 0); PG8_LDB(B1, 1, 1); PG8_SCHED; PG8_LDA(At, 1, 0); PG8_STAGE(PG8_SA(0, 1), a2 + hstep, voffA);
;             PG8_WAIT_V(8); PG8_WAIT_L(0); PG8_BAR; PG8_MMA(0, 0, At, B0); PG8_MMA(0, 1, At, B1); PG8_BAR; PG8_SCHED;
;             PG8_LDA(At, 1, 1); PG8_STAGE(PG8_SB(1, 0), b3, voffB); PG8_STAGE(PG8_SB(1, 1), b3 + hstep, voffB); PG8_STAGE(PG8_SA(1, 0), a3, voffA);
;             PG8_WAIT_V(8); PG8_WAIT_L(0); PG8_BAR; PG8_MMA(1, 0, At, B0); PG8_MMA(1, 1, At, B1); PG8_BAR; PG8_SCHED;
	s_waitcnt lgkmcnt(0)
	v_mfma_f32_16x16x32_bf16 v[60:63], v[152:155], v[184:187], v[60:63]
	v_mfma_f32_16x16x32_bf16 v[56:59], v[160:163], v[184:187], v[56:59]
	v_mfma_f32_16x16x32_bf16 v[52:55], v[152:155], v[192:195], v[52:55]
	v_mfma_f32_16x16x32_bf16 v[44:47], v[160:163], v[192:195], v[44:47]
	v_mfma_f32_16x16x32_bf16 v[36:39], v[152:155], v[200:203], v[36:39]
	v_mfma_f32_16x16x32_bf16 v[28:31], v[160:163], v[200:203], v[28:31]
	v_mfma_f32_16x16x32_bf16 v[20:23], v[152:155], v[212:215], v[20:23]
	v_mfma_f32_16x16x32_bf16 v[12:15], v[160:163], v[212:215], v[12:15]
	v_mfma_f32_16x16x32_bf16 v[60:63], v[156:159], v[188:191], v[60:63]
	v_mfma_f32_16x16x32_bf16 v[56:59], v[164:167], v[188:191], v[56:59]
	v_mfma_f32_16x16x32_bf16 v[52:55], v[156:159], v[196:199], v[52:55]
	v_mfma_f32_16x16x32_bf16 v[44:47], v[164:167], v[196:199], v[44:47]
	v_mfma_f32_16x16x32_bf16 v[36:39], v[156:159], v[204:207], v[36:39]
	v_mfma_f32_16x16x32_bf16 v[28:31], v[164:167], v[204:207], v[28:31]
	v_mfma_f32_16x16x32_bf16 v[20:23], v[156:159], v[216:219], v[20:23]
	v_mfma_f32_16x16x32_bf16 v[12:15], v[164:167], v[216:219], v[12:15]
	v_mfma_f32_16x16x32_bf16 v[48:51], v[168:171], v[184:187], v[48:51]
	v_mfma_f32_16x16x32_bf16 v[40:43], v[176:179], v[184:187], v[40:43]
	v_mfma_f32_16x16x32_bf16 v[32:35], v[168:171], v[192:195], v[32:35]
	v_mfma_f32_16x16x32_bf16 v[24:27], v[176:179], v[192:195], v[24:27]
	v_mfma_f32_16x16x32_bf16 v[16:19], v[168:171], v[200:203], v[16:19]
	v_mfma_f32_16x16x32_bf16 v[8:11], v[176:179], v[200:203], v[8:11]
	v_mfma_f32_16x16x32_bf16 v[4:7], v[168:171], v[212:215], v[4:7]
	v_mfma_f32_16x16x32_bf16 v[0:3], v[176:179], v[212:215], v[0:3]
	v_mfma_f32_16x16x32_bf16 v[48:51], v[172:175], v[188:191], v[48:51]
	v_mfma_f32_16x16x32_bf16 v[40:43], v[180:183], v[188:191], v[40:43]
	v_mfma_f32_16x16x32_bf16 v[32:35], v[172:175], v[196:199], v[32:35]
	v_mfma_f32_16x16x32_bf16 v[24:27], v[180:183], v[196:199], v[24:27]
	v_mfma_f32_16x16x32_bf16 v[16:19], v[172:175], v[204:207], v[16:19]
	v_mfma_f32_16x16x32_bf16 v[8:11], v[180:183], v[204:207], v[8:11]
	v_mfma_f32_16x16x32_bf16 v[4:7], v[172:175], v[216:219], v[4:7]
	v_mfma_f32_16x16x32_bf16 v[0:3], v[180:183], v[216:219], v[0:3]
	s_barrier
	s_add_i32 s47, s47, 2
	s_add_u32 s20, s20, 0x100
	s_addc_u32 s21, s21, 0
	s_add_u32 s45, s45, 0x100
	s_addc_u32 s46, s46, 0
	s_cmp_gt_u32 s47, 13
	s_cbranch_scc0 .LBB0_882
	s_branch .Lkp_exit_2
.LBB0_882:
	ds_read_b128 v[152:155], v149
	ds_read_b128 v[156:159], v149 offset:1024
	ds_read_b128 v[160:163], v149 offset:2048
	ds_read_b128 v[164:167], v149 offset:3072
	ds_read_b128 v[168:171], v150
	ds_read_b128 v[172:175], v150 offset:1024
	ds_read_b128 v[176:179], v150 offset:2048
	ds_read_b128 v[180:183], v150 offset:3072
	s_add_u32 s22, s20, 0xfffc0080
	s_addc_u32 s23, s21, -1
	s_cmp_eq_u32 s47, 12
	s_cselect_b32 s25, s13, s23
	s_cselect_b32 s24, s43, s22
	s_cselect_b32 s23, s9, s46
	s_cselect_b32 s22, s44, s45
	v_lshl_add_u64 v[144:145], s[20:21], 0, v[136:137]
	s_add_i32 m0, s17, 0xc000
	ds_read_b128 v[184:187], v151
	ds_read_b128 v[188:191], v151 offset:1024
	ds_read_b128 v[192:195], v151 offset:2048
	ds_read_b128 v[196:199], v151 offset:3072
	ds_read_b128 v[200:203], v151 offset:4096
	ds_read_b128 v[204:207], v151 offset:5120
	ds_read_b128 v[212:215], v151 offset:6144
	ds_read_b128 v[216:219], v151 offset:7168
	global_load_lds_dwordx4 v[144:145], off
	v_lshl_add_u64 v[144:145], s[20:21], 0, v[138:139]
	s_add_i32 m0, s17, 0xe000
	s_nop 0
	global_load_lds_dwordx4 v[144:145], off
	s_waitcnt vmcnt(8)
	s_waitcnt lgkmcnt(0)
	s_barrier
	s_waitcnt lgkmcnt(0)
	v_mfma_f32_16x16x32_bf16 v[124:127], v[152:155], v[184:187], v[124:127]
	v_mfma_f32_16x16x32_bf16 v[120:123], v[160:163], v[184:187], v[120:123]
	v_mfma_f32_16x16x32_bf16 v[116:119], v[152:155], v[192:195], v[116:119]
	v_mfma_f32_16x16x32_bf16 v[108:111], v[160:163], v[192:195], v[108:111]
	v_mfma_f32_16x16x32_bf16 v[100:103], v[152:155], v[200:203], v[100:103]
	v_mfma_f32_16x16x32_bf16 v[92:95], v[160:163], v[200:203], v[92:95]
	v_mfma_f32_16x16x32_bf16 v[84:87], v[152:155], v[212:215], v[84:87]
	v_mfma_f32_16x16x32_bf16 v[76:79], v[160:163], v[212:215], v[76:79]
	v_mfma_f32_16x16x32_bf16 v[124:127], v[156:159], v[188:191], v[124:127]
	v_mfma_f32_16x16x32_bf16 v[120:123], v[164:167], v[188:191], v[120:123]
	v_mfma_f32_16x16x32_bf16 v[116:119], v[156:159], v[196:199], v[116:119]
	v_mfma_f32_16x16x32_bf16 v[108:111], v[164:167], v[196:199], v[108:111]
	v_mfma_f32_16x16x32_bf16 v[100:103], v[156:159], v[204:207], v[100:103]
	v_mfma_f32_16x16x32_bf16 v[92:95], v[164:167], v[204:207], v[92:95]
	v_mfma_f32_16x16x32_bf16 v[84:87], v[156:159], v[216:219], v[84:87]
	v_mfma_f32_16x16x32_bf16 v[76:79], v[164:167], v[216:219], v[76:79]
	v_mfma_f32_16x16x32_bf16 v[112:115], v[168:171], v[184:187], v[112:115]
	v_mfma_f32_16x16x32_bf16 v[104:107], v[176:179], v[184:187], v[104:107]
	v_mfma_f32_16x16x32_bf16 v[96:99], v[168:171], v[192:195], v[96:99]
	v_mfma_f32_16x16x32_bf16 v[88:91], v[176:179], v[192:195], v[88:91]
	v_mfma_f32_16x16x32_bf16 v[80:83], v[168:171], v[200:203], v[80:83]
	v_mfma_f32_16x16x32_bf16 v[72:75], v[176:179], v[200:203], v[72:75]
	v_mfma_f32_16x16x32_bf16 v[68:71], v[168:171], v[212:215], v[68:71]
	v_mfma_f32_16x16x32_bf16 v[64:67], v[176:179], v[212:215], v[64:67]
	v_mfma_f32_16x16x32_bf16 v[112:115], v[172:175], v[188:191], v[112:115]
	v_mfma_f32_16x16x32_bf16 v[104:107], v[180:183], v[188:191], v[104:107]
	v_mfma_f32_16x16x32_bf16 v[96:99], v[172:175], v[196:199], v[96:99]
	v_mfma_f32_16x16x32_bf16 v[88:91], v[180:183], v[196:199], v[88:91]
	v_mfma_f32_16x16x32_bf16 v[80:83], v[172:175], v[204:207], v[80:83]
	v_mfma_f32_16x16x32_bf16 v[72:75], v[180:183], v[204:207], v[72:75]
	v_mfma_f32_16x16x32_bf16 v[68:71], v[172:175], v[216:219], v[68:71]
	v_mfma_f32_16x16x32_bf16 v[64:67], v[180:183], v[216:219], v[64:67]
	s_barrier
; #define PG8_STAGE(bufoff, gbase, voff) do { _Pragma("unroll") for (int _i = 0; _i < 2; ++_i) \
;         __builtin_amdgcn_global_load_lds((const unsigned*)((const char*)(gbase) + (voff)[_i]), (PG8_LAS unsigned*)(lds + (bufoff) + ldsw + _i * 8192), 16, 0, 0); } while (0)
; #define PG8_LDA(dst, b, h) do { _Pragma("unroll") for (int m = 0; m < 4; ++m) _Pragma("unroll") for (int k = 0; k < 2; ++k) dst[m][k] = *(const PG8_LAS bf16x8*)(lds + PG8_SA(b, h) + aoff + m * 2048 + k * 1024); } while (0)
; #define PG8_LDB(dst, b, h) do { _Pragma("unroll") for (int n = 0; n < 2; ++n) _Pragma("unroll") for (int k = 0; k < 2; ++k) dst[n][k] = *(const PG8_LAS bf16x8*)(lds + PG8_SB(b, h) + boff + n * 2048 + k * 1024); } while (0)
; #define PG8_MMA(ai, bj, At, Bt) do { __builtin_amdgcn_s_setprio(1); _Pragma("unroll") for (int m = 0; m < 4; ++m) _Pragma("unroll") for (int n = 0; n < 2; ++n) _Pragma("unroll") for (int k = 0; k < 2; ++k) \
;         acc[ai][bj][m][n] = __builtin_amdgcn_mfma_f32_16x16x32_bf16(Bt[n][k], At[m][k], acc[ai][bj][m][n], 0, 0, 0); __builtin_amdgcn_s_setprio(0); } while (0)
; #define PG8_WAIT_V(n) asm volatile("s_waitcnt vmcnt(" #n ")" ::: "memory")
; #define PG8_WAIT_L(n) asm volatile("s_waitcnt lgkmcnt(" #n ")" ::: "memory")
; #define PG8_BAR __builtin_amdgcn_s_barrier()
; #define PG8_SCHED __builtin_amdgcn_sched_barrier(0)
; template <class Epi, class Sched, bool ALIGN_EPI = false, bool SP2 = false>
; __device__ __forceinline__ void gemm_phase(PG8_LAS unsigned char* lds, const Gemm g, const Sched& S, const Epi& E, const int wid) {
;     ...
;             PG8_LDA(At, 0, 1); PG8_STAGE(PG8_SB(0, 0), b2, voffB); PG8_STAGE(PG8_SB(0, 1), b2 + hstep, voffB); PG8_STAGE(PG8_SA(0, 0), a2, voffA);
;             PG8_WAIT_V(8); PG8_WAIT_L(0); PG8_BAR; PG8_MMA(1, 0, At, B0); PG8_MMA(1, 1, At, B1); PG8_BAR; PG8_SCHED;
;             PG8_LDB(B0, 1, 0); PG8_LDB(B1, 1, 1); PG8_SCHED; PG8_LDA(At, 1, 0); PG8_STAGE(PG8_SA(0, 1), a2 + hstep, voffA);
;             PG8_WAIT_V(8); PG8_WAIT_L(0); PG8_BAR; PG8_MMA(0, 0, At, B0); PG8_MMA(0, 1, At, B1); PG8_BAR; PG8_SCHED;
	s_add_i32 s48, s39, s26
	v_lshl_add_u64 v[144:145], s[22:23], 0, v[132:133]
	s_mov_b32 m0, s48
	ds_read_b128 v[184:187], v151 offset:16384
	ds_read_b128 v[188:191], v151 offset:17408
	ds_read_b128 v[192:195], v151 offset:18432
	ds_read_b128 v[196:199], v151 offset:19456
	ds_read_b128 v[200:203], v151 offset:20480
	ds_read_b128 v[204:207], v151 offset:21504
	ds_read_b128 v[212:215], v151 offset:22528
	ds_read_b128 v[216:219], v151 offset:23552
	global_load_lds_dwordx4 v[144:145], off
	s_add_i32 m0, s48, 0x2000
	s_add_u32 s48, s22, 0x40000
	v_lshl_add_u64 v[220:221], s[22:23], 0, v[128:129]
	s_addc_u32 s49, s23, 0
	s_add_i32 s50, s40, s26
	global_load_lds_dwordx4 v[220:221], off
	v_lshl_add_u64 v[222:223], s[48:49], 0, v[132:133]
	s_mov_b32 m0, s50
	v_lshl_add_u64 v[224:225], s[24:25], 0, v[130:131]
	global_load_lds_dwordx4 v[222:223], off
	v_lshl_add_u64 v[222:223], s[48:49], 0, v[128:129]
	s_add_i32 m0, s50, 0x2000
	s_nop 0
	global_load_lds_dwordx4 v[222:223], off
	v_lshl_add_u64 v[222:223], s[24:25], 0, v[134:135]
	s_mov_b32 m0, s17
	s_nop 0
	global_load_lds_dwordx4 v[222:223], off
	s_mov_b32 m0, s29
	s_nop 0
	global_load_lds_dwordx4 v[224:225], off
	s_nop 0
	s_waitcnt vmcnt(8)
	s_waitcnt lgkmcnt(0)
	s_barrier
	s_waitcnt lgkmcnt(0)
	v_mfma_f32_16x16x32_bf16 v[60:63], v[152:155], v[184:187], v[60:63]
	v_mfma_f32_16x16x32_bf16 v[56:59], v[160:163], v[184:187], v[56:59]
	v_mfma_f32_16x16x32_bf16 v[52:55], v[152:155], v[192:195], v[52:55]
	v_mfma_f32_16x16x32_bf16 v[44:47], v[160:163], v[192:195], v[44:47]
	v_mfma_f32_16x16x32_bf16 v[36:39], v[152:155], v[200:203], v[36:39]
	v_mfma_f32_16x16x32_bf16 v[28:31], v[160:163], v[200:203], v[28:31]
	v_mfma_f32_16x16x32_bf16 v[20:23], v[152:155], v[212:215], v[20:23]
	v_mfma_f32_16x16x32_bf16 v[12:15], v[160:163], v[212:215], v[12:15]
	v_mfma_f32_16x16x32_bf16 v[60:63], v[156:159], v[188:191], v[60:63]
	v_mfma_f32_16x16x32_bf16 v[56:59], v[164:167], v[188:191], v[56:59]
	v_mfma_f32_16x16x32_bf16 v[52:55], v[156:159], v[196:199], v[52:55]
	v_mfma_f32_16x16x32_bf16 v[44:47], v[164:167], v[196:199], v[44:47]
	v_mfma_f32_16x16x32_bf16 v[36:39], v[156:159], v[204:207], v[36:39]
	v_mfma_f32_16x16x32_bf16 v[28:31], v[164:167], v[204:207], v[28:31]
	v_mfma_f32_16x16x32_bf16 v[20:23], v[156:159], v[216:219], v[20:23]
	v_mfma_f32_16x16x32_bf16 v[12:15], v[164:167], v[216:219], v[12:15]
	v_mfma_f32_16x16x32_bf16 v[48:51], v[168:171], v[184:187], v[48:51]
	v_mfma_f32_16x16x32_bf16 v[40:43], v[176:179], v[184:187], v[40:43]
	v_mfma_f32_16x16x32_bf16 v[32:35], v[168:171], v[192:195], v[32:35]
	v_mfma_f32_16x16x32_bf16 v[24:27], v[176:179], v[192:195], v[24:27]
	v_mfma_f32_16x16x32_bf16 v[16:19], v[168:171], v[200:203], v[16:19]
	v_mfma_f32_16x16x32_bf16 v[8:11], v[176:179], v[200:203], v[8:11]
	v_mfma_f32_16x16x32_bf16 v[4:7], v[168:171], v[212:215], v[4:7]
	v_mfma_f32_16x16x32_bf16 v[0:3], v[176:179], v[212:215], v[0:3]
	v_mfma_f32_16x16x32_bf16 v[48:51], v[172:175], v[188:191], v[48:51]
	v_mfma_f32_16x16x32_bf16 v[40:43], v[180:183], v[188:191], v[40:43]
	v_mfma_f32_16x16x32_bf16 v[32:35], v[172:175], v[196:199], v[32:35]
	v_mfma_f32_16x16x32_bf16 v[24:27], v[180:183], v[196:199], v[24:27]
	v_mfma_f32_16x16x32_bf16 v[16:19], v[172:175], v[204:207], v[16:19]
	v_mfma_f32_16x16x32_bf16 v[8:11], v[180:183], v[204:207], v[8:11]
	v_mfma_f32_16x16x32_bf16 v[4:7], v[172:175], v[216:219], v[4:7]
	v_mfma_f32_16x16x32_bf16 v[0:3], v[180:183], v[216:219], v[0:3]
	s_barrier
	s_add_i32 s48, 0, 0x18000
	s_add_i32 s49, 0, 0x1c000
	v_add_u32_e32 v164, s48, v147
	v_add_u32_e32 v180, s49, v147
	ds_read_b128 v[152:155], v164
	ds_read_b128 v[156:159], v164 offset:1024
	ds_read_b128 v[160:163], v164 offset:2048
	ds_read_b128 v[164:167], v164 offset:3072
	ds_read_b128 v[168:171], v180
	ds_read_b128 v[172:175], v180 offset:1024
	ds_read_b128 v[176:179], v180 offset:2048
	ds_read_b128 v[180:183], v180 offset:3072
	s_add_u32 s24, s24, 0x40000
	s_addc_u32 s25, s25, 0
	s_mov_b32 m0, s30
	v_lshl_add_u64 v[226:227], s[24:25], 0, v[134:135]
	ds_read_b128 v[184:187], v151 offset:32768
	ds_read_b128 v[188:191], v151 offset:33792
	ds_read_b128 v[192:195], v151 offset:34816
	ds_read_b128 v[196:199], v151 offset:35840
	ds_read_b128 v[200:203], v151 offset:36864
	ds_read_b128 v[204:207], v151 offset:37888
	ds_read_b128 v[212:215], v151 offset:38912
	ds_read_b128 v[216:219], v151 offset:39936
	global_load_lds_dwordx4 v[226:227], off
	v_lshl_add_u64 v[226:227], s[24:25], 0, v[130:131]
	s_mov_b32 m0, s31
	s_nop 0
	global_load_lds_dwordx4 v[226:227], off
	s_nop 0
	s_waitcnt vmcnt(8)
	s_waitcnt lgkmcnt(0)
	s_barrier
; #define PG8_STAGE(bufoff, gbase, voff) do { _Pragma("unroll") for (int _i = 0; _i < 2; ++_i) \
;         __builtin_amdgcn_global_load_lds((const unsigned*)((const char*)(gbase) + (voff)[_i]), (PG8_LAS unsigned*)(lds + (bufoff) + ldsw + _i * 8192), 16, 0, 0); } while (0)
; #define PG8_LDA(dst, b, h) do { _Pragma("unroll") for (int m = 0; m < 4; ++m) _Pragma("unroll") for (int k = 0; k < 2; ++k) dst[m][k] = *(const PG8_LAS bf16x8*)(lds + PG8_SA(b, h) + aoff + m * 2048 + k * 1024); } while (0)
; #define PG8_LDB(dst, b, h) do { _Pragma("unroll") for (int n = 0; n < 2; ++n) _Pragma("unroll") for (int k = 0; k < 2; ++k) dst[n][k] = *(const PG8_LAS bf16x8*)(lds + PG8_SB(b, h) + boff + n * 2048 + k * 1024); } while (0)
; #define PG8_MMA(ai, bj, At, Bt) do { __builtin_amdgcn_s_setprio(1); _Pragma("unroll") for (int m = 0; m < 4; ++m) _Pragma("unroll") for (int n = 0; n < 2; ++n) _Pragma("unroll") for (int k = 0; k < 2; ++k) \
;         acc[ai][bj][m][n] = __builtin_amdgcn_mfma_f32_16x16x32_bf16(Bt[n][k], At[m][k], acc[ai][bj][m][n], 0, 0, 0); __builtin_amdgcn_s_setprio(0); } while (0)
; #define PG8_WAIT_V(n) asm volatile("s_waitcnt vmcnt(" #n ")" ::: "memory")
; #define PG8_WAIT_L(n) asm volatile("s_waitcnt lgkmcnt(" #n ")" ::: "memory")
; #define PG8_BAR __builtin_amdgcn_s_barrier()
; #define PG8_SCHED __builtin_amdgcn_sched_barrier(0)
; template <class Epi, class Sched, bool ALIGN_EPI = false, bool SP2 = false>
; __device__ __forceinline__ void gemm_phase(PG8_LAS unsigned char* lds, const Gemm g, const Sched& S, const Epi& E, const int wid) {
;     ...
;             PG8_LDB(B0, 1, 0); PG8_LDB(B1, 1, 1); PG8_SCHED; PG8_LDA(At, 1, 0); PG8_STAGE(PG8_SA(0, 1), a2 + hstep, voffA);
;             PG8_WAIT_V(8); PG8_WAIT_L(0); PG8_BAR; PG8_MMA(0, 0, At, B0); PG8_MMA(0, 1, At, B1); PG8_BAR; PG8_SCHED;
;             PG8_LDA(At, 1, 1); PG8_STAGE(PG8_SB(1, 0), b3, voffB); PG8_STAGE(PG8_SB(1, 1), b3 + hstep, voffB); PG8_STAGE(PG8_SA(1, 0), a3, voffA);
;             PG8_WAIT_V(8); PG8_WAIT_L(0); PG8_BAR; PG8_MMA(1, 0, At, B0); PG8_MMA(1, 1, At, B1); PG8_BAR; PG8_SCHED;
	s_waitcnt lgkmcnt(0)
	v_mfma_f32_16x16x32_bf16 v[124:127], v[152:155], v[184:187], v[124:127]
	v_mfma_f32_16x16x32_bf16 v[120:123], v[160:163], v[184:187], v[120:123]
	v_mfma_f32_16x16x32_bf16 v[116:119], v[152:155], v[192:195], v[116:119]
	v_mfma_f32_16x16x32_bf16 v[108:111], v[160:163], v[192:195], v[108:111]
	v_mfma_f32_16x16x32_bf16 v[100:103], v[152:155], v[200:203], v[100:103]
	v_mfma_f32_16x16x32_bf16 v[92:95], v[160:163], v[200:203], v[92:95]
	v_mfma_f32_16x16x32_bf16 v[84:87], v[152:155], v[212:215], v[84:87]
	v_mfma_f32_16x16x32_bf16 v[76:79], v[160:163], v[212:215], v[76:79]
	v_mfma_f32_16x16x32_bf16 v[124:127], v[156:159], v[188:191], v[124:127]
	v_mfma_f32_16x16x32_bf16 v[120:123], v[164:167], v[188:191], v[120:123]
	v_mfma_f32_16x16x32_bf16 v[116:119], v[156:159], v[196:199], v[116:119]
	v_mfma_f32_16x16x32_bf16 v[108:111], v[164:167], v[196:199], v[108:111]
	v_mfma_f32_16x16x32_bf16 v[100:103], v[156:159], v[204:207], v[100:103]
	v_mfma_f32_16x16x32_bf16 v[92:95], v[164:167], v[204:207], v[92:95]
	v_mfma_f32_16x16x32_bf16 v[84:87], v[156:159], v[216:219], v[84:87]
	v_mfma_f32_16x16x32_bf16 v[76:79], v[164:167], v[216:219], v[76:79]
	v_mfma_f32_16x16x32_bf16 v[112:115], v[168:171], v[184:187], v[112:115]
	v_mfma_f32_16x16x32_bf16 v[104:107], v[176:179], v[184:187], v[104:107]
	v_mfma_f32_16x16x32_bf16 v[96:99], v[168:171], v[192:195], v[96:99]
	v_mfma_f32_16x16x32_bf16 v[88:91], v[176:179], v[192:195], v[88:91]
	v_mfma_f32_16x16x32_bf16 v[80:83], v[168:171], v[200:203], v[80:83]
	v_mfma_f32_16x16x32_bf16 v[72:75], v[176:179], v[200:203], v[72:75]
	v_mfma_f32_16x16x32_bf16 v[68:71], v[168:171], v[212:215], v[68:71]
	v_mfma_f32_16x16x32_bf16 v[64:67], v[176:179], v[212:215], v[64:67]
	v_mfma_f32_16x16x32_bf16 v[112:115], v[172:175], v[188:191], v[112:115]
	v_mfma_f32_16x16x32_bf16 v[104:107], v[180:183], v[188:191], v[104:107]
	v_mfma_f32_16x16x32_bf16 v[96:99], v[172:175], v[196:199], v[96:99]
	v_mfma_f32_16x16x32_bf16 v[88:91], v[180:183], v[196:199], v[88:91]
	v_mfma_f32_16x16x32_bf16 v[80:83], v[172:175], v[204:207], v[80:83]
	v_mfma_f32_16x16x32_bf16 v[72:75], v[180:183], v[204:207], v[72:75]
	v_mfma_f32_16x16x32_bf16 v[68:71], v[172:175], v[216:219], v[68:71]
	v_mfma_f32_16x16x32_bf16 v[64:67], v[180:183], v[216:219], v[64:67]
	s_barrier
	s_add_i32 s24, s48, s26
	v_lshl_add_u64 v[144:145], v[144:145], 0, s[6:7]
	s_mov_b32 m0, s24
	ds_read_b128 v[184:187], v151 offset:49152
	ds_read_b128 v[188:191], v151 offset:50176
	ds_read_b128 v[192:195], v151 offset:51200
	ds_read_b128 v[196:199], v151 offset:52224
	ds_read_b128 v[200:203], v151 offset:53248
	ds_read_b128 v[204:207], v151 offset:54272
	ds_read_b128 v[212:215], v151 offset:55296
	ds_read_b128 v[216:219], v151 offset:56320
	global_load_lds_dwordx4 v[144:145], off
	s_add_i32 m0, s24, 0x2000
	s_add_u32 s22, s22, 0x40080
	v_lshl_add_u64 v[144:145], v[220:221], 0, s[6:7]
	s_addc_u32 s23, s23, 0
	s_add_i32 s24, s49, s26
	global_load_lds_dwordx4 v[144:145], off
	v_lshl_add_u64 v[144:145], s[22:23], 0, v[132:133]
	s_mov_b32 m0, s24
	s_nop 0
	global_load_lds_dwordx4 v[144:145], off
	v_lshl_add_u64 v[144:145], s[22:23], 0, v[128:129]
	s_add_i32 m0, s24, 0x2000
	s_nop 0
	global_load_lds_dwordx4 v[144:145], off
	v_lshl_add_u64 v[144:145], v[222:223], 0, s[6:7]
	s_mov_b32 m0, s37
	s_nop 0
	global_load_lds_dwordx4 v[144:145], off
	v_lshl_add_u64 v[144:145], v[224:225], 0, s[6:7]
	s_mov_b32 m0, s38
	s_nop 0
	global_load_lds_dwordx4 v[144:145], off
	s_waitcnt vmcnt(8)
	s_waitcnt lgkmcnt(0)
	s_barrier
	s_waitcnt lgkmcnt(0)
	v_mfma_f32_16x16x32_bf16 v[60:63], v[152:155], v[184:187], v[60:63]
	v_mfma_f32_16x16x32_bf16 v[56:59], v[160:163], v[184:187], v[56:59]
	v_mfma_f32_16x16x32_bf16 v[52:55], v[152:155], v[192:195], v[52:55]
	v_mfma_f32_16x16x32_bf16 v[44:47], v[160:163], v[192:195], v[44:47]
	v_mfma_f32_16x16x32_bf16 v[36:39], v[152:155], v[200:203], v[36:39]
	v_mfma_f32_16x16x32_bf16 v[28:31], v[160:163], v[200:203], v[28:31]
	v_mfma_f32_16x16x32_bf16 v[20:23], v[152:155], v[212:215], v[20:23]
	v_mfma_f32_16x16x32_bf16 v[12:15], v[160:163], v[212:215], v[12:15]
	v_mfma_f32_16x16x32_bf16 v[60:63], v[156:159], v[188:191], v[60:63]
	v_mfma_f32_16x16x32_bf16 v[56:59], v[164:167], v[188:191], v[56:59]
	v_mfma_f32_16x16x32_bf16 v[52:55], v[156:159], v[196:199], v[52:55]
	v_mfma_f32_16x16x32_bf16 v[44:47], v[164:167], v[196:199], v[44:47]
	v_mfma_f32_16x16x32_bf16 v[36:39], v[156:159], v[204:207], v[36:39]
	v_mfma_f32_16x16x32_bf16 v[28:31], v[164:167], v[204:207], v[28:31]
	v_mfma_f32_16x16x32_bf16 v[20:23], v[156:159], v[216:219], v[20:23]
	v_mfma_f32_16x16x32_bf16 v[12:15], v[164:167], v[216:219], v[12:15]
	v_mfma_f32_16x16x32_bf16 v[48:51], v[168:171], v[184:187], v[48:51]
	v_mfma_f32_16x16x32_bf16 v[40:43], v[176:179], v[184:187], v[40:43]
	v_mfma_f32_16x16x32_bf16 v[32:35], v[168:171], v[192:195], v[32:35]
	v_mfma_f32_16x16x32_bf16 v[24:27], v[176:179], v[192:195], v[24:27]
	v_mfma_f32_16x16x32_bf16 v[16:19], v[168:171], v[200:203], v[16:19]
	v_mfma_f32_16x16x32_bf16 v[8:11], v[176:179], v[200:203], v[8:11]
	v_mfma_f32_16x16x32_bf16 v[4:7], v[168:171], v[212:215], v[4:7]
	v_mfma_f32_16x16x32_bf16 v[0:3], v[176:179], v[212:215], v[0:3]
	v_mfma_f32_16x16x32_bf16 v[48:51], v[172:175], v[188:191], v[48:51]
	v_mfma_f32_16x16x32_bf16 v[40:43], v[180:183], v[188:191], v[40:43]
	v_mfma_f32_16x16x32_bf16 v[32:35], v[172:175], v[196:199], v[32:35]
	v_mfma_f32_16x16x32_bf16 v[24:27], v[180:183], v[196:199], v[24:27]
	v_mfma_f32_16x16x32_bf16 v[16:19], v[172:175], v[204:207], v[16:19]
	v_mfma_f32_16x16x32_bf16 v[8:11], v[180:183], v[204:207], v[8:11]
	v_mfma_f32_16x16x32_bf16 v[4:7], v[172:175], v[216:219], v[4:7]
	v_mfma_f32_16x16x32_bf16 v[0:3], v[180:183], v[216:219], v[0:3]
	s_barrier
	s_add_i32 s47, s47, 2
	s_add_u32 s20, s20, 0x100
	s_addc_u32 s21, s21, 0
	s_add_u32 s45, s45, 0x100
	s_addc_u32 s46, s46, 0
	s_cmp_gt_u32 s47, 13
	s_cbranch_scc0 .LBB0_882

; #define PG8_STAGE(bufoff, gbase, voff) do { _Pragma("unroll") for (int _i = 0; _i < 2; ++_i) \
;         __builtin_amdgcn_global_load_lds((const unsigned*)((const char*)(gbase) + (voff)[_i]), (PG8_LAS unsigned*)(lds + (bufoff) + ldsw + _i * 8192), 16, 0, 0); } while (0)
; #define PG8_LDA(dst, b, h) do { _Pragma("unroll") for (int m = 0; m < 4; ++m) _Pragma("unroll") for (int k = 0; k < 2; ++k) dst[m][k] = *(const PG8_LAS bf16x8*)(lds + PG8_SA(b, h) + aoff + m * 2048 + k * 1024); } while (0)
; #define PG8_LDB(dst, b, h) do { _Pragma("unroll") for (int n = 0; n < 2; ++n) _Pragma("unroll") for (int k = 0; k < 2; ++k) dst[n][k] = *(const PG8_LAS bf16x8*)(lds + PG8_SB(b, h) + boff + n * 2048 + k * 1024); } while (0)
; #define PG8_MMA(ai, bj, At, Bt) do { __builtin_amdgcn_s_setprio(1); _Pragma("unroll") for (int m = 0; m < 4; ++m) _Pragma("unroll") for (int n = 0; n < 2; ++n) _Pragma("unroll") for (int k = 0; k < 2; ++k) \
;         acc[ai][bj][m][n] = __builtin_amdgcn_mfma_f32_16x16x32_bf16(Bt[n][k], At[m][k], acc[ai][bj][m][n], 0, 0, 0); __builtin_amdgcn_s_setprio(0); } while (0)
; #define PG8_WAIT_V(n) asm volatile("s_waitcnt vmcnt(" #n ")" ::: "memory")
; #define PG8_WAIT_L(n) asm volatile("s_waitcnt lgkmcnt(" #n ")" ::: "memory")
; #define PG8_BAR __builtin_amdgcn_s_barrier()
; #define PG8_SCHED __builtin_amdgcn_sched_barrier(0)
; template <class Epi, class Sched, bool ALIGN_EPI = false, bool SP2 = false>
; __device__ __forceinline__ void gemm_phase(PG8_LAS unsigned char* lds, const Gemm g, const Sched& S, const Epi& E, const int wid) {
;     ...
;             PG8_LDB(B0, 0, 0); PG8_LDB(B1, 0, 1); PG8_SCHED; PG8_LDA(At, 0, 0); PG8_STAGE(PG8_SA(1, 1), a1 + hstep, voffA);
;             PG8_WAIT_V(8); PG8_WAIT_L(0); PG8_BAR; PG8_MMA(0, 0, At, B0); PG8_MMA(0, 1, At, B1); PG8_BAR; PG8_SCHED;
;             PG8_LDA(At, 0, 1); PG8_STAGE(PG8_SB(0, 0), b2, voffB); PG8_STAGE(PG8_SB(0, 1), b2 + hstep, voffB); PG8_STAGE(PG8_SA(0, 0), a2, voffA);
.LBB0_1786:
	v_add_u32_e32 v164, s41, v150
	v_add_u32_e32 v180, s42, v150
	s_add_u32 s22, s8, s20
	ds_read_b128 v[152:155], v164
	ds_read_b128 v[156:159], v164 offset:1024
	ds_read_b128 v[160:163], v164 offset:2048
	ds_read_b128 v[164:167], v164 offset:3072
	ds_read_b128 v[168:171], v180
	ds_read_b128 v[172:175], v180 offset:1024
	ds_read_b128 v[176:179], v180 offset:2048
	ds_read_b128 v[180:183], v180 offset:3072
	s_addc_u32 s23, s9, s21
	s_add_u32 s22, s22, 0x100
	s_addc_u32 s23, s23, 0
	s_add_u32 s49, s44, s20
	s_addc_u32 s50, s45, s21
	s_cmpk_eq_i32 s20, 0x700
	s_cselect_b32 s25, s15, s23
	s_cselect_b32 s24, s46, s22
	s_cselect_b32 s23, s13, s50
	s_cselect_b32 s22, s47, s49
	v_lshl_add_u64 v[206:207], v[144:145], 0, s[20:21]
	s_add_i32 m0, s33, 0xc000
	ds_read_b128 v[186:189], v151
	ds_read_b128 v[190:193], v151 offset:1024
	ds_read_b128 v[194:197], v151 offset:2048
	ds_read_b128 v[198:201], v151 offset:3072
	ds_read_b128 v[202:205], v151 offset:4096
	ds_read_b128 v[210:213], v151 offset:5120
	ds_read_b128 v[214:217], v151 offset:6144
	ds_read_b128 v[218:221], v151 offset:7168
	global_load_lds_dwordx4 v[206:207], off
	v_lshl_add_u64 v[206:207], v[146:147], 0, s[20:21]
	s_add_i32 m0, s33, 0xe000
	s_nop 0
	global_load_lds_dwordx4 v[206:207], off
	s_nop 0
	s_waitcnt vmcnt(8)
	s_waitcnt lgkmcnt(0)
	s_barrier
	s_waitcnt lgkmcnt(0)
	v_mfma_f32_16x16x32_bf16 v[124:127], v[152:155], v[186:189], v[124:127]
	v_mfma_f32_16x16x32_bf16 v[120:123], v[160:163], v[186:189], v[120:123]
	v_mfma_f32_16x16x32_bf16 v[112:115], v[152:155], v[194:197], v[112:115]
	v_mfma_f32_16x16x32_bf16 v[104:107], v[160:163], v[194:197], v[104:107]
	v_mfma_f32_16x16x32_bf16 v[96:99], v[152:155], v[202:205], v[96:99]
	v_mfma_f32_16x16x32_bf16 v[88:91], v[160:163], v[202:205], v[88:91]
	v_mfma_f32_16x16x32_bf16 v[80:83], v[152:155], v[214:217], v[80:83]
	v_mfma_f32_16x16x32_bf16 v[72:75], v[160:163], v[214:217], v[72:75]
	v_mfma_f32_16x16x32_bf16 v[124:127], v[156:159], v[190:193], v[124:127]
	v_mfma_f32_16x16x32_bf16 v[120:123], v[164:167], v[190:193], v[120:123]
	v_mfma_f32_16x16x32_bf16 v[112:115], v[156:159], v[198:201], v[112:115]
	v_mfma_f32_16x16x32_bf16 v[104:107], v[164:167], v[198:201], v[104:107]
	v_mfma_f32_16x16x32_bf16 v[96:99], v[156:159], v[210:213], v[96:99]
	v_mfma_f32_16x16x32_bf16 v[88:91], v[164:167], v[210:213], v[88:91]
	v_mfma_f32_16x16x32_bf16 v[80:83], v[156:159], v[218:221], v[80:83]
	v_mfma_f32_16x16x32_bf16 v[72:75], v[164:167], v[218:221], v[72:75]
	v_mfma_f32_16x16x32_bf16 v[116:119], v[168:171], v[186:189], v[116:119]
	v_mfma_f32_16x16x32_bf16 v[108:111], v[176:179], v[186:189], v[108:111]
	v_mfma_f32_16x16x32_bf16 v[100:103], v[168:171], v[194:197], v[100:103]
	v_mfma_f32_16x16x32_bf16 v[92:95], v[176:179], v[194:197], v[92:95]
	v_mfma_f32_16x16x32_bf16 v[84:87], v[168:171], v[202:205], v[84:87]
	v_mfma_f32_16x16x32_bf16 v[76:79], v[176:179], v[202:205], v[76:79]
	v_mfma_f32_16x16x32_bf16 v[68:71], v[168:171], v[214:217], v[68:71]
	v_mfma_f32_16x16x32_bf16 v[64:67], v[176:179], v[214:217], v[64:67]
	v_mfma_f32_16x16x32_bf16 v[116:119], v[172:175], v[190:193], v[116:119]
	v_mfma_f32_16x16x32_bf16 v[108:111], v[180:183], v[190:193], v[108:111]
	v_mfma_f32_16x16x32_bf16 v[100:103], v[172:175], v[198:201], v[100:103]
	v_mfma_f32_16x16x32_bf16 v[92:95], v[180:183], v[198:201], v[92:95]
	v_mfma_f32_16x16x32_bf16 v[84:87], v[172:175], v[210:213], v[84:87]
	v_mfma_f32_16x16x32_bf16 v[76:79], v[180:183], v[210:213], v[76:79]
	v_mfma_f32_16x16x32_bf16 v[68:71], v[172:175], v[218:221], v[68:71]
	v_mfma_f32_16x16x32_bf16 v[64:67], v[180:183], v[218:221], v[64:67]
	s_barrier
	s_add_i32 s49, s41, s31
	v_lshl_add_u64 v[206:207], s[22:23], 0, v[130:131]
	s_mov_b32 m0, s49
	ds_read_b128 v[186:189], v151 offset:16384
	ds_read_b128 v[190:193], v151 offset:17408
	ds_read_b128 v[194:197], v151 offset:18432
	ds_read_b128 v[198:201], v151 offset:19456
	ds_read_b128 v[202:205], v151 offset:20480
	ds_read_b128 v[210:213], v151 offset:21504
	ds_read_b128 v[214:217], v151 offset:22528
	ds_read_b128 v[218:221], v151 offset:23552
	global_load_lds_dwordx4 v[206:207], off
	s_add_i32 m0, s49, 0x2000
	s_add_u32 s50, s22, 0x40000
	v_lshl_add_u64 v[222:223], s[22:23], 0, v[134:135]
	s_addc_u32 s51, s23, 0
	s_add_i32 s49, s42, s31
	global_load_lds_dwordx4 v[222:223], off
	v_lshl_add_u64 v[224:225], s[50:51], 0, v[130:131]
	s_mov_b32 m0, s49
	v_lshl_add_u64 v[226:227], s[24:25], 0, v[132:133]
	global_load_lds_dwordx4 v[224:225], off
	v_lshl_add_u64 v[224:225], s[50:51], 0, v[134:135]
	s_add_i32 m0, s49, 0x2000
	s_nop 0
	global_load_lds_dwordx4 v[224:225], off
	v_lshl_add_u64 v[224:225], s[24:25], 0, v[128:129]
	s_mov_b32 m0, s33
	s_nop 0
	global_load_lds_dwordx4 v[224:225], off
	s_mov_b32 m0, s34
	s_nop 0
	global_load_lds_dwordx4 v[226:227], off
	s_nop 0
	s_waitcnt vmcnt(8)
	s_waitcnt lgkmcnt(0)
	s_barrier
; #define PG8_STAGE(bufoff, gbase, voff) do { _Pragma("unroll") for (int _i = 0; _i < 2; ++_i) \
;         __builtin_amdgcn_global_load_lds((const unsigned*)((const char*)(gbase) + (voff)[_i]), (PG8_LAS unsigned*)(lds + (bufoff) + ldsw + _i * 8192), 16, 0, 0); } while (0)
; #define PG8_LDA(dst, b, h) do { _Pragma("unroll") for (int m = 0; m < 4; ++m) _Pragma("unroll") for (int k = 0; k < 2; ++k) dst[m][k] = *(const PG8_LAS bf16x8*)(lds + PG8_SA(b, h) + aoff + m * 2048 + k * 1024); } while (0)
; #define PG8_LDB(dst, b, h) do { _Pragma("unroll") for (int n = 0; n < 2; ++n) _Pragma("unroll") for (int k = 0; k < 2; ++k) dst[n][k] = *(const PG8_LAS bf16x8*)(lds + PG8_SB(b, h) + boff + n * 2048 + k * 1024); } while (0)
; #define PG8_MMA(ai, bj, At, Bt) do { __builtin_amdgcn_s_setprio(1); _Pragma("unroll") for (int m = 0; m < 4; ++m) _Pragma("unroll") for (int n = 0; n < 2; ++n) _Pragma("unroll") for (int k = 0; k < 2; ++k) \
;         acc[ai][bj][m][n] = __builtin_amdgcn_mfma_f32_16x16x32_bf16(Bt[n][k], At[m][k], acc[ai][bj][m][n], 0, 0, 0); __builtin_amdgcn_s_setprio(0); } while (0)
; #define PG8_WAIT_V(n) asm volatile("s_waitcnt vmcnt(" #n ")" ::: "memory")
; #define PG8_WAIT_L(n) asm volatile("s_waitcnt lgkmcnt(" #n ")" ::: "memory")
; #define PG8_BAR __builtin_amdgcn_s_barrier()
; #define PG8_SCHED __builtin_amdgcn_sched_barrier(0)
; template <class Epi, class Sched, bool ALIGN_EPI = false, bool SP2 = false>
; __device__ __forceinline__ void gemm_phase(PG8_LAS unsigned char* lds, const Gemm g, const Sched& S, const Epi& E, const int wid) {
;     ...
;             PG8_WAIT_V(8); PG8_WAIT_L(0); PG8_BAR; PG8_MMA(1, 0, At, B0); PG8_MMA(1, 1, At, B1); PG8_BAR; PG8_SCHED;
;             PG8_LDB(B0, 1, 0); PG8_LDB(B1, 1, 1); PG8_SCHED; PG8_LDA(At, 1, 0); PG8_STAGE(PG8_SA(0, 1), a2 + hstep, voffA);
;             PG8_WAIT_V(8); PG8_WAIT_L(0); PG8_BAR; PG8_MMA(0, 0, At, B0); PG8_MMA(0, 1, At, B1); PG8_BAR; PG8_SCHED;
	s_waitcnt lgkmcnt(0)
	v_mfma_f32_16x16x32_bf16 v[60:63], v[152:155], v[186:189], v[60:63]
	v_mfma_f32_16x16x32_bf16 v[56:59], v[160:163], v[186:189], v[56:59]
	v_mfma_f32_16x16x32_bf16 v[44:47], v[152:155], v[194:197], v[44:47]
	v_mfma_f32_16x16x32_bf16 v[40:43], v[160:163], v[194:197], v[40:43]
	v_mfma_f32_16x16x32_bf16 v[28:31], v[152:155], v[202:205], v[28:31]
	v_mfma_f32_16x16x32_bf16 v[24:27], v[160:163], v[202:205], v[24:27]
	v_mfma_f32_16x16x32_bf16 v[12:15], v[152:155], v[214:217], v[12:15]
	v_mfma_f32_16x16x32_bf16 v[8:11], v[160:163], v[214:217], v[8:11]
	v_mfma_f32_16x16x32_bf16 v[60:63], v[156:159], v[190:193], v[60:63]
	v_mfma_f32_16x16x32_bf16 v[56:59], v[164:167], v[190:193], v[56:59]
	v_mfma_f32_16x16x32_bf16 v[44:47], v[156:159], v[198:201], v[44:47]
	v_mfma_f32_16x16x32_bf16 v[40:43], v[164:167], v[198:201], v[40:43]
	v_mfma_f32_16x16x32_bf16 v[28:31], v[156:159], v[210:213], v[28:31]
	v_mfma_f32_16x16x32_bf16 v[24:27], v[164:167], v[210:213], v[24:27]
	v_mfma_f32_16x16x32_bf16 v[12:15], v[156:159], v[218:221], v[12:15]
	v_mfma_f32_16x16x32_bf16 v[8:11], v[164:167], v[218:221], v[8:11]
	v_mfma_f32_16x16x32_bf16 v[52:55], v[168:171], v[186:189], v[52:55]
	v_mfma_f32_16x16x32_bf16 v[48:51], v[176:179], v[186:189], v[48:51]
	v_mfma_f32_16x16x32_bf16 v[36:39], v[168:171], v[194:197], v[36:39]
	v_mfma_f32_16x16x32_bf16 v[32:35], v[176:179], v[194:197], v[32:35]
	v_mfma_f32_16x16x32_bf16 v[20:23], v[168:171], v[202:205], v[20:23]
	v_mfma_f32_16x16x32_bf16 v[16:19], v[176:179], v[202:205], v[16:19]
	v_mfma_f32_16x16x32_bf16 v[4:7], v[168:171], v[214:217], v[4:7]
	v_mfma_f32_16x16x32_bf16 v[0:3], v[176:179], v[214:217], v[0:3]
	v_mfma_f32_16x16x32_bf16 v[52:55], v[172:175], v[190:193], v[52:55]
	v_mfma_f32_16x16x32_bf16 v[48:51], v[180:183], v[190:193], v[48:51]
	v_mfma_f32_16x16x32_bf16 v[36:39], v[172:175], v[198:201], v[36:39]
	v_mfma_f32_16x16x32_bf16 v[32:35], v[180:183], v[198:201], v[32:35]
	v_mfma_f32_16x16x32_bf16 v[20:23], v[172:175], v[210:213], v[20:23]
	v_mfma_f32_16x16x32_bf16 v[16:19], v[180:183], v[210:213], v[16:19]
	v_mfma_f32_16x16x32_bf16 v[4:7], v[172:175], v[218:221], v[4:7]
	v_mfma_f32_16x16x32_bf16 v[0:3], v[180:183], v[218:221], v[0:3]
	s_barrier
	s_add_i32 s49, 0, 0x18000
	s_add_i32 s50, 0, 0x1c000
	v_add_u32_e32 v164, s49, v150
	v_add_u32_e32 v180, s50, v150
	ds_read_b128 v[152:155], v164
	ds_read_b128 v[156:159], v164 offset:1024
	ds_read_b128 v[160:163], v164 offset:2048
	ds_read_b128 v[164:167], v164 offset:3072
	ds_read_b128 v[168:171], v180
	ds_read_b128 v[172:175], v180 offset:1024
	ds_read_b128 v[176:179], v180 offset:2048
	ds_read_b128 v[180:183], v180 offset:3072
	s_add_u32 s24, s24, 0x40000
	s_addc_u32 s25, s25, 0
	s_mov_b32 m0, s35
	v_lshl_add_u64 v[228:229], s[24:25], 0, v[128:129]
	ds_read_b128 v[186:189], v151 offset:32768
	ds_read_b128 v[190:193], v151 offset:33792
	ds_read_b128 v[194:197], v151 offset:34816
	ds_read_b128 v[198:201], v151 offset:35840
	ds_read_b128 v[202:205], v151 offset:36864
	ds_read_b128 v[210:213], v151 offset:37888
	ds_read_b128 v[214:217], v151 offset:38912
	ds_read_b128 v[218:221], v151 offset:39936
	global_load_lds_dwordx4 v[228:229], off
	v_lshl_add_u64 v[228:229], s[24:25], 0, v[132:133]
	s_mov_b32 m0, s36
	s_nop 0
	global_load_lds_dwordx4 v[228:229], off
	s_nop 0
	s_waitcnt vmcnt(8)
	s_waitcnt lgkmcnt(0)
	s_barrier
	s_waitcnt lgkmcnt(0)
	v_mfma_f32_16x16x32_bf16 v[124:127], v[152:155], v[186:189], v[124:127]
	v_mfma_f32_16x16x32_bf16 v[120:123], v[160:163], v[186:189], v[120:123]
	v_mfma_f32_16x16x32_bf16 v[112:115], v[152:155], v[194:197], v[112:115]
	v_mfma_f32_16x16x32_bf16 v[104:107], v[160:163], v[194:197], v[104:107]
	v_mfma_f32_16x16x32_bf16 v[96:99], v[152:155], v[202:205], v[96:99]
	v_mfma_f32_16x16x32_bf16 v[88:91], v[160:163], v[202:205], v[88:91]
	v_mfma_f32_16x16x32_bf16 v[80:83], v[152:155], v[214:217], v[80:83]
	v_mfma_f32_16x16x32_bf16 v[72:75], v[160:163], v[214:217], v[72:75]
	v_mfma_f32_16x16x32_bf16 v[124:127], v[156:159], v[190:193], v[124:127]
	v_mfma_f32_16x16x32_bf16 v[120:123], v[164:167], v[190:193], v[120:123]
	v_mfma_f32_16x16x32_bf16 v[112:115], v[156:159], v[198:201], v[112:115]
	v_mfma_f32_16x16x32_bf16 v[104:107], v[164:167], v[198:201], v[104:107]
	v_mfma_f32_16x16x32_bf16 v[96:99], v[156:159], v[210:213], v[96:99]
	v_mfma_f32_16x16x32_bf16 v[88:91], v[164:167], v[210:213], v[88:91]
	v_mfma_f32_16x16x32_bf16 v[80:83], v[156:159], v[218:221], v[80:83]
	v_mfma_f32_16x16x32_bf16 v[72:75], v[164:167], v[218:221], v[72:75]
	v_mfma_f32_16x16x32_bf16 v[116:119], v[168:171], v[186:189], v[116:119]
	v_mfma_f32_16x16x32_bf16 v[108:111], v[176:179], v[186:189], v[108:111]
	v_mfma_f32_16x16x32_bf16 v[100:103], v[168:171], v[194:197], v[100:103]
	v_mfma_f32_16x16x32_bf16 v[92:95], v[176:179], v[194:197], v[92:95]
	v_mfma_f32_16x16x32_bf16 v[84:87], v[168:171], v[202:205], v[84:87]
	v_mfma_f32_16x16x32_bf16 v[76:79], v[176:179], v[202:205], v[76:79]
	v_mfma_f32_16x16x32_bf16 v[68:71], v[168:171], v[214:217], v[68:71]
	v_mfma_f32_16x16x32_bf16 v[64:67], v[176:179], v[214:217], v[64:67]
	v_mfma_f32_16x16x32_bf16 v[116:119], v[172:175], v[190:193], v[116:119]
	v_mfma_f32_16x16x32_bf16 v[108:111], v[180:183], v[190:193], v[108:111]
	v_mfma_f32_16x16x32_bf16 v[100:103], v[172:175], v[198:201], v[100:103]
	v_mfma_f32_16x16x32_bf16 v[92:95], v[180:183], v[198:201], v[92:95]
	v_mfma_f32_16x16x32_bf16 v[84:87], v[172:175], v[210:213], v[84:87]
	v_mfma_f32_16x16x32_bf16 v[76:79], v[180:183], v[210:213], v[76:79]
	v_mfma_f32_16x16x32_bf16 v[68:71], v[172:175], v[218:221], v[68:71]
	v_mfma_f32_16x16x32_bf16 v[64:67], v[180:183], v[218:221], v[64:67]
	s_barrier
; #define PG8_STAGE(bufoff, gbase, voff) do { _Pragma("unroll") for (int _i = 0; _i < 2; ++_i) \
;         __builtin_amdgcn_global_load_lds((const unsigned*)((const char*)(gbase) + (voff)[_i]), (PG8_LAS unsigned*)(lds + (bufoff) + ldsw + _i * 8192), 16, 0, 0); } while (0)
; #define PG8_LDA(dst, b, h) do { _Pragma("unroll") for (int m = 0; m < 4; ++m) _Pragma("unroll") for (int k = 0; k < 2; ++k) dst[m][k] = *(const PG8_LAS bf16x8*)(lds + PG8_SA(b, h) + aoff + m * 2048 + k * 1024); } while (0)
; #define PG8_MMA(ai, bj, At, Bt) do { __builtin_amdgcn_s_setprio(1); _Pragma("unroll") for (int m = 0; m < 4; ++m) _Pragma("unroll") for (int n = 0; n < 2; ++n) _Pragma("unroll") for (int k = 0; k < 2; ++k) \
;         acc[ai][bj][m][n] = __builtin_amdgcn_mfma_f32_16x16x32_bf16(Bt[n][k], At[m][k], acc[ai][bj][m][n], 0, 0, 0); __builtin_amdgcn_s_setprio(0); } while (0)
; #define PG8_WAIT_V(n) asm volatile("s_waitcnt vmcnt(" #n ")" ::: "memory")
; #define PG8_WAIT_L(n) asm volatile("s_waitcnt lgkmcnt(" #n ")" ::: "memory")
; #define PG8_BAR __builtin_amdgcn_s_barrier()
; #define PG8_SCHED __builtin_amdgcn_sched_barrier(0)
; template <class Epi, class Sched, bool ALIGN_EPI = false, bool SP2 = false>
; __device__ __forceinline__ void gemm_phase(PG8_LAS unsigned char* lds, const Gemm g, const Sched& S, const Epi& E, const int wid) {
;     ...
;             PG8_LDA(At, 1, 1); PG8_STAGE(PG8_SB(1, 0), b3, voffB); PG8_STAGE(PG8_SB(1, 1), b3 + hstep, voffB); PG8_STAGE(PG8_SA(1, 0), a3, voffA);
;             PG8_WAIT_V(8); PG8_WAIT_L(0); PG8_BAR; PG8_MMA(1, 0, At, B0); PG8_MMA(1, 1, At, B1); PG8_BAR; PG8_SCHED;
;     ...
;         if (!has_next) break;
; #pragma unroll
;         for (int a = 0; a < 2; ++a)
; #pragma unroll
;             for (int b = 0; b < 2; ++b)
; #pragma unroll
;                 for (int m = 0; m < 4; ++m)
; #pragma unroll
;                     for (int n = 0; n < 2; ++n) acc[a][b][m][n] = (f32x4){0.f, 0.f, 0.f, 0.f};
;         cur = nxt; cA = nA; cB = nB; ++ui;
	s_add_i32 s24, s49, s31
	v_lshl_add_u64 v[206:207], v[206:207], 0, s[10:11]
	s_mov_b32 m0, s24
	ds_read_b128 v[186:189], v151 offset:49152
	ds_read_b128 v[190:193], v151 offset:50176
	ds_read_b128 v[194:197], v151 offset:51200
	ds_read_b128 v[198:201], v151 offset:52224
	ds_read_b128 v[202:205], v151 offset:53248
	ds_read_b128 v[210:213], v151 offset:54272
	ds_read_b128 v[214:217], v151 offset:55296
	ds_read_b128 v[218:221], v151 offset:56320
	global_load_lds_dwordx4 v[206:207], off
	s_add_i32 m0, s24, 0x2000
	s_add_u32 s22, s22, 0x40080
	v_lshl_add_u64 v[206:207], v[222:223], 0, s[10:11]
	s_addc_u32 s23, s23, 0
	s_add_i32 s24, s50, s31
	global_load_lds_dwordx4 v[206:207], off
	v_lshl_add_u64 v[206:207], s[22:23], 0, v[130:131]
	s_mov_b32 m0, s24
	s_nop 0
	global_load_lds_dwordx4 v[206:207], off
	v_lshl_add_u64 v[206:207], s[22:23], 0, v[134:135]
	s_add_i32 m0, s24, 0x2000
	s_nop 0
	global_load_lds_dwordx4 v[206:207], off
	v_lshl_add_u64 v[206:207], v[224:225], 0, s[10:11]
	s_mov_b32 m0, s38
	s_nop 0
	global_load_lds_dwordx4 v[206:207], off
	v_lshl_add_u64 v[206:207], v[226:227], 0, s[10:11]
	s_mov_b32 m0, s39
	s_nop 0
	global_load_lds_dwordx4 v[206:207], off
	s_waitcnt vmcnt(8)
	s_waitcnt lgkmcnt(0)
	s_barrier
	s_waitcnt lgkmcnt(0)
	v_mfma_f32_16x16x32_bf16 v[60:63], v[152:155], v[186:189], v[60:63]
	v_mfma_f32_16x16x32_bf16 v[56:59], v[160:163], v[186:189], v[56:59]
	v_mfma_f32_16x16x32_bf16 v[44:47], v[152:155], v[194:197], v[44:47]
	v_mfma_f32_16x16x32_bf16 v[40:43], v[160:163], v[194:197], v[40:43]
	v_mfma_f32_16x16x32_bf16 v[28:31], v[152:155], v[202:205], v[28:31]
	v_mfma_f32_16x16x32_bf16 v[24:27], v[160:163], v[202:205], v[24:27]
	v_mfma_f32_16x16x32_bf16 v[12:15], v[152:155], v[214:217], v[12:15]
	v_mfma_f32_16x16x32_bf16 v[8:11], v[160:163], v[214:217], v[8:11]
	v_mfma_f32_16x16x32_bf16 v[60:63], v[156:159], v[190:193], v[60:63]
	v_mfma_f32_16x16x32_bf16 v[56:59], v[164:167], v[190:193], v[56:59]
	v_mfma_f32_16x16x32_bf16 v[44:47], v[156:159], v[198:201], v[44:47]
	v_mfma_f32_16x16x32_bf16 v[40:43], v[164:167], v[198:201], v[40:43]
	v_mfma_f32_16x16x32_bf16 v[28:31], v[156:159], v[210:213], v[28:31]
	v_mfma_f32_16x16x32_bf16 v[24:27], v[164:167], v[210:213], v[24:27]
	v_mfma_f32_16x16x32_bf16 v[12:15], v[156:159], v[218:221], v[12:15]
	v_mfma_f32_16x16x32_bf16 v[8:11], v[164:167], v[218:221], v[8:11]
	v_mfma_f32_16x16x32_bf16 v[52:55], v[168:171], v[186:189], v[52:55]
	v_mfma_f32_16x16x32_bf16 v[48:51], v[176:179], v[186:189], v[48:51]
	v_mfma_f32_16x16x32_bf16 v[36:39], v[168:171], v[194:197], v[36:39]
	v_mfma_f32_16x16x32_bf16 v[32:35], v[176:179], v[194:197], v[32:35]
	v_mfma_f32_16x16x32_bf16 v[20:23], v[168:171], v[202:205], v[20:23]
	v_mfma_f32_16x16x32_bf16 v[16:19], v[176:179], v[202:205], v[16:19]
	v_mfma_f32_16x16x32_bf16 v[4:7], v[168:171], v[214:217], v[4:7]
	v_mfma_f32_16x16x32_bf16 v[0:3], v[176:179], v[214:217], v[0:3]
	v_mfma_f32_16x16x32_bf16 v[52:55], v[172:175], v[190:193], v[52:55]
	v_mfma_f32_16x16x32_bf16 v[48:51], v[180:183], v[190:193], v[48:51]
	v_mfma_f32_16x16x32_bf16 v[36:39], v[172:175], v[198:201], v[36:39]
	v_mfma_f32_16x16x32_bf16 v[32:35], v[180:183], v[198:201], v[32:35]
	v_mfma_f32_16x16x32_bf16 v[20:23], v[172:175], v[210:213], v[20:23]
	v_mfma_f32_16x16x32_bf16 v[16:19], v[180:183], v[210:213], v[16:19]
	v_mfma_f32_16x16x32_bf16 v[4:7], v[172:175], v[218:221], v[4:7]
	v_mfma_f32_16x16x32_bf16 v[0:3], v[180:183], v[218:221], v[0:3]
	s_barrier
	s_add_i32 s48, s48, 2
	s_add_u32 s20, s20, 0x100
	s_addc_u32 s21, s21, 0
	s_cmp_gt_u32 s48, 13
	s_cbranch_scc0 .LBB0_1786
	s_add_u32 s20, s44, 0xffffff00
	s_addc_u32 s21, s45, -1
	s_andn2_b64 vcc, exec, s[6:7]
	s_cbranch_vccnz .LBB0_1777
	v_mov_b32_e32 v0, 0
	s_mov_b32 s2, s12
	s_mov_b32 s0, s14
	s_mov_b64 s[8:9], s[18:19]
	s_mov_b32 s40, s43
	v_mov_b32_e32 v1, v0
	v_mov_b32_e32 v2, v0
	v_mov_b32_e32 v3, v0
	v_mov_b32_e32 v4, v0
	v_mov_b32_e32 v5, v0
	v_mov_b32_e32 v6, v0
	v_mov_b32_e32 v7, v0
	v_mov_b32_e32 v16, v0
	v_mov_b32_e32 v17, v0
	v_mov_b32_e32 v18, v0
	v_mov_b32_e32 v19, v0
	v_mov_b32_e32 v20, v0
	v_mov_b32_e32 v21, v0
	v_mov_b32_e32 v22, v0
	v_mov_b32_e32 v23, v0
	v_mov_b32_e32 v32, v0
	v_mov_b32_e32 v33, v0
	v_mov_b32_e32 v34, v0
	v_mov_b32_e32 v35, v0
	v_mov_b32_e32 v36, v0
	v_mov_b32_e32 v37, v0
	v_mov_b32_e32 v38, v0
	v_mov_b32_e32 v39, v0
	v_mov_b32_e32 v48, v0
	v_mov_b32_e32 v49, v0
	v_mov_b32_e32 v50, v0
	v_mov_b32_e32 v51, v0
	v_mov_b32_e32 v52, v0
	v_mov_b32_e32 v53, v0
	v_mov_b32_e32 v54, v0
	v_mov_b32_e32 v55, v0
	v_mov_b32_e32 v8, v0
	v_mov_b32_e32 v9, v0
	v_mov_b32_e32 v10, v0
	v_mov_b32_e32 v11, v0
	v_mov_b32_e32 v12, v0
	v_mov_b32_e32 v13, v0
	v_mov_b32_e32 v14, v0
	v_mov_b32_e32 v15, v0
	v_mov_b32_e32 v24, v0
	v_mov_b32_e32 v25, v0
	v_mov_b32_e32 v26, v0
	v_mov_b32_e32 v27, v0
	v_mov_b32_e32 v28, v0
	v_mov_b32_e32 v29, v0
	v_mov_b32_e32 v30, v0
	v_mov_b32_e32 v31, v0
	v_mov_b32_e32 v40, v0
	v_mov_b32_e32 v41, v0
	v_mov_b32_e32 v42, v0
	v_mov_b32_e32 v43, v0
	v_mov_b32_e32 v44, v0
	v_mov_b32_e32 v45, v0
	v_mov_b32_e32 v46, v0
	v_mov_b32_e32 v47, v0
	v_mov_b32_e32 v56, v0
	v_mov_b32_e32 v57, v0
	v_mov_b32_e32 v58, v0
	v_mov_b32_e32 v59, v0
	v_mov_b32_e32 v60, v0
	v_mov_b32_e32 v61, v0
	v_mov_b32_e32 v62, v0
	v_mov_b32_e32 v63, v0
	v_mov_b32_e32 v64, v0
	v_mov_b32_e32 v65, v0
	v_mov_b32_e32 v66, v0
	v_mov_b32_e32 v67, v0
	v_mov_b32_e32 v68, v0
	v_mov_b32_e32 v69, v0
	v_mov_b32_e32 v70, v0
	v_mov_b32_e32 v71, v0
	v_mov_b32_e32 v76, v0
	v_mov_b32_e32 v77, v0
	v_mov_b32_e32 v78, v0
	v_mov_b32_e32 v79, v0
	v_mov_b32_e32 v84, v0
	v_mov_b32_e32 v85, v0
	v_mov_b32_e32 v86, v0
	v_mov_b32_e32 v87, v0
	v_mov_b32_e32 v92, v0
	v_mov_b32_e32 v93, v0
	v_mov_b32_e32 v94, v0
	v_mov_b32_e32 v95, v0
	v_mov_b32_e32 v100, v0
	v_mov_b32_e32 v101, v0
	v_mov_b32_e32 v102, v0
	v_mov_b32_e32 v103, v0
	v_mov_b32_e32 v108, v0
	v_mov_b32_e32 v109, v0
	v_mov_b32_e32 v110, v0
	v_mov_b32_e32 v111, v0
	v_mov_b32_e32 v116, v0
	v_mov_b32_e32 v117, v0
	v_mov_b32_e32 v118, v0
	v_mov_b32_e32 v119, v0
	v_mov_b32_e32 v72, v0
	v_mov_b32_e32 v73, v0
	v_mov_b32_e32 v74, v0
	v_mov_b32_e32 v75, v0
	v_mov_b32_e32 v80, v0
	v_mov_b32_e32 v81, v0
	v_mov_b32_e32 v82, v0
	v_mov_b32_e32 v83, v0
	v_mov_b32_e32 v88, v0
	v_mov_b32_e32 v89, v0
	v_mov_b32_e32 v90, v0
	v_mov_b32_e32 v91, v0
	v_mov_b32_e32 v96, v0
	v_mov_b32_e32 v97, v0
	v_mov_b32_e32 v98, v0
	v_mov_b32_e32 v99, v0
	v_mov_b32_e32 v104, v0
	v_mov_b32_e32 v105, v0
	v_mov_b32_e32 v106, v0
	v_mov_b32_e32 v107, v0
	v_mov_b32_e32 v112, v0
	v_mov_b32_e32 v113, v0
	v_mov_b32_e32 v114, v0
	v_mov_b32_e32 v115, v0
	v_mov_b32_e32 v120, v0
	v_mov_b32_e32 v121, v0
	v_mov_b32_e32 v122, v0
	v_mov_b32_e32 v123, v0
	v_mov_b32_e32 v124, v0
	v_mov_b32_e32 v125, v0
	v_mov_b32_e32 v126, v0
	v_mov_b32_e32 v127, v0
	s_andn2_b64 vcc, exec, s[4:5]
	s_cbranch_vccnz .LBB0_1778

; template <class Epi, class Sched, bool ALIGN_EPI = false, bool SP2 = false>
; __device__ __forceinline__ void gemm_phase(PG8_LAS unsigned char* lds, const Gemm g, const Sched& S, const Epi& E, const int wid) {
;     ...
;         const bool has_next = S.next(ui + 1, nxt);
;         const char* nA = has_next ? (const char*)g.A + (size_t)nxt.pm * tstep : cA; const char* nB = has_next ? (const char*)g.Bt + (size_t)nxt.pn * tstep : cB;
.LBB0_1911:
	s_ashr_i32 s15, s14, 31
	s_lshl_b64 s[16:17], s[14:15], 19
	s_add_u32 s16, s80, s16
	s_addc_u32 s17, s81, s17
	s_and_b64 s[18:19], s[4:5], exec
	s_cselect_b32 s15, s17, s23
	s_cselect_b32 s42, s16, s22
	s_ashr_i32 s13, s12, 31
	s_lshl_b64 s[18:19], s[12:13], 19
	s_add_u32 s18, s10, s18
	s_addc_u32 s19, s11, s19
	s_and_b64 s[26:27], s[4:5], exec
	s_cselect_b32 s13, s19, s25
	s_cselect_b32 s43, s18, s24
	s_add_u32 s22, s22, 0x40080
	s_addc_u32 s23, s23, 0
	s_add_u32 s44, s24, 0x100

; template <class Epi, class Sched, bool ALIGN_EPI = false, bool SP2 = false>
; __device__ __forceinline__ void gemm_phase(PG8_LAS unsigned char* lds, const Gemm g, const Sched& S, const Epi& E, const int wid) {
;     ...
;         const char* nA = has_next ? (const char*)g.A + (size_t)nxt.pm * tstep : cA; const char* nB = has_next ? (const char*)g.Bt + (size_t)nxt.pn * tstep : cB;
;         for (int t = 0; t < nt; t += 2) {
	s_addc_u32 s45, s25, 0
	s_mov_b32 s46, -2


; #define PG8_STAGE(bufoff, gbase, voff) do { _Pragma("unroll") for (int _i = 0; _i < 2; ++_i) \
;         __builtin_amdgcn_global_load_lds((const unsigned*)((const char*)(gbase) + (voff)[_i]), (PG8_LAS unsigned*)(lds + (bufoff) + ldsw + _i * 8192), 16, 0, 0); } while (0)
; #define PG8_LDA(dst, b, h) do { _Pragma("unroll") for (int m = 0; m < 4; ++m) _Pragma("unroll") for (int k = 0; k < 2; ++k) dst[m][k] = *(const PG8_LAS bf16x8*)(lds + PG8_SA(b, h) + aoff + m * 2048 + k * 1024); } while (0)
; #define PG8_LDB(dst, b, h) do { _Pragma("unroll") for (int n = 0; n < 2; ++n) _Pragma("unroll") for (int k = 0; k < 2; ++k) dst[n][k] = *(const PG8_LAS bf16x8*)(lds + PG8_SB(b, h) + boff + n * 2048 + k * 1024); } while (0)
; #define PG8_MMA(ai, bj, At, Bt) do { __builtin_amdgcn_s_setprio(1); _Pragma("unroll") for (int m = 0; m < 4; ++m) _Pragma("unroll") for (int n = 0; n < 2; ++n) _Pragma("unroll") for (int k = 0; k < 2; ++k) \
;         acc[ai][bj][m][n] = __builtin_amdgcn_mfma_f32_16x16x32_bf16(Bt[n][k], At[m][k], acc[ai][bj][m][n], 0, 0, 0); __builtin_amdgcn_s_setprio(0); } while (0)
; #define PG8_WAIT_V(n) asm volatile("s_waitcnt vmcnt(" #n ")" ::: "memory")
; #define PG8_WAIT_L(n) asm volatile("s_waitcnt lgkmcnt(" #n ")" ::: "memory")
; #define PG8_BAR __builtin_amdgcn_s_barrier()
; #define PG8_SCHED __builtin_amdgcn_sched_barrier(0)
; template <class Epi, class Sched, bool ALIGN_EPI = false, bool SP2 = false>
; __device__ __forceinline__ void gemm_phase(PG8_LAS unsigned char* lds, const Gemm g, const Sched& S, const Epi& E, const int wid) {
;     ...
;             PG8_LDB(B0, 0, 0); PG8_LDB(B1, 0, 1); PG8_SCHED; PG8_LDA(At, 0, 0); PG8_STAGE(PG8_SA(1, 1), a1 + hstep, voffA);
;             PG8_WAIT_V(8); PG8_WAIT_L(0); PG8_BAR; PG8_MMA(0, 0, At, B0); PG8_MMA(0, 1, At, B1); PG8_BAR; PG8_SCHED;
;             PG8_LDA(At, 0, 1); PG8_STAGE(PG8_SB(0, 0), b2, voffB); PG8_STAGE(PG8_SB(0, 1), b2 + hstep, voffB); PG8_STAGE(PG8_SA(0, 0), a2, voffA);
;             PG8_WAIT_V(8); PG8_WAIT_L(0); PG8_BAR; PG8_MMA(1, 0, At, B0); PG8_MMA(1, 1, At, B1); PG8_BAR; PG8_SCHED;
	ds_read_b128 v[144:147], v151
	ds_read_b128 v[154:157], v151 offset:1024
	ds_read_b128 v[158:161], v151 offset:2048
	ds_read_b128 v[162:165], v151 offset:3072
	ds_read_b128 v[166:169], v152
	ds_read_b128 v[170:173], v152 offset:1024
	ds_read_b128 v[174:177], v152 offset:2048
	ds_read_b128 v[178:181], v152 offset:3072
	s_add_u32 s24, s22, 0xfffc0080
	s_addc_u32 s25, s23, -1
	s_cmp_eq_u32 s46, 12
	s_cselect_b32 s27, s15, s25
	s_cselect_b32 s26, s42, s24
	s_cselect_b32 s25, s13, s45
	s_cselect_b32 s24, s43, s44
	v_lshl_add_u64 v[206:207], s[22:23], 0, v[136:137]
	s_add_i32 m0, s21, 0xc000
	ds_read_b128 v[182:185], v153
	ds_read_b128 v[186:189], v153 offset:1024
	ds_read_b128 v[190:193], v153 offset:2048
	ds_read_b128 v[194:197], v153 offset:3072
	ds_read_b128 v[198:201], v153 offset:4096
	ds_read_b128 v[202:205], v153 offset:5120
	ds_read_b128 v[210:213], v153 offset:6144
	ds_read_b128 v[214:217], v153 offset:7168
	global_load_lds_dwordx4 v[206:207], off
	v_lshl_add_u64 v[206:207], s[22:23], 0, v[138:139]
	s_add_i32 m0, s21, 0xe000
	s_nop 0
	global_load_lds_dwordx4 v[206:207], off
	s_nop 0
	s_waitcnt vmcnt(8)
	s_waitcnt lgkmcnt(0)
	s_barrier
	s_waitcnt lgkmcnt(0)
	v_mfma_f32_16x16x32_bf16 v[124:127], v[144:147], v[182:185], 0
	v_mfma_f32_16x16x32_bf16 v[116:119], v[158:161], v[182:185], 0
	v_mfma_f32_16x16x32_bf16 v[108:111], v[144:147], v[190:193], 0
	v_mfma_f32_16x16x32_bf16 v[100:103], v[158:161], v[190:193], 0
	v_mfma_f32_16x16x32_bf16 v[92:95], v[144:147], v[198:201], 0
	v_mfma_f32_16x16x32_bf16 v[84:87], v[158:161], v[198:201], 0
	v_mfma_f32_16x16x32_bf16 v[76:79], v[144:147], v[210:213], 0
	v_mfma_f32_16x16x32_bf16 v[68:71], v[158:161], v[210:213], 0
	v_mfma_f32_16x16x32_bf16 v[124:127], v[154:157], v[186:189], v[124:127]
	v_mfma_f32_16x16x32_bf16 v[116:119], v[162:165], v[186:189], v[116:119]
	v_mfma_f32_16x16x32_bf16 v[108:111], v[154:157], v[194:197], v[108:111]
	v_mfma_f32_16x16x32_bf16 v[100:103], v[162:165], v[194:197], v[100:103]
	v_mfma_f32_16x16x32_bf16 v[92:95], v[154:157], v[202:205], v[92:95]
	v_mfma_f32_16x16x32_bf16 v[84:87], v[162:165], v[202:205], v[84:87]
	v_mfma_f32_16x16x32_bf16 v[76:79], v[154:157], v[214:217], v[76:79]
	v_mfma_f32_16x16x32_bf16 v[68:71], v[162:165], v[214:217], v[68:71]
	v_mfma_f32_16x16x32_bf16 v[120:123], v[166:169], v[182:185], 0
	v_mfma_f32_16x16x32_bf16 v[112:115], v[174:177], v[182:185], 0
	v_mfma_f32_16x16x32_bf16 v[104:107], v[166:169], v[190:193], 0
	v_mfma_f32_16x16x32_bf16 v[96:99], v[174:177], v[190:193], 0
	v_mfma_f32_16x16x32_bf16 v[88:91], v[166:169], v[198:201], 0
	v_mfma_f32_16x16x32_bf16 v[80:83], v[174:177], v[198:201], 0
	v_mfma_f32_16x16x32_bf16 v[72:75], v[166:169], v[210:213], 0
	v_mfma_f32_16x16x32_bf16 v[64:67], v[174:177], v[210:213], 0
	v_mfma_f32_16x16x32_bf16 v[120:123], v[170:173], v[186:189], v[120:123]
	v_mfma_f32_16x16x32_bf16 v[112:115], v[178:181], v[186:189], v[112:115]
	v_mfma_f32_16x16x32_bf16 v[104:107], v[170:173], v[194:197], v[104:107]
	v_mfma_f32_16x16x32_bf16 v[96:99], v[178:181], v[194:197], v[96:99]
	v_mfma_f32_16x16x32_bf16 v[88:91], v[170:173], v[202:205], v[88:91]
	v_mfma_f32_16x16x32_bf16 v[80:83], v[178:181], v[202:205], v[80:83]
	v_mfma_f32_16x16x32_bf16 v[72:75], v[170:173], v[214:217], v[72:75]
	v_mfma_f32_16x16x32_bf16 v[64:67], v[178:181], v[214:217], v[64:67]
	s_barrier
	s_add_i32 s47, s38, s9
	v_lshl_add_u64 v[206:207], s[24:25], 0, v[132:133]
	s_mov_b32 m0, s47
	ds_read_b128 v[182:185], v153 offset:16384
	ds_read_b128 v[186:189], v153 offset:17408
	ds_read_b128 v[190:193], v153 offset:18432
	ds_read_b128 v[194:197], v153 offset:19456
	ds_read_b128 v[198:201], v153 offset:20480
	ds_read_b128 v[202:205], v153 offset:21504
	ds_read_b128 v[210:213], v153 offset:22528
	ds_read_b128 v[214:217], v153 offset:23552
	global_load_lds_dwordx4 v[206:207], off
	s_add_i32 m0, s47, 0x2000
	s_add_u32 s48, s24, 0x40000
	v_lshl_add_u64 v[218:219], s[24:25], 0, v[128:129]
	s_addc_u32 s49, s25, 0
	s_add_i32 s47, s39, s9
	global_load_lds_dwordx4 v[218:219], off
	v_lshl_add_u64 v[220:221], s[48:49], 0, v[132:133]
	s_mov_b32 m0, s47
	v_lshl_add_u64 v[222:223], s[26:27], 0, v[130:131]
	global_load_lds_dwordx4 v[220:221], off
	v_lshl_add_u64 v[220:221], s[48:49], 0, v[128:129]
	s_add_i32 m0, s47, 0x2000
	s_nop 0
	global_load_lds_dwordx4 v[220:221], off
	v_lshl_add_u64 v[220:221], s[26:27], 0, v[134:135]
	s_mov_b32 m0, s21
	s_nop 0
	global_load_lds_dwordx4 v[220:221], off
	s_mov_b32 m0, s30
	s_nop 0
	global_load_lds_dwordx4 v[222:223], off
	s_nop 0
	s_waitcnt vmcnt(8)
	s_waitcnt lgkmcnt(0)
	s_barrier
	s_waitcnt lgkmcnt(0)
	v_mfma_f32_16x16x32_bf16 v[60:63], v[144:147], v[182:185], 0
	v_mfma_f32_16x16x32_bf16 v[52:55], v[158:161], v[182:185], 0
	v_mfma_f32_16x16x32_bf16 v[44:47], v[144:147], v[190:193], 0
	v_mfma_f32_16x16x32_bf16 v[36:39], v[158:161], v[190:193], 0
	v_mfma_f32_16x16x32_bf16 v[28:31], v[144:147], v[198:201], 0
	v_mfma_f32_16x16x32_bf16 v[20:23], v[158:161], v[198:201], 0
	v_mfma_f32_16x16x32_bf16 v[12:15], v[144:147], v[210:213], 0
	v_mfma_f32_16x16x32_bf16 v[4:7], v[158:161], v[210:213], 0
	v_mfma_f32_16x16x32_bf16 v[60:63], v[154:157], v[186:189], v[60:63]
	v_mfma_f32_16x16x32_bf16 v[52:55], v[162:165], v[186:189], v[52:55]
	v_mfma_f32_16x16x32_bf16 v[44:47], v[154:157], v[194:197], v[44:47]
	v_mfma_f32_16x16x32_bf16 v[36:39], v[162:165], v[194:197], v[36:39]
	v_mfma_f32_16x16x32_bf16 v[28:31], v[154:157], v[202:205], v[28:31]
	v_mfma_f32_16x16x32_bf16 v[20:23], v[162:165], v[202:205], v[20:23]
	v_mfma_f32_16x16x32_bf16 v[12:15], v[154:157], v[214:217], v[12:15]
	v_mfma_f32_16x16x32_bf16 v[4:7], v[162:165], v[214:217], v[4:7]
	v_mfma_f32_16x16x32_bf16 v[56:59], v[166:169], v[182:185], 0
	v_mfma_f32_16x16x32_bf16 v[48:51], v[174:177], v[182:185], 0
	v_mfma_f32_16x16x32_bf16 v[40:43], v[166:169], v[190:193], 0
	v_mfma_f32_16x16x32_bf16 v[32:35], v[174:177], v[190:193], 0
	v_mfma_f32_16x16x32_bf16 v[24:27], v[166:169], v[198:201], 0
	v_mfma_f32_16x16x32_bf16 v[16:19], v[174:177], v[198:201], 0
	v_mfma_f32_16x16x32_bf16 v[8:11], v[166:169], v[210:213], 0
	v_mfma_f32_16x16x32_bf16 v[0:3], v[174:177], v[210:213], 0
	v_mfma_f32_16x16x32_bf16 v[56:59], v[170:173], v[186:189], v[56:59]
	v_mfma_f32_16x16x32_bf16 v[48:51], v[178:181], v[186:189], v[48:51]
	v_mfma_f32_16x16x32_bf16 v[40:43], v[170:173], v[194:197], v[40:43]
	v_mfma_f32_16x16x32_bf16 v[32:35], v[178:181], v[194:197], v[32:35]
	v_mfma_f32_16x16x32_bf16 v[24:27], v[170:173], v[202:205], v[24:27]
	v_mfma_f32_16x16x32_bf16 v[16:19], v[178:181], v[202:205], v[16:19]
	v_mfma_f32_16x16x32_bf16 v[8:11], v[170:173], v[214:217], v[8:11]
	v_mfma_f32_16x16x32_bf16 v[0:3], v[178:181], v[214:217], v[0:3]
	s_barrier
; #define PG8_STAGE(bufoff, gbase, voff) do { _Pragma("unroll") for (int _i = 0; _i < 2; ++_i) \
;         __builtin_amdgcn_global_load_lds((const unsigned*)((const char*)(gbase) + (voff)[_i]), (PG8_LAS unsigned*)(lds + (bufoff) + ldsw + _i * 8192), 16, 0, 0); } while (0)
; #define PG8_LDA(dst, b, h) do { _Pragma("unroll") for (int m = 0; m < 4; ++m) _Pragma("unroll") for (int k = 0; k < 2; ++k) dst[m][k] = *(const PG8_LAS bf16x8*)(lds + PG8_SA(b, h) + aoff + m * 2048 + k * 1024); } while (0)
; #define PG8_LDB(dst, b, h) do { _Pragma("unroll") for (int n = 0; n < 2; ++n) _Pragma("unroll") for (int k = 0; k < 2; ++k) dst[n][k] = *(const PG8_LAS bf16x8*)(lds + PG8_SB(b, h) + boff + n * 2048 + k * 1024); } while (0)
; #define PG8_MMA(ai, bj, At, Bt) do { __builtin_amdgcn_s_setprio(1); _Pragma("unroll") for (int m = 0; m < 4; ++m) _Pragma("unroll") for (int n = 0; n < 2; ++n) _Pragma("unroll") for (int k = 0; k < 2; ++k) \
;         acc[ai][bj][m][n] = __builtin_amdgcn_mfma_f32_16x16x32_bf16(Bt[n][k], At[m][k], acc[ai][bj][m][n], 0, 0, 0); __builtin_amdgcn_s_setprio(0); } while (0)
; #define PG8_WAIT_V(n) asm volatile("s_waitcnt vmcnt(" #n ")" ::: "memory")
; #define PG8_WAIT_L(n) asm volatile("s_waitcnt lgkmcnt(" #n ")" ::: "memory")
; #define PG8_BAR __builtin_amdgcn_s_barrier()
; #define PG8_SCHED __builtin_amdgcn_sched_barrier(0)
; template <class Epi, class Sched, bool ALIGN_EPI = false, bool SP2 = false>
; __device__ __forceinline__ void gemm_phase(PG8_LAS unsigned char* lds, const Gemm g, const Sched& S, const Epi& E, const int wid) {
;     ...
;             PG8_LDB(B0, 1, 0); PG8_LDB(B1, 1, 1); PG8_SCHED; PG8_LDA(At, 1, 0); PG8_STAGE(PG8_SA(0, 1), a2 + hstep, voffA);
;             PG8_WAIT_V(8); PG8_WAIT_L(0); PG8_BAR; PG8_MMA(0, 0, At, B0); PG8_MMA(0, 1, At, B1); PG8_BAR; PG8_SCHED;
;             PG8_LDA(At, 1, 1); PG8_STAGE(PG8_SB(1, 0), b3, voffB); PG8_STAGE(PG8_SB(1, 1), b3 + hstep, voffB); PG8_STAGE(PG8_SA(1, 0), a3, voffA);
	s_add_i32 s47, 0, 0x18000
	s_add_i32 s48, 0, 0x1c000
	v_add_u32_e32 v162, s47, v149
	v_add_u32_e32 v178, s48, v149
	ds_read_b128 v[144:147], v162
	ds_read_b128 v[154:157], v162 offset:1024
	ds_read_b128 v[158:161], v162 offset:2048
	ds_read_b128 v[162:165], v162 offset:3072
	ds_read_b128 v[166:169], v178
	ds_read_b128 v[170:173], v178 offset:1024
	ds_read_b128 v[174:177], v178 offset:2048
	ds_read_b128 v[178:181], v178 offset:3072
	s_add_u32 s26, s26, 0x40000
	s_addc_u32 s27, s27, 0
	s_mov_b32 m0, s31
	v_lshl_add_u64 v[224:225], s[26:27], 0, v[134:135]
	ds_read_b128 v[182:185], v153 offset:32768
	ds_read_b128 v[186:189], v153 offset:33792
	ds_read_b128 v[190:193], v153 offset:34816
	ds_read_b128 v[194:197], v153 offset:35840
	ds_read_b128 v[198:201], v153 offset:36864
	ds_read_b128 v[202:205], v153 offset:37888
	ds_read_b128 v[210:213], v153 offset:38912
	ds_read_b128 v[214:217], v153 offset:39936
	global_load_lds_dwordx4 v[224:225], off
	v_lshl_add_u64 v[224:225], s[26:27], 0, v[130:131]
	s_mov_b32 m0, s33
	s_nop 0
	global_load_lds_dwordx4 v[224:225], off
	s_nop 0
	s_waitcnt vmcnt(8)
	s_waitcnt lgkmcnt(0)
	s_barrier
	s_waitcnt lgkmcnt(0)
	v_mfma_f32_16x16x32_bf16 v[124:127], v[144:147], v[182:185], v[124:127]
	v_mfma_f32_16x16x32_bf16 v[116:119], v[158:161], v[182:185], v[116:119]
	v_mfma_f32_16x16x32_bf16 v[108:111], v[144:147], v[190:193], v[108:111]
	v_mfma_f32_16x16x32_bf16 v[100:103], v[158:161], v[190:193], v[100:103]
	v_mfma_f32_16x16x32_bf16 v[92:95], v[144:147], v[198:201], v[92:95]
	v_mfma_f32_16x16x32_bf16 v[84:87], v[158:161], v[198:201], v[84:87]
	v_mfma_f32_16x16x32_bf16 v[76:79], v[144:147], v[210:213], v[76:79]
	v_mfma_f32_16x16x32_bf16 v[68:71], v[158:161], v[210:213], v[68:71]
	v_mfma_f32_16x16x32_bf16 v[124:127], v[154:157], v[186:189], v[124:127]
	v_mfma_f32_16x16x32_bf16 v[116:119], v[162:165], v[186:189], v[116:119]
	v_mfma_f32_16x16x32_bf16 v[108:111], v[154:157], v[194:197], v[108:111]
	v_mfma_f32_16x16x32_bf16 v[100:103], v[162:165], v[194:197], v[100:103]
	v_mfma_f32_16x16x32_bf16 v[92:95], v[154:157], v[202:205], v[92:95]
	v_mfma_f32_16x16x32_bf16 v[84:87], v[162:165], v[202:205], v[84:87]
	v_mfma_f32_16x16x32_bf16 v[76:79], v[154:157], v[214:217], v[76:79]
	v_mfma_f32_16x16x32_bf16 v[68:71], v[162:165], v[214:217], v[68:71]
	v_mfma_f32_16x16x32_bf16 v[120:123], v[166:169], v[182:185], v[120:123]
	v_mfma_f32_16x16x32_bf16 v[112:115], v[174:177], v[182:185], v[112:115]
	v_mfma_f32_16x16x32_bf16 v[104:107], v[166:169], v[190:193], v[104:107]
	v_mfma_f32_16x16x32_bf16 v[96:99], v[174:177], v[190:193], v[96:99]
	v_mfma_f32_16x16x32_bf16 v[88:91], v[166:169], v[198:201], v[88:91]
	v_mfma_f32_16x16x32_bf16 v[80:83], v[174:177], v[198:201], v[80:83]
	v_mfma_f32_16x16x32_bf16 v[72:75], v[166:169], v[210:213], v[72:75]
	v_mfma_f32_16x16x32_bf16 v[64:67], v[174:177], v[210:213], v[64:67]
	v_mfma_f32_16x16x32_bf16 v[120:123], v[170:173], v[186:189], v[120:123]
	v_mfma_f32_16x16x32_bf16 v[112:115], v[178:181], v[186:189], v[112:115]
	v_mfma_f32_16x16x32_bf16 v[104:107], v[170:173], v[194:197], v[104:107]
	v_mfma_f32_16x16x32_bf16 v[96:99], v[178:181], v[194:197], v[96:99]
	v_mfma_f32_16x16x32_bf16 v[88:91], v[170:173], v[202:205], v[88:91]
	v_mfma_f32_16x16x32_bf16 v[80:83], v[178:181], v[202:205], v[80:83]
	v_mfma_f32_16x16x32_bf16 v[72:75], v[170:173], v[214:217], v[72:75]
	v_mfma_f32_16x16x32_bf16 v[64:67], v[178:181], v[214:217], v[64:67]
	s_barrier
	s_add_i32 s26, s47, s9
	v_lshl_add_u64 v[206:207], v[206:207], 0, s[2:3]
	s_mov_b32 m0, s26
	ds_read_b128 v[182:185], v153 offset:49152
	ds_read_b128 v[186:189], v153 offset:50176
	ds_read_b128 v[190:193], v153 offset:51200
	ds_read_b128 v[194:197], v153 offset:52224
	ds_read_b128 v[198:201], v153 offset:53248
	ds_read_b128 v[202:205], v153 offset:54272
	ds_read_b128 v[210:213], v153 offset:55296
	ds_read_b128 v[214:217], v153 offset:56320
	global_load_lds_dwordx4 v[206:207], off
	s_add_i32 m0, s26, 0x2000
	s_add_u32 s24, s24, 0x40080
	v_lshl_add_u64 v[206:207], v[218:219], 0, s[2:3]
	s_addc_u32 s25, s25, 0
	s_add_i32 s26, s48, s9
	global_load_lds_dwordx4 v[206:207], off
	v_lshl_add_u64 v[206:207], s[24:25], 0, v[132:133]
	s_mov_b32 m0, s26
	s_nop 0
	global_load_lds_dwordx4 v[206:207], off
	v_lshl_add_u64 v[206:207], s[24:25], 0, v[128:129]
	s_add_i32 m0, s26, 0x2000
	s_nop 0
	global_load_lds_dwordx4 v[206:207], off
	v_lshl_add_u64 v[206:207], v[220:221], 0, s[2:3]
	s_mov_b32 m0, s35
	s_nop 0
	global_load_lds_dwordx4 v[206:207], off
	v_lshl_add_u64 v[206:207], v[222:223], 0, s[2:3]
	s_mov_b32 m0, s36
	s_nop 0
	global_load_lds_dwordx4 v[206:207], off
	s_waitcnt vmcnt(8)
	s_waitcnt lgkmcnt(0)
	s_barrier
; #define PG8_STAGE(bufoff, gbase, voff) do { _Pragma("unroll") for (int _i = 0; _i < 2; ++_i) \
;         __builtin_amdgcn_global_load_lds((const unsigned*)((const char*)(gbase) + (voff)[_i]), (PG8_LAS unsigned*)(lds + (bufoff) + ldsw + _i * 8192), 16, 0, 0); } while (0)
; #define PG8_LDA(dst, b, h) do { _Pragma("unroll") for (int m = 0; m < 4; ++m) _Pragma("unroll") for (int k = 0; k < 2; ++k) dst[m][k] = *(const PG8_LAS bf16x8*)(lds + PG8_SA(b, h) + aoff + m * 2048 + k * 1024); } while (0)
; #define PG8_WAIT_V(n) asm volatile("s_waitcnt vmcnt(" #n ")" ::: "memory")
; #define PG8_WAIT_L(n) asm volatile("s_waitcnt lgkmcnt(" #n ")" ::: "memory")
; #define PG8_BAR __builtin_amdgcn_s_barrier()
; template <class Epi, class Sched, bool ALIGN_EPI = false, bool SP2 = false>
; __device__ __forceinline__ void gemm_phase(PG8_LAS unsigned char* lds, const Gemm g, const Sched& S, const Epi& E, const int wid) {
;     ...
;         for (int t = 0; t < nt; t += 2) {
;             const bool last = (t == nt - 2);
;             const char* a1 = cA + (size_t)(t + 1) * kstep;
;             const char* a2 = last ? nA : cA + (size_t)(t + 2) * kstep; const char* b2 = last ? nB : cB + (size_t)(t + 2) * kstep;
;             const char* a3 = a2 + kstep; const char* b3 = b2 + kstep;
;             if (last && has_next) S.a_ready(nxt);
;             if constexpr (SP2) {
;             PG8_LDB(B0, 0, 0); PG8_LDB(B1, 0, 1); PG8_SCHED; PG8_LDA(At, 0, 0); PG8_STAGE(PG8_SA(1, 1), a1 + hstep, voffA);
;             PG8_WAIT_V(8); PG8_WAIT_L(0); PG8_BAR; PG8_MMA(0, 0, At, B0); PG8_MMA(0, 1, At, B1); PG8_BAR; PG8_SCHED;
;             PG8_LDA(At, 0, 1); PG8_STAGE(PG8_SB(0, 0), b2, voffB); PG8_STAGE(PG8_SB(0, 1), b2 + hstep, voffB); PG8_STAGE(PG8_SA(0, 0), a2, voffA);
;             PG8_WAIT_V(8); PG8_WAIT_L(0); PG8_BAR; PG8_MMA(1, 0, At, B0); PG8_MMA(1, 1, At, B1); PG8_BAR; PG8_SCHED;
;             PG8_LDB(B0, 1, 0); PG8_LDB(B1, 1, 1); PG8_SCHED; PG8_LDA(At, 1, 0); PG8_STAGE(PG8_SA(0, 1), a2 + hstep, voffA);
;             PG8_WAIT_V(8); PG8_WAIT_L(0); PG8_BAR; PG8_MMA(0, 0, At, B0); PG8_MMA(0, 1, At, B1); PG8_BAR; PG8_SCHED;
;             PG8_LDA(At, 1, 1); PG8_STAGE(PG8_SB(1, 0), b3, voffB); PG8_STAGE(PG8_SB(1, 1), b3 + hstep, voffB); PG8_STAGE(PG8_SA(1, 0), a3, voffA);
;             PG8_WAIT_V(8); PG8_WAIT_L(0); PG8_BAR; PG8_MMA(1, 0, At, B0); PG8_MMA(1, 1, At, B1); PG8_BAR; PG8_SCHED;
	s_waitcnt lgkmcnt(0)
	v_mfma_f32_16x16x32_bf16 v[60:63], v[144:147], v[182:185], v[60:63]
	v_mfma_f32_16x16x32_bf16 v[52:55], v[158:161], v[182:185], v[52:55]
	v_mfma_f32_16x16x32_bf16 v[44:47], v[144:147], v[190:193], v[44:47]
	v_mfma_f32_16x16x32_bf16 v[36:39], v[158:161], v[190:193], v[36:39]
	v_mfma_f32_16x16x32_bf16 v[28:31], v[144:147], v[198:201], v[28:31]
	v_mfma_f32_16x16x32_bf16 v[20:23], v[158:161], v[198:201], v[20:23]
	v_mfma_f32_16x16x32_bf16 v[12:15], v[144:147], v[210:213], v[12:15]
	v_mfma_f32_16x16x32_bf16 v[4:7], v[158:161], v[210:213], v[4:7]
	v_mfma_f32_16x16x32_bf16 v[60:63], v[154:157], v[186:189], v[60:63]
	v_mfma_f32_16x16x32_bf16 v[52:55], v[162:165], v[186:189], v[52:55]
	v_mfma_f32_16x16x32_bf16 v[44:47], v[154:157], v[194:197], v[44:47]
	v_mfma_f32_16x16x32_bf16 v[36:39], v[162:165], v[194:197], v[36:39]
	v_mfma_f32_16x16x32_bf16 v[28:31], v[154:157], v[202:205], v[28:31]
	v_mfma_f32_16x16x32_bf16 v[20:23], v[162:165], v[202:205], v[20:23]
	v_mfma_f32_16x16x32_bf16 v[12:15], v[154:157], v[214:217], v[12:15]
	v_mfma_f32_16x16x32_bf16 v[4:7], v[162:165], v[214:217], v[4:7]
	v_mfma_f32_16x16x32_bf16 v[56:59], v[166:169], v[182:185], v[56:59]
	v_mfma_f32_16x16x32_bf16 v[48:51], v[174:177], v[182:185], v[48:51]
	v_mfma_f32_16x16x32_bf16 v[40:43], v[166:169], v[190:193], v[40:43]
	v_mfma_f32_16x16x32_bf16 v[32:35], v[174:177], v[190:193], v[32:35]
	v_mfma_f32_16x16x32_bf16 v[24:27], v[166:169], v[198:201], v[24:27]
	v_mfma_f32_16x16x32_bf16 v[16:19], v[174:177], v[198:201], v[16:19]
	v_mfma_f32_16x16x32_bf16 v[8:11], v[166:169], v[210:213], v[8:11]
	v_mfma_f32_16x16x32_bf16 v[0:3], v[174:177], v[210:213], v[0:3]
	v_mfma_f32_16x16x32_bf16 v[56:59], v[170:173], v[186:189], v[56:59]
	v_mfma_f32_16x16x32_bf16 v[48:51], v[178:181], v[186:189], v[48:51]
	v_mfma_f32_16x16x32_bf16 v[40:43], v[170:173], v[194:197], v[40:43]
	v_mfma_f32_16x16x32_bf16 v[32:35], v[178:181], v[194:197], v[32:35]
	v_mfma_f32_16x16x32_bf16 v[24:27], v[170:173], v[202:205], v[24:27]
	v_mfma_f32_16x16x32_bf16 v[16:19], v[178:181], v[202:205], v[16:19]
	v_mfma_f32_16x16x32_bf16 v[8:11], v[170:173], v[214:217], v[8:11]
	v_mfma_f32_16x16x32_bf16 v[0:3], v[178:181], v[214:217], v[0:3]
	s_barrier
	s_add_i32 s46, s46, 2
	s_add_u32 s22, s22, 0x100
	s_addc_u32 s23, s23, 0
	s_add_u32 s44, s44, 0x100
	s_addc_u32 s45, s45, 0
	s_cmp_gt_u32 s46, 13
	s_cbranch_scc0 .LBB0_1912
	s_branch .Lkp_exit_4
.LBB0_1912:
	ds_read_b128 v[144:147], v151
	ds_read_b128 v[154:157], v151 offset:1024
	ds_read_b128 v[158:161], v151 offset:2048
	ds_read_b128 v[162:165], v151 offset:3072
	ds_read_b128 v[166:169], v152
	ds_read_b128 v[170:173], v152 offset:1024
	ds_read_b128 v[174:177], v152 offset:2048
	ds_read_b128 v[178:181], v152 offset:3072
	s_add_u32 s24, s22, 0xfffc0080
	s_addc_u32 s25, s23, -1
	s_cmp_eq_u32 s46, 12
	s_cselect_b32 s27, s15, s25
	s_cselect_b32 s26, s42, s24
	s_cselect_b32 s25, s13, s45
	s_cselect_b32 s24, s43, s44
	v_lshl_add_u64 v[206:207], s[22:23], 0, v[136:137]
	s_add_i32 m0, s21, 0xc000
	ds_read_b128 v[182:185], v153
	ds_read_b128 v[186:189], v153 offset:1024
	ds_read_b128 v[190:193], v153 offset:2048
	ds_read_b128 v[194:197], v153 offset:3072
	ds_read_b128 v[198:201], v153 offset:4096
	ds_read_b128 v[202:205], v153 offset:5120
	ds_read_b128 v[210:213], v153 offset:6144
	ds_read_b128 v[214:217], v153 offset:7168
	global_load_lds_dwordx4 v[206:207], off
	v_lshl_add_u64 v[206:207], s[22:23], 0, v[138:139]
	s_add_i32 m0, s21, 0xe000
	s_nop 0
	global_load_lds_dwordx4 v[206:207], off
	s_waitcnt vmcnt(8)
	s_waitcnt lgkmcnt(0)
	s_barrier
	s_waitcnt lgkmcnt(0)
	v_mfma_f32_16x16x32_bf16 v[124:127], v[144:147], v[182:185], v[124:127]
	v_mfma_f32_16x16x32_bf16 v[116:119], v[158:161], v[182:185], v[116:119]
	v_mfma_f32_16x16x32_bf16 v[108:111], v[144:147], v[190:193], v[108:111]
	v_mfma_f32_16x16x32_bf16 v[100:103], v[158:161], v[190:193], v[100:103]
	v_mfma_f32_16x16x32_bf16 v[92:95], v[144:147], v[198:201], v[92:95]
	v_mfma_f32_16x16x32_bf16 v[84:87], v[158:161], v[198:201], v[84:87]
	v_mfma_f32_16x16x32_bf16 v[76:79], v[144:147], v[210:213], v[76:79]
	v_mfma_f32_16x16x32_bf16 v[68:71], v[158:161], v[210:213], v[68:71]
	v_mfma_f32_16x16x32_bf16 v[124:127], v[154:157], v[186:189], v[124:127]
	v_mfma_f32_16x16x32_bf16 v[116:119], v[162:165], v[186:189], v[116:119]
	v_mfma_f32_16x16x32_bf16 v[108:111], v[154:157], v[194:197], v[108:111]
	v_mfma_f32_16x16x32_bf16 v[100:103], v[162:165], v[194:197], v[100:103]
	v_mfma_f32_16x16x32_bf16 v[92:95], v[154:157], v[202:205], v[92:95]
	v_mfma_f32_16x16x32_bf16 v[84:87], v[162:165], v[202:205], v[84:87]
	v_mfma_f32_16x16x32_bf16 v[76:79], v[154:157], v[214:217], v[76:79]
	v_mfma_f32_16x16x32_bf16 v[68:71], v[162:165], v[214:217], v[68:71]
	v_mfma_f32_16x16x32_bf16 v[120:123], v[166:169], v[182:185], v[120:123]
	v_mfma_f32_16x16x32_bf16 v[112:115], v[174:177], v[182:185], v[112:115]
	v_mfma_f32_16x16x32_bf16 v[104:107], v[166:169], v[190:193], v[104:107]
	v_mfma_f32_16x16x32_bf16 v[96:99], v[174:177], v[190:193], v[96:99]
	v_mfma_f32_16x16x32_bf16 v[88:91], v[166:169], v[198:201], v[88:91]
	v_mfma_f32_16x16x32_bf16 v[80:83], v[174:177], v[198:201], v[80:83]
	v_mfma_f32_16x16x32_bf16 v[72:75], v[166:169], v[210:213], v[72:75]
	v_mfma_f32_16x16x32_bf16 v[64:67], v[174:177], v[210:213], v[64:67]
	v_mfma_f32_16x16x32_bf16 v[120:123], v[170:173], v[186:189], v[120:123]
	v_mfma_f32_16x16x32_bf16 v[112:115], v[178:181], v[186:189], v[112:115]
	v_mfma_f32_16x16x32_bf16 v[104:107], v[170:173], v[194:197], v[104:107]
	v_mfma_f32_16x16x32_bf16 v[96:99], v[178:181], v[194:197], v[96:99]
	v_mfma_f32_16x16x32_bf16 v[88:91], v[170:173], v[202:205], v[88:91]
	v_mfma_f32_16x16x32_bf16 v[80:83], v[178:181], v[202:205], v[80:83]
	v_mfma_f32_16x16x32_bf16 v[72:75], v[170:173], v[214:217], v[72:75]
	v_mfma_f32_16x16x32_bf16 v[64:67], v[178:181], v[214:217], v[64:67]
	s_barrier
; #define PG8_STAGE(bufoff, gbase, voff) do { _Pragma("unroll") for (int _i = 0; _i < 2; ++_i) \
;         __builtin_amdgcn_global_load_lds((const unsigned*)((const char*)(gbase) + (voff)[_i]), (PG8_LAS unsigned*)(lds + (bufoff) + ldsw + _i * 8192), 16, 0, 0); } while (0)
; #define PG8_LDA(dst, b, h) do { _Pragma("unroll") for (int m = 0; m < 4; ++m) _Pragma("unroll") for (int k = 0; k < 2; ++k) dst[m][k] = *(const PG8_LAS bf16x8*)(lds + PG8_SA(b, h) + aoff + m * 2048 + k * 1024); } while (0)
; #define PG8_LDB(dst, b, h) do { _Pragma("unroll") for (int n = 0; n < 2; ++n) _Pragma("unroll") for (int k = 0; k < 2; ++k) dst[n][k] = *(const PG8_LAS bf16x8*)(lds + PG8_SB(b, h) + boff + n * 2048 + k * 1024); } while (0)
; #define PG8_MMA(ai, bj, At, Bt) do { __builtin_amdgcn_s_setprio(1); _Pragma("unroll") for (int m = 0; m < 4; ++m) _Pragma("unroll") for (int n = 0; n < 2; ++n) _Pragma("unroll") for (int k = 0; k < 2; ++k) \
;         acc[ai][bj][m][n] = __builtin_amdgcn_mfma_f32_16x16x32_bf16(Bt[n][k], At[m][k], acc[ai][bj][m][n], 0, 0, 0); __builtin_amdgcn_s_setprio(0); } while (0)
; #define PG8_WAIT_V(n) asm volatile("s_waitcnt vmcnt(" #n ")" ::: "memory")
; #define PG8_WAIT_L(n) asm volatile("s_waitcnt lgkmcnt(" #n ")" ::: "memory")
; #define PG8_BAR __builtin_amdgcn_s_barrier()
; #define PG8_SCHED __builtin_amdgcn_sched_barrier(0)
; template <class Epi, class Sched, bool ALIGN_EPI = false, bool SP2 = false>
; __device__ __forceinline__ void gemm_phase(PG8_LAS unsigned char* lds, const Gemm g, const Sched& S, const Epi& E, const int wid) {
;     ...
;             PG8_LDA(At, 0, 1); PG8_STAGE(PG8_SB(0, 0), b2, voffB); PG8_STAGE(PG8_SB(0, 1), b2 + hstep, voffB); PG8_STAGE(PG8_SA(0, 0), a2, voffA);
;             PG8_WAIT_V(8); PG8_WAIT_L(0); PG8_BAR; PG8_MMA(1, 0, At, B0); PG8_MMA(1, 1, At, B1); PG8_BAR; PG8_SCHED;
;             PG8_LDB(B0, 1, 0); PG8_LDB(B1, 1, 1); PG8_SCHED; PG8_LDA(At, 1, 0); PG8_STAGE(PG8_SA(0, 1), a2 + hstep, voffA);
;             PG8_WAIT_V(8); PG8_WAIT_L(0); PG8_BAR; PG8_MMA(0, 0, At, B0); PG8_MMA(0, 1, At, B1); PG8_BAR; PG8_SCHED;
	s_add_i32 s47, s38, s9
	v_lshl_add_u64 v[206:207], s[24:25], 0, v[132:133]
	s_mov_b32 m0, s47
	ds_read_b128 v[182:185], v153 offset:16384
	ds_read_b128 v[186:189], v153 offset:17408
	ds_read_b128 v[190:193], v153 offset:18432
	ds_read_b128 v[194:197], v153 offset:19456
	ds_read_b128 v[198:201], v153 offset:20480
	ds_read_b128 v[202:205], v153 offset:21504
	ds_read_b128 v[210:213], v153 offset:22528
	ds_read_b128 v[214:217], v153 offset:23552
	global_load_lds_dwordx4 v[206:207], off
	s_add_i32 m0, s47, 0x2000
	s_add_u32 s48, s24, 0x40000
	v_lshl_add_u64 v[218:219], s[24:25], 0, v[128:129]
	s_addc_u32 s49, s25, 0
	s_add_i32 s47, s39, s9
	global_load_lds_dwordx4 v[218:219], off
	v_lshl_add_u64 v[220:221], s[48:49], 0, v[132:133]
	s_mov_b32 m0, s47
	v_lshl_add_u64 v[222:223], s[26:27], 0, v[130:131]
	global_load_lds_dwordx4 v[220:221], off
	v_lshl_add_u64 v[220:221], s[48:49], 0, v[128:129]
	s_add_i32 m0, s47, 0x2000
	s_nop 0
	global_load_lds_dwordx4 v[220:221], off
	v_lshl_add_u64 v[220:221], s[26:27], 0, v[134:135]
	s_mov_b32 m0, s21
	s_nop 0
	global_load_lds_dwordx4 v[220:221], off
	s_mov_b32 m0, s30
	s_nop 0
	global_load_lds_dwordx4 v[222:223], off
	s_nop 0
	s_waitcnt vmcnt(8)
	s_waitcnt lgkmcnt(0)
	s_barrier
	s_waitcnt lgkmcnt(0)
	v_mfma_f32_16x16x32_bf16 v[60:63], v[144:147], v[182:185], v[60:63]
	v_mfma_f32_16x16x32_bf16 v[52:55], v[158:161], v[182:185], v[52:55]
	v_mfma_f32_16x16x32_bf16 v[44:47], v[144:147], v[190:193], v[44:47]
	v_mfma_f32_16x16x32_bf16 v[36:39], v[158:161], v[190:193], v[36:39]
	v_mfma_f32_16x16x32_bf16 v[28:31], v[144:147], v[198:201], v[28:31]
	v_mfma_f32_16x16x32_bf16 v[20:23], v[158:161], v[198:201], v[20:23]
	v_mfma_f32_16x16x32_bf16 v[12:15], v[144:147], v[210:213], v[12:15]
	v_mfma_f32_16x16x32_bf16 v[4:7], v[158:161], v[210:213], v[4:7]
	v_mfma_f32_16x16x32_bf16 v[60:63], v[154:157], v[186:189], v[60:63]
	v_mfma_f32_16x16x32_bf16 v[52:55], v[162:165], v[186:189], v[52:55]
	v_mfma_f32_16x16x32_bf16 v[44:47], v[154:157], v[194:197], v[44:47]
	v_mfma_f32_16x16x32_bf16 v[36:39], v[162:165], v[194:197], v[36:39]
	v_mfma_f32_16x16x32_bf16 v[28:31], v[154:157], v[202:205], v[28:31]
	v_mfma_f32_16x16x32_bf16 v[20:23], v[162:165], v[202:205], v[20:23]
	v_mfma_f32_16x16x32_bf16 v[12:15], v[154:157], v[214:217], v[12:15]
	v_mfma_f32_16x16x32_bf16 v[4:7], v[162:165], v[214:217], v[4:7]
	v_mfma_f32_16x16x32_bf16 v[56:59], v[166:169], v[182:185], v[56:59]
	v_mfma_f32_16x16x32_bf16 v[48:51], v[174:177], v[182:185], v[48:51]
	v_mfma_f32_16x16x32_bf16 v[40:43], v[166:169], v[190:193], v[40:43]
	v_mfma_f32_16x16x32_bf16 v[32:35], v[174:177], v[190:193], v[32:35]
	v_mfma_f32_16x16x32_bf16 v[24:27], v[166:169], v[198:201], v[24:27]
	v_mfma_f32_16x16x32_bf16 v[16:19], v[174:177], v[198:201], v[16:19]
	v_mfma_f32_16x16x32_bf16 v[8:11], v[166:169], v[210:213], v[8:11]
	v_mfma_f32_16x16x32_bf16 v[0:3], v[174:177], v[210:213], v[0:3]
	v_mfma_f32_16x16x32_bf16 v[56:59], v[170:173], v[186:189], v[56:59]
	v_mfma_f32_16x16x32_bf16 v[48:51], v[178:181], v[186:189], v[48:51]
	v_mfma_f32_16x16x32_bf16 v[40:43], v[170:173], v[194:197], v[40:43]
	v_mfma_f32_16x16x32_bf16 v[32:35], v[178:181], v[194:197], v[32:35]
	v_mfma_f32_16x16x32_bf16 v[24:27], v[170:173], v[202:205], v[24:27]
	v_mfma_f32_16x16x32_bf16 v[16:19], v[178:181], v[202:205], v[16:19]
	v_mfma_f32_16x16x32_bf16 v[8:11], v[170:173], v[214:217], v[8:11]
	v_mfma_f32_16x16x32_bf16 v[0:3], v[178:181], v[214:217], v[0:3]
	s_barrier
	s_add_i32 s47, 0, 0x18000
	s_add_i32 s48, 0, 0x1c000
	v_add_u32_e32 v162, s47, v149
	v_add_u32_e32 v178, s48, v149
	ds_read_b128 v[144:147], v162
	ds_read_b128 v[154:157], v162 offset:1024
	ds_read_b128 v[158:161], v162 offset:2048
	ds_read_b128 v[162:165], v162 offset:3072
	ds_read_b128 v[166:169], v178
	ds_read_b128 v[170:173], v178 offset:1024
	ds_read_b128 v[174:177], v178 offset:2048
	ds_read_b128 v[178:181], v178 offset:3072
	s_add_u32 s26, s26, 0x40000
	s_addc_u32 s27, s27, 0
	s_mov_b32 m0, s31
	v_lshl_add_u64 v[224:225], s[26:27], 0, v[134:135]
	ds_read_b128 v[182:185], v153 offset:32768
	ds_read_b128 v[186:189], v153 offset:33792
	ds_read_b128 v[190:193], v153 offset:34816
	ds_read_b128 v[194:197], v153 offset:35840
	ds_read_b128 v[198:201], v153 offset:36864
	ds_read_b128 v[202:205], v153 offset:37888
	ds_read_b128 v[210:213], v153 offset:38912
	ds_read_b128 v[214:217], v153 offset:39936
	global_load_lds_dwordx4 v[224:225], off
	v_lshl_add_u64 v[224:225], s[26:27], 0, v[130:131]
	s_mov_b32 m0, s33
	s_nop 0
	global_load_lds_dwordx4 v[224:225], off
	s_nop 0
	s_waitcnt vmcnt(8)
	s_waitcnt lgkmcnt(0)
	s_barrier
; #define PG8_STAGE(bufoff, gbase, voff) do { _Pragma("unroll") for (int _i = 0; _i < 2; ++_i) \
;         __builtin_amdgcn_global_load_lds((const unsigned*)((const char*)(gbase) + (voff)[_i]), (PG8_LAS unsigned*)(lds + (bufoff) + ldsw + _i * 8192), 16, 0, 0); } while (0)
; #define PG8_LDA(dst, b, h) do { _Pragma("unroll") for (int m = 0; m < 4; ++m) _Pragma("unroll") for (int k = 0; k < 2; ++k) dst[m][k] = *(const PG8_LAS bf16x8*)(lds + PG8_SA(b, h) + aoff + m * 2048 + k * 1024); } while (0)
; #define PG8_LDB(dst, b, h) do { _Pragma("unroll") for (int n = 0; n < 2; ++n) _Pragma("unroll") for (int k = 0; k < 2; ++k) dst[n][k] = *(const PG8_LAS bf16x8*)(lds + PG8_SB(b, h) + boff + n * 2048 + k * 1024); } while (0)
; #define PG8_MMA(ai, bj, At, Bt) do { __builtin_amdgcn_s_setprio(1); _Pragma("unroll") for (int m = 0; m < 4; ++m) _Pragma("unroll") for (int n = 0; n < 2; ++n) _Pragma("unroll") for (int k = 0; k < 2; ++k) \
;         acc[ai][bj][m][n] = __builtin_amdgcn_mfma_f32_16x16x32_bf16(Bt[n][k], At[m][k], acc[ai][bj][m][n], 0, 0, 0); __builtin_amdgcn_s_setprio(0); } while (0)
; #define PG8_WAIT_V(n) asm volatile("s_waitcnt vmcnt(" #n ")" ::: "memory")
; #define PG8_WAIT_L(n) asm volatile("s_waitcnt lgkmcnt(" #n ")" ::: "memory")
; #define PG8_BAR __builtin_amdgcn_s_barrier()
; #define PG8_SCHED __builtin_amdgcn_sched_barrier(0)
; template <class Epi, class Sched, bool ALIGN_EPI = false, bool SP2 = false>
; __device__ __forceinline__ void gemm_phase(PG8_LAS unsigned char* lds, const Gemm g, const Sched& S, const Epi& E, const int wid) {
;     ...
;             PG8_LDB(B0, 1, 0); PG8_LDB(B1, 1, 1); PG8_SCHED; PG8_LDA(At, 1, 0); PG8_STAGE(PG8_SA(0, 1), a2 + hstep, voffA);
;             PG8_WAIT_V(8); PG8_WAIT_L(0); PG8_BAR; PG8_MMA(0, 0, At, B0); PG8_MMA(0, 1, At, B1); PG8_BAR; PG8_SCHED;
;             PG8_LDA(At, 1, 1); PG8_STAGE(PG8_SB(1, 0), b3, voffB); PG8_STAGE(PG8_SB(1, 1), b3 + hstep, voffB); PG8_STAGE(PG8_SA(1, 0), a3, voffA);
;             PG8_WAIT_V(8); PG8_WAIT_L(0); PG8_BAR; PG8_MMA(1, 0, At, B0); PG8_MMA(1, 1, At, B1); PG8_BAR; PG8_SCHED;
	s_waitcnt lgkmcnt(0)
	v_mfma_f32_16x16x32_bf16 v[124:127], v[144:147], v[182:185], v[124:127]
	v_mfma_f32_16x16x32_bf16 v[116:119], v[158:161], v[182:185], v[116:119]
	v_mfma_f32_16x16x32_bf16 v[108:111], v[144:147], v[190:193], v[108:111]
	v_mfma_f32_16x16x32_bf16 v[100:103], v[158:161], v[190:193], v[100:103]
	v_mfma_f32_16x16x32_bf16 v[92:95], v[144:147], v[198:201], v[92:95]
	v_mfma_f32_16x16x32_bf16 v[84:87], v[158:161], v[198:201], v[84:87]
	v_mfma_f32_16x16x32_bf16 v[76:79], v[144:147], v[210:213], v[76:79]
	v_mfma_f32_16x16x32_bf16 v[68:71], v[158:161], v[210:213], v[68:71]
	v_mfma_f32_16x16x32_bf16 v[124:127], v[154:157], v[186:189], v[124:127]
	v_mfma_f32_16x16x32_bf16 v[116:119], v[162:165], v[186:189], v[116:119]
	v_mfma_f32_16x16x32_bf16 v[108:111], v[154:157], v[194:197], v[108:111]
	v_mfma_f32_16x16x32_bf16 v[100:103], v[162:165], v[194:197], v[100:103]
	v_mfma_f32_16x16x32_bf16 v[92:95], v[154:157], v[202:205], v[92:95]
	v_mfma_f32_16x16x32_bf16 v[84:87], v[162:165], v[202:205], v[84:87]
	v_mfma_f32_16x16x32_bf16 v[76:79], v[154:157], v[214:217], v[76:79]
	v_mfma_f32_16x16x32_bf16 v[68:71], v[162:165], v[214:217], v[68:71]
	v_mfma_f32_16x16x32_bf16 v[120:123], v[166:169], v[182:185], v[120:123]
	v_mfma_f32_16x16x32_bf16 v[112:115], v[174:177], v[182:185], v[112:115]
	v_mfma_f32_16x16x32_bf16 v[104:107], v[166:169], v[190:193], v[104:107]
	v_mfma_f32_16x16x32_bf16 v[96:99], v[174:177], v[190:193], v[96:99]
	v_mfma_f32_16x16x32_bf16 v[88:91], v[166:169], v[198:201], v[88:91]
	v_mfma_f32_16x16x32_bf16 v[80:83], v[174:177], v[198:201], v[80:83]
	v_mfma_f32_16x16x32_bf16 v[72:75], v[166:169], v[210:213], v[72:75]
	v_mfma_f32_16x16x32_bf16 v[64:67], v[174:177], v[210:213], v[64:67]
	v_mfma_f32_16x16x32_bf16 v[120:123], v[170:173], v[186:189], v[120:123]
	v_mfma_f32_16x16x32_bf16 v[112:115], v[178:181], v[186:189], v[112:115]
	v_mfma_f32_16x16x32_bf16 v[104:107], v[170:173], v[194:197], v[104:107]
	v_mfma_f32_16x16x32_bf16 v[96:99], v[178:181], v[194:197], v[96:99]
	v_mfma_f32_16x16x32_bf16 v[88:91], v[170:173], v[202:205], v[88:91]
	v_mfma_f32_16x16x32_bf16 v[80:83], v[178:181], v[202:205], v[80:83]
	v_mfma_f32_16x16x32_bf16 v[72:75], v[170:173], v[214:217], v[72:75]
	v_mfma_f32_16x16x32_bf16 v[64:67], v[178:181], v[214:217], v[64:67]
	s_barrier
	s_add_i32 s26, s47, s9
	v_lshl_add_u64 v[206:207], v[206:207], 0, s[2:3]
	s_mov_b32 m0, s26
	ds_read_b128 v[182:185], v153 offset:49152
	ds_read_b128 v[186:189], v153 offset:50176
	ds_read_b128 v[190:193], v153 offset:51200
	ds_read_b128 v[194:197], v153 offset:52224
	ds_read_b128 v[198:201], v153 offset:53248
	ds_read_b128 v[202:205], v153 offset:54272
	ds_read_b128 v[210:213], v153 offset:55296
	ds_read_b128 v[214:217], v153 offset:56320
	global_load_lds_dwordx4 v[206:207], off
	s_add_i32 m0, s26, 0x2000
	s_add_u32 s24, s24, 0x40080
	v_lshl_add_u64 v[206:207], v[218:219], 0, s[2:3]
	s_addc_u32 s25, s25, 0
	s_add_i32 s26, s48, s9
	global_load_lds_dwordx4 v[206:207], off
	v_lshl_add_u64 v[206:207], s[24:25], 0, v[132:133]
	s_mov_b32 m0, s26
	s_nop 0
	global_load_lds_dwordx4 v[206:207], off
	v_lshl_add_u64 v[206:207], s[24:25], 0, v[128:129]
	s_add_i32 m0, s26, 0x2000
	s_nop 0
	global_load_lds_dwordx4 v[206:207], off
	v_lshl_add_u64 v[206:207], v[220:221], 0, s[2:3]
	s_mov_b32 m0, s35
	s_nop 0
	global_load_lds_dwordx4 v[206:207], off
	v_lshl_add_u64 v[206:207], v[222:223], 0, s[2:3]
	s_mov_b32 m0, s36
	s_nop 0
	global_load_lds_dwordx4 v[206:207], off
	s_waitcnt vmcnt(8)
	s_waitcnt lgkmcnt(0)
	s_barrier
	s_waitcnt lgkmcnt(0)
	v_mfma_f32_16x16x32_bf16 v[60:63], v[144:147], v[182:185], v[60:63]
	v_mfma_f32_16x16x32_bf16 v[52:55], v[158:161], v[182:185], v[52:55]
	v_mfma_f32_16x16x32_bf16 v[44:47], v[144:147], v[190:193], v[44:47]
	v_mfma_f32_16x16x32_bf16 v[36:39], v[158:161], v[190:193], v[36:39]
	v_mfma_f32_16x16x32_bf16 v[28:31], v[144:147], v[198:201], v[28:31]
	v_mfma_f32_16x16x32_bf16 v[20:23], v[158:161], v[198:201], v[20:23]
	v_mfma_f32_16x16x32_bf16 v[12:15], v[144:147], v[210:213], v[12:15]
	v_mfma_f32_16x16x32_bf16 v[4:7], v[158:161], v[210:213], v[4:7]
	v_mfma_f32_16x16x32_bf16 v[60:63], v[154:157], v[186:189], v[60:63]
	v_mfma_f32_16x16x32_bf16 v[52:55], v[162:165], v[186:189], v[52:55]
	v_mfma_f32_16x16x32_bf16 v[44:47], v[154:157], v[194:197], v[44:47]
	v_mfma_f32_16x16x32_bf16 v[36:39], v[162:165], v[194:197], v[36:39]
	v_mfma_f32_16x16x32_bf16 v[28:31], v[154:157], v[202:205], v[28:31]
	v_mfma_f32_16x16x32_bf16 v[20:23], v[162:165], v[202:205], v[20:23]
	v_mfma_f32_16x16x32_bf16 v[12:15], v[154:157], v[214:217], v[12:15]
	v_mfma_f32_16x16x32_bf16 v[4:7], v[162:165], v[214:217], v[4:7]
	v_mfma_f32_16x16x32_bf16 v[56:59], v[166:169], v[182:185], v[56:59]
	v_mfma_f32_16x16x32_bf16 v[48:51], v[174:177], v[182:185], v[48:51]
	v_mfma_f32_16x16x32_bf16 v[40:43], v[166:169], v[190:193], v[40:43]
	v_mfma_f32_16x16x32_bf16 v[32:35], v[174:177], v[190:193], v[32:35]
	v_mfma_f32_16x16x32_bf16 v[24:27], v[166:169], v[198:201], v[24:27]
	v_mfma_f32_16x16x32_bf16 v[16:19], v[174:177], v[198:201], v[16:19]
	v_mfma_f32_16x16x32_bf16 v[8:11], v[166:169], v[210:213], v[8:11]
	v_mfma_f32_16x16x32_bf16 v[0:3], v[174:177], v[210:213], v[0:3]
	v_mfma_f32_16x16x32_bf16 v[56:59], v[170:173], v[186:189], v[56:59]
	v_mfma_f32_16x16x32_bf16 v[48:51], v[178:181], v[186:189], v[48:51]
	v_mfma_f32_16x16x32_bf16 v[40:43], v[170:173], v[194:197], v[40:43]
	v_mfma_f32_16x16x32_bf16 v[32:35], v[178:181], v[194:197], v[32:35]
	v_mfma_f32_16x16x32_bf16 v[24:27], v[170:173], v[202:205], v[24:27]
	v_mfma_f32_16x16x32_bf16 v[16:19], v[178:181], v[202:205], v[16:19]
	v_mfma_f32_16x16x32_bf16 v[8:11], v[170:173], v[214:217], v[8:11]
	v_mfma_f32_16x16x32_bf16 v[0:3], v[178:181], v[214:217], v[0:3]
	s_barrier
	s_add_i32 s46, s46, 2
	s_add_u32 s22, s22, 0x100
	s_addc_u32 s23, s23, 0
	s_add_u32 s44, s44, 0x100
	s_addc_u32 s45, s45, 0
	s_cmp_gt_u32 s46, 13
	s_cbranch_scc0 .LBB0_1912

; #define PG8_STAGE(bufoff, gbase, voff) do { _Pragma("unroll") for (int _i = 0; _i < 2; ++_i) \
;         __builtin_amdgcn_global_load_lds((const unsigned*)((const char*)(gbase) + (voff)[_i]), (PG8_LAS unsigned*)(lds + (bufoff) + ldsw + _i * 8192), 16, 0, 0); } while (0)
; #define PG8_LDA(dst, b, h) do { _Pragma("unroll") for (int m = 0; m < 4; ++m) _Pragma("unroll") for (int k = 0; k < 2; ++k) dst[m][k] = *(const PG8_LAS bf16x8*)(lds + PG8_SA(b, h) + aoff + m * 2048 + k * 1024); } while (0)
; #define PG8_LDB(dst, b, h) do { _Pragma("unroll") for (int n = 0; n < 2; ++n) _Pragma("unroll") for (int k = 0; k < 2; ++k) dst[n][k] = *(const PG8_LAS bf16x8*)(lds + PG8_SB(b, h) + boff + n * 2048 + k * 1024); } while (0)
; #define PG8_MMA(ai, bj, At, Bt) do { __builtin_amdgcn_s_setprio(1); _Pragma("unroll") for (int m = 0; m < 4; ++m) _Pragma("unroll") for (int n = 0; n < 2; ++n) _Pragma("unroll") for (int k = 0; k < 2; ++k) \
;         acc[ai][bj][m][n] = __builtin_amdgcn_mfma_f32_16x16x32_bf16(Bt[n][k], At[m][k], acc[ai][bj][m][n], 0, 0, 0); __builtin_amdgcn_s_setprio(0); } while (0)
; #define PG8_WAIT_V(n) asm volatile("s_waitcnt vmcnt(" #n ")" ::: "memory")
; #define PG8_WAIT_L(n) asm volatile("s_waitcnt lgkmcnt(" #n ")" ::: "memory")
; #define PG8_BAR __builtin_amdgcn_s_barrier()
; #define PG8_SCHED __builtin_amdgcn_sched_barrier(0)
; template <class Epi, class Sched, bool ALIGN_EPI = false, bool SP2 = false>
; __device__ __forceinline__ void gemm_phase(PG8_LAS unsigned char* lds, const Gemm g, const Sched& S, const Epi& E, const int wid) {
;     ...
;             PG8_LDB(B0, 0, 0); PG8_LDB(B1, 0, 1); PG8_SCHED; PG8_LDA(At, 0, 0); PG8_STAGE(PG8_SA(1, 1), a1 + hstep, voffA);
;             PG8_WAIT_V(8); PG8_WAIT_L(0); PG8_BAR; PG8_MMA(0, 0, At, B0); PG8_MMA(0, 1, At, B1); PG8_BAR; PG8_SCHED;
;             PG8_LDA(At, 0, 1); PG8_STAGE(PG8_SB(0, 0), b2, voffB); PG8_STAGE(PG8_SB(0, 1), b2 + hstep, voffB); PG8_STAGE(PG8_SA(0, 0), a2, voffA);
.LBB0_2460:
	v_add_u32_e32 v151, s35, v149
	ds_read_b128 v[152:155], v151
	ds_read_b128 v[156:159], v151 offset:1024
	ds_read_b128 v[160:163], v151 offset:2048
	ds_read_b128 v[168:171], v151 offset:3072
	v_add_u32_e32 v151, s36, v149
	s_add_u32 s16, s8, s14
	ds_read_b128 v[172:175], v151
	ds_read_b128 v[178:181], v151 offset:1024
	ds_read_b128 v[182:185], v151 offset:2048
	ds_read_b128 v[186:189], v151 offset:3072
	s_addc_u32 s17, s9, s15
	s_add_u32 s16, s16, 0x100
	s_addc_u32 s17, s17, 0
	s_add_u32 s43, s40, s14
	s_addc_u32 s44, s41, s15
	s_cmpk_eq_i32 s14, 0x1500
	s_cselect_b32 s19, s13, s17
	s_cselect_b32 s18, s12, s16
	s_cselect_b32 s17, s5, s44
	s_cselect_b32 s16, s4, s43
	v_lshl_add_u64 v[222:223], v[144:145], 0, s[14:15]
	s_add_i32 m0, s26, 0xc000
	ds_read_b128 v[190:193], v150
	ds_read_b128 v[194:197], v150 offset:1024
	ds_read_b128 v[198:201], v150 offset:2048
	ds_read_b128 v[202:205], v150 offset:3072
	ds_read_b128 v[206:209], v150 offset:4096
	ds_read_b128 v[210:213], v150 offset:5120
	ds_read_b128 v[214:217], v150 offset:6144
	ds_read_b128 v[218:221], v150 offset:7168
	global_load_lds_dwordx4 v[222:223], off
	v_lshl_add_u64 v[222:223], v[146:147], 0, s[14:15]
	s_add_i32 m0, s26, 0xe000
	s_nop 0
	global_load_lds_dwordx4 v[222:223], off
	s_waitcnt vmcnt(8)
	s_waitcnt lgkmcnt(0)
	s_barrier
	s_waitcnt lgkmcnt(0)
	v_mfma_f32_16x16x32_bf16 v[124:127], v[152:155], v[190:193], v[124:127]
	v_mfma_f32_16x16x32_bf16 v[120:123], v[160:163], v[190:193], v[120:123]
	v_mfma_f32_16x16x32_bf16 v[112:115], v[152:155], v[198:201], v[112:115]
	v_mfma_f32_16x16x32_bf16 v[104:107], v[160:163], v[198:201], v[104:107]
	v_mfma_f32_16x16x32_bf16 v[96:99], v[152:155], v[206:209], v[96:99]
	v_mfma_f32_16x16x32_bf16 v[88:91], v[160:163], v[206:209], v[88:91]
	v_mfma_f32_16x16x32_bf16 v[80:83], v[152:155], v[214:217], v[80:83]
	v_mfma_f32_16x16x32_bf16 v[72:75], v[160:163], v[214:217], v[72:75]
	v_mfma_f32_16x16x32_bf16 v[124:127], v[156:159], v[194:197], v[124:127]
	v_mfma_f32_16x16x32_bf16 v[120:123], v[168:171], v[194:197], v[120:123]
	v_mfma_f32_16x16x32_bf16 v[112:115], v[156:159], v[202:205], v[112:115]
	v_mfma_f32_16x16x32_bf16 v[104:107], v[168:171], v[202:205], v[104:107]
	v_mfma_f32_16x16x32_bf16 v[96:99], v[156:159], v[210:213], v[96:99]
	v_mfma_f32_16x16x32_bf16 v[88:91], v[168:171], v[210:213], v[88:91]
	v_mfma_f32_16x16x32_bf16 v[80:83], v[156:159], v[218:221], v[80:83]
	v_mfma_f32_16x16x32_bf16 v[72:75], v[168:171], v[218:221], v[72:75]
	v_mfma_f32_16x16x32_bf16 v[116:119], v[172:175], v[190:193], v[116:119]
	v_mfma_f32_16x16x32_bf16 v[108:111], v[182:185], v[190:193], v[108:111]
	v_mfma_f32_16x16x32_bf16 v[100:103], v[172:175], v[198:201], v[100:103]
	v_mfma_f32_16x16x32_bf16 v[92:95], v[182:185], v[198:201], v[92:95]
	v_mfma_f32_16x16x32_bf16 v[84:87], v[172:175], v[206:209], v[84:87]
	v_mfma_f32_16x16x32_bf16 v[76:79], v[182:185], v[206:209], v[76:79]
	v_mfma_f32_16x16x32_bf16 v[68:71], v[172:175], v[214:217], v[68:71]
	v_mfma_f32_16x16x32_bf16 v[64:67], v[182:185], v[214:217], v[64:67]
	v_mfma_f32_16x16x32_bf16 v[116:119], v[178:181], v[194:197], v[116:119]
	v_mfma_f32_16x16x32_bf16 v[108:111], v[186:189], v[194:197], v[108:111]
	v_mfma_f32_16x16x32_bf16 v[100:103], v[178:181], v[202:205], v[100:103]
	v_mfma_f32_16x16x32_bf16 v[92:95], v[186:189], v[202:205], v[92:95]
	v_mfma_f32_16x16x32_bf16 v[84:87], v[178:181], v[210:213], v[84:87]
	v_mfma_f32_16x16x32_bf16 v[76:79], v[186:189], v[210:213], v[76:79]
	v_mfma_f32_16x16x32_bf16 v[68:71], v[178:181], v[218:221], v[68:71]
	v_mfma_f32_16x16x32_bf16 v[64:67], v[186:189], v[218:221], v[64:67]
	s_barrier
	s_add_i32 s43, s35, s24
	v_lshl_add_u64 v[222:223], s[16:17], 0, v[130:131]
	s_mov_b32 m0, s43
	ds_read_b128 v[190:193], v150 offset:16384
	ds_read_b128 v[194:197], v150 offset:17408
	ds_read_b128 v[198:201], v150 offset:18432
	ds_read_b128 v[202:205], v150 offset:19456
	ds_read_b128 v[206:209], v150 offset:20480
	ds_read_b128 v[210:213], v150 offset:21504
	ds_read_b128 v[214:217], v150 offset:22528
	ds_read_b128 v[218:221], v150 offset:23552
	global_load_lds_dwordx4 v[222:223], off
	s_add_i32 m0, s43, 0x2000
	s_add_u32 s44, s16, 0xb0000
	v_lshl_add_u64 v[224:225], s[16:17], 0, v[134:135]
	s_addc_u32 s45, s17, 0
	s_add_i32 s43, s36, s24
	global_load_lds_dwordx4 v[224:225], off
	v_lshl_add_u64 v[226:227], s[44:45], 0, v[130:131]
	s_mov_b32 m0, s43
	v_lshl_add_u64 v[228:229], s[18:19], 0, v[132:133]
	global_load_lds_dwordx4 v[226:227], off
	v_lshl_add_u64 v[226:227], s[44:45], 0, v[134:135]
	s_add_i32 m0, s43, 0x2000
	s_nop 0
	global_load_lds_dwordx4 v[226:227], off
	v_lshl_add_u64 v[226:227], s[18:19], 0, v[128:129]
	s_mov_b32 m0, s26
	s_nop 0
	global_load_lds_dwordx4 v[226:227], off
	s_mov_b32 m0, s27
	s_nop 0
	global_load_lds_dwordx4 v[228:229], off
	s_nop 0
	s_waitcnt vmcnt(8)
	s_waitcnt lgkmcnt(0)
	s_barrier
; #define PG8_STAGE(bufoff, gbase, voff) do { _Pragma("unroll") for (int _i = 0; _i < 2; ++_i) \
;         __builtin_amdgcn_global_load_lds((const unsigned*)((const char*)(gbase) + (voff)[_i]), (PG8_LAS unsigned*)(lds + (bufoff) + ldsw + _i * 8192), 16, 0, 0); } while (0)
; #define PG8_LDA(dst, b, h) do { _Pragma("unroll") for (int m = 0; m < 4; ++m) _Pragma("unroll") for (int k = 0; k < 2; ++k) dst[m][k] = *(const PG8_LAS bf16x8*)(lds + PG8_SA(b, h) + aoff + m * 2048 + k * 1024); } while (0)
; #define PG8_LDB(dst, b, h) do { _Pragma("unroll") for (int n = 0; n < 2; ++n) _Pragma("unroll") for (int k = 0; k < 2; ++k) dst[n][k] = *(const PG8_LAS bf16x8*)(lds + PG8_SB(b, h) + boff + n * 2048 + k * 1024); } while (0)
; #define PG8_MMA(ai, bj, At, Bt) do { __builtin_amdgcn_s_setprio(1); _Pragma("unroll") for (int m = 0; m < 4; ++m) _Pragma("unroll") for (int n = 0; n < 2; ++n) _Pragma("unroll") for (int k = 0; k < 2; ++k) \
;         acc[ai][bj][m][n] = __builtin_amdgcn_mfma_f32_16x16x32_bf16(Bt[n][k], At[m][k], acc[ai][bj][m][n], 0, 0, 0); __builtin_amdgcn_s_setprio(0); } while (0)
; #define PG8_WAIT_V(n) asm volatile("s_waitcnt vmcnt(" #n ")" ::: "memory")
; #define PG8_WAIT_L(n) asm volatile("s_waitcnt lgkmcnt(" #n ")" ::: "memory")
; #define PG8_BAR __builtin_amdgcn_s_barrier()
; #define PG8_SCHED __builtin_amdgcn_sched_barrier(0)
; template <class Epi, class Sched, bool ALIGN_EPI = false, bool SP2 = false>
; __device__ __forceinline__ void gemm_phase(PG8_LAS unsigned char* lds, const Gemm g, const Sched& S, const Epi& E, const int wid) {
;     ...
;             PG8_WAIT_V(8); PG8_WAIT_L(0); PG8_BAR; PG8_MMA(1, 0, At, B0); PG8_MMA(1, 1, At, B1); PG8_BAR; PG8_SCHED;
;             PG8_LDB(B0, 1, 0); PG8_LDB(B1, 1, 1); PG8_SCHED; PG8_LDA(At, 1, 0); PG8_STAGE(PG8_SA(0, 1), a2 + hstep, voffA);
;             PG8_WAIT_V(8); PG8_WAIT_L(0); PG8_BAR; PG8_MMA(0, 0, At, B0); PG8_MMA(0, 1, At, B1); PG8_BAR; PG8_SCHED;
	s_waitcnt lgkmcnt(0)
	v_mfma_f32_16x16x32_bf16 v[60:63], v[152:155], v[190:193], v[60:63]
	v_mfma_f32_16x16x32_bf16 v[56:59], v[160:163], v[190:193], v[56:59]
	v_mfma_f32_16x16x32_bf16 v[44:47], v[152:155], v[198:201], v[44:47]
	v_mfma_f32_16x16x32_bf16 v[40:43], v[160:163], v[198:201], v[40:43]
	v_mfma_f32_16x16x32_bf16 v[28:31], v[152:155], v[206:209], v[28:31]
	v_mfma_f32_16x16x32_bf16 v[24:27], v[160:163], v[206:209], v[24:27]
	v_mfma_f32_16x16x32_bf16 v[12:15], v[152:155], v[214:217], v[12:15]
	v_mfma_f32_16x16x32_bf16 v[8:11], v[160:163], v[214:217], v[8:11]
	v_mfma_f32_16x16x32_bf16 v[60:63], v[156:159], v[194:197], v[60:63]
	v_mfma_f32_16x16x32_bf16 v[56:59], v[168:171], v[194:197], v[56:59]
	v_mfma_f32_16x16x32_bf16 v[44:47], v[156:159], v[202:205], v[44:47]
	v_mfma_f32_16x16x32_bf16 v[40:43], v[168:171], v[202:205], v[40:43]
	v_mfma_f32_16x16x32_bf16 v[28:31], v[156:159], v[210:213], v[28:31]
	v_mfma_f32_16x16x32_bf16 v[24:27], v[168:171], v[210:213], v[24:27]
	v_mfma_f32_16x16x32_bf16 v[12:15], v[156:159], v[218:221], v[12:15]
	v_mfma_f32_16x16x32_bf16 v[8:11], v[168:171], v[218:221], v[8:11]
	v_mfma_f32_16x16x32_bf16 v[52:55], v[172:175], v[190:193], v[52:55]
	v_mfma_f32_16x16x32_bf16 v[48:51], v[182:185], v[190:193], v[48:51]
	v_mfma_f32_16x16x32_bf16 v[36:39], v[172:175], v[198:201], v[36:39]
	v_mfma_f32_16x16x32_bf16 v[32:35], v[182:185], v[198:201], v[32:35]
	v_mfma_f32_16x16x32_bf16 v[20:23], v[172:175], v[206:209], v[20:23]
	v_mfma_f32_16x16x32_bf16 v[16:19], v[182:185], v[206:209], v[16:19]
	v_mfma_f32_16x16x32_bf16 v[4:7], v[172:175], v[214:217], v[4:7]
	v_mfma_f32_16x16x32_bf16 v[0:3], v[182:185], v[214:217], v[0:3]
	v_mfma_f32_16x16x32_bf16 v[52:55], v[178:181], v[194:197], v[52:55]
	v_mfma_f32_16x16x32_bf16 v[48:51], v[186:189], v[194:197], v[48:51]
	v_mfma_f32_16x16x32_bf16 v[36:39], v[178:181], v[202:205], v[36:39]
	v_mfma_f32_16x16x32_bf16 v[32:35], v[186:189], v[202:205], v[32:35]
	v_mfma_f32_16x16x32_bf16 v[20:23], v[178:181], v[210:213], v[20:23]
	v_mfma_f32_16x16x32_bf16 v[16:19], v[186:189], v[210:213], v[16:19]
	v_mfma_f32_16x16x32_bf16 v[4:7], v[178:181], v[218:221], v[4:7]
	v_mfma_f32_16x16x32_bf16 v[0:3], v[186:189], v[218:221], v[0:3]
	s_barrier
	s_add_i32 s43, 0, 0x18000
	v_add_u32_e32 v151, s43, v149
	s_add_i32 s44, 0, 0x1c000
	ds_read_b128 v[152:155], v151
	ds_read_b128 v[156:159], v151 offset:1024
	ds_read_b128 v[160:163], v151 offset:2048
	ds_read_b128 v[168:171], v151 offset:3072
	v_add_u32_e32 v151, s44, v149
	ds_read_b128 v[172:175], v151
	ds_read_b128 v[178:181], v151 offset:1024
	ds_read_b128 v[182:185], v151 offset:2048
	ds_read_b128 v[186:189], v151 offset:3072
	s_add_u32 s18, s18, 0xb0000
	s_addc_u32 s19, s19, 0
	s_mov_b32 m0, s28
	v_lshl_add_u64 v[230:231], s[18:19], 0, v[128:129]
	ds_read_b128 v[190:193], v150 offset:32768
	ds_read_b128 v[194:197], v150 offset:33792
	ds_read_b128 v[198:201], v150 offset:34816
	ds_read_b128 v[202:205], v150 offset:35840
	ds_read_b128 v[206:209], v150 offset:36864
	ds_read_b128 v[210:213], v150 offset:37888
	ds_read_b128 v[214:217], v150 offset:38912
	ds_read_b128 v[218:221], v150 offset:39936
	global_load_lds_dwordx4 v[230:231], off
	v_lshl_add_u64 v[230:231], s[18:19], 0, v[132:133]
	s_mov_b32 m0, s29
	s_nop 0
	global_load_lds_dwordx4 v[230:231], off
	s_nop 0
	s_waitcnt vmcnt(8)
	s_waitcnt lgkmcnt(0)
	s_barrier
	s_waitcnt lgkmcnt(0)
	v_mfma_f32_16x16x32_bf16 v[124:127], v[152:155], v[190:193], v[124:127]
	v_mfma_f32_16x16x32_bf16 v[120:123], v[160:163], v[190:193], v[120:123]
	v_mfma_f32_16x16x32_bf16 v[112:115], v[152:155], v[198:201], v[112:115]
	v_mfma_f32_16x16x32_bf16 v[104:107], v[160:163], v[198:201], v[104:107]
	v_mfma_f32_16x16x32_bf16 v[96:99], v[152:155], v[206:209], v[96:99]
	v_mfma_f32_16x16x32_bf16 v[88:91], v[160:163], v[206:209], v[88:91]
	v_mfma_f32_16x16x32_bf16 v[80:83], v[152:155], v[214:217], v[80:83]
	v_mfma_f32_16x16x32_bf16 v[72:75], v[160:163], v[214:217], v[72:75]
	v_mfma_f32_16x16x32_bf16 v[124:127], v[156:159], v[194:197], v[124:127]
	v_mfma_f32_16x16x32_bf16 v[120:123], v[168:171], v[194:197], v[120:123]
	v_mfma_f32_16x16x32_bf16 v[112:115], v[156:159], v[202:205], v[112:115]
	v_mfma_f32_16x16x32_bf16 v[104:107], v[168:171], v[202:205], v[104:107]
	v_mfma_f32_16x16x32_bf16 v[96:99], v[156:159], v[210:213], v[96:99]
	v_mfma_f32_16x16x32_bf16 v[88:91], v[168:171], v[210:213], v[88:91]
	v_mfma_f32_16x16x32_bf16 v[80:83], v[156:159], v[218:221], v[80:83]
	v_mfma_f32_16x16x32_bf16 v[72:75], v[168:171], v[218:221], v[72:75]
	v_mfma_f32_16x16x32_bf16 v[116:119], v[172:175], v[190:193], v[116:119]
	v_mfma_f32_16x16x32_bf16 v[108:111], v[182:185], v[190:193], v[108:111]
	v_mfma_f32_16x16x32_bf16 v[100:103], v[172:175], v[198:201], v[100:103]
	v_mfma_f32_16x16x32_bf16 v[92:95], v[182:185], v[198:201], v[92:95]
	v_mfma_f32_16x16x32_bf16 v[84:87], v[172:175], v[206:209], v[84:87]
	v_mfma_f32_16x16x32_bf16 v[76:79], v[182:185], v[206:209], v[76:79]
	v_mfma_f32_16x16x32_bf16 v[68:71], v[172:175], v[214:217], v[68:71]
	v_mfma_f32_16x16x32_bf16 v[64:67], v[182:185], v[214:217], v[64:67]
	v_mfma_f32_16x16x32_bf16 v[116:119], v[178:181], v[194:197], v[116:119]
	v_mfma_f32_16x16x32_bf16 v[108:111], v[186:189], v[194:197], v[108:111]
	v_mfma_f32_16x16x32_bf16 v[100:103], v[178:181], v[202:205], v[100:103]
	v_mfma_f32_16x16x32_bf16 v[92:95], v[186:189], v[202:205], v[92:95]
	v_mfma_f32_16x16x32_bf16 v[84:87], v[178:181], v[210:213], v[84:87]
	v_mfma_f32_16x16x32_bf16 v[76:79], v[186:189], v[210:213], v[76:79]
	v_mfma_f32_16x16x32_bf16 v[68:71], v[178:181], v[218:221], v[68:71]
	v_mfma_f32_16x16x32_bf16 v[64:67], v[186:189], v[218:221], v[64:67]
	s_barrier
; #define PG8_STAGE(bufoff, gbase, voff) do { _Pragma("unroll") for (int _i = 0; _i < 2; ++_i) \
;         __builtin_amdgcn_global_load_lds((const unsigned*)((const char*)(gbase) + (voff)[_i]), (PG8_LAS unsigned*)(lds + (bufoff) + ldsw + _i * 8192), 16, 0, 0); } while (0)
; #define PG8_LDA(dst, b, h) do { _Pragma("unroll") for (int m = 0; m < 4; ++m) _Pragma("unroll") for (int k = 0; k < 2; ++k) dst[m][k] = *(const PG8_LAS bf16x8*)(lds + PG8_SA(b, h) + aoff + m * 2048 + k * 1024); } while (0)
; #define PG8_MMA(ai, bj, At, Bt) do { __builtin_amdgcn_s_setprio(1); _Pragma("unroll") for (int m = 0; m < 4; ++m) _Pragma("unroll") for (int n = 0; n < 2; ++n) _Pragma("unroll") for (int k = 0; k < 2; ++k) \
;         acc[ai][bj][m][n] = __builtin_amdgcn_mfma_f32_16x16x32_bf16(Bt[n][k], At[m][k], acc[ai][bj][m][n], 0, 0, 0); __builtin_amdgcn_s_setprio(0); } while (0)
; #define PG8_WAIT_V(n) asm volatile("s_waitcnt vmcnt(" #n ")" ::: "memory")
; #define PG8_WAIT_L(n) asm volatile("s_waitcnt lgkmcnt(" #n ")" ::: "memory")
; #define PG8_BAR __builtin_amdgcn_s_barrier()
; #define PG8_SCHED __builtin_amdgcn_sched_barrier(0)
; template <class Epi, class Sched, bool ALIGN_EPI = false, bool SP2 = false>
; __device__ __forceinline__ void gemm_phase(PG8_LAS unsigned char* lds, const Gemm g, const Sched& S, const Epi& E, const int wid) {
;     ...
;             PG8_LDA(At, 1, 1); PG8_STAGE(PG8_SB(1, 0), b3, voffB); PG8_STAGE(PG8_SB(1, 1), b3 + hstep, voffB); PG8_STAGE(PG8_SA(1, 0), a3, voffA);
;             PG8_WAIT_V(8); PG8_WAIT_L(0); PG8_BAR; PG8_MMA(1, 0, At, B0); PG8_MMA(1, 1, At, B1); PG8_BAR; PG8_SCHED;
;     ...
;         if (!has_next) break;
; #pragma unroll
;         for (int a = 0; a < 2; ++a)
; #pragma unroll
;             for (int b = 0; b < 2; ++b)
; #pragma unroll
;                 for (int m = 0; m < 4; ++m)
; #pragma unroll
;                     for (int n = 0; n < 2; ++n) acc[a][b][m][n] = (f32x4){0.f, 0.f, 0.f, 0.f};
;         cur = nxt; cA = nA; cB = nB; ++ui;
	s_add_i32 s18, s43, s24
	v_lshl_add_u64 v[222:223], v[222:223], 0, s[10:11]
	s_mov_b32 m0, s18
	ds_read_b128 v[190:193], v150 offset:49152
	ds_read_b128 v[194:197], v150 offset:50176
	ds_read_b128 v[198:201], v150 offset:51200
	ds_read_b128 v[202:205], v150 offset:52224
	ds_read_b128 v[206:209], v150 offset:53248
	ds_read_b128 v[210:213], v150 offset:54272
	ds_read_b128 v[214:217], v150 offset:55296
	ds_read_b128 v[218:221], v150 offset:56320
	global_load_lds_dwordx4 v[222:223], off
	s_add_i32 m0, s18, 0x2000
	s_add_u32 s16, s16, 0xb0080
	v_lshl_add_u64 v[222:223], v[224:225], 0, s[10:11]
	s_addc_u32 s17, s17, 0
	s_add_i32 s18, s44, s24
	global_load_lds_dwordx4 v[222:223], off
	v_lshl_add_u64 v[222:223], s[16:17], 0, v[130:131]
	s_mov_b32 m0, s18
	s_nop 0
	global_load_lds_dwordx4 v[222:223], off
	v_lshl_add_u64 v[222:223], s[16:17], 0, v[134:135]
	s_add_i32 m0, s18, 0x2000
	s_nop 0
	global_load_lds_dwordx4 v[222:223], off
	v_lshl_add_u64 v[222:223], v[226:227], 0, s[10:11]
	s_mov_b32 m0, s31
	s_nop 0
	global_load_lds_dwordx4 v[222:223], off
	v_lshl_add_u64 v[222:223], v[228:229], 0, s[10:11]
	s_mov_b32 m0, s33
	s_nop 0
	global_load_lds_dwordx4 v[222:223], off
	s_waitcnt vmcnt(8)
	s_waitcnt lgkmcnt(0)
	s_barrier
	s_waitcnt lgkmcnt(0)
	v_mfma_f32_16x16x32_bf16 v[60:63], v[152:155], v[190:193], v[60:63]
	v_mfma_f32_16x16x32_bf16 v[56:59], v[160:163], v[190:193], v[56:59]
	v_mfma_f32_16x16x32_bf16 v[44:47], v[152:155], v[198:201], v[44:47]
	v_mfma_f32_16x16x32_bf16 v[40:43], v[160:163], v[198:201], v[40:43]
	v_mfma_f32_16x16x32_bf16 v[28:31], v[152:155], v[206:209], v[28:31]
	v_mfma_f32_16x16x32_bf16 v[24:27], v[160:163], v[206:209], v[24:27]
	v_mfma_f32_16x16x32_bf16 v[12:15], v[152:155], v[214:217], v[12:15]
	v_mfma_f32_16x16x32_bf16 v[8:11], v[160:163], v[214:217], v[8:11]
	v_mfma_f32_16x16x32_bf16 v[60:63], v[156:159], v[194:197], v[60:63]
	v_mfma_f32_16x16x32_bf16 v[56:59], v[168:171], v[194:197], v[56:59]
	v_mfma_f32_16x16x32_bf16 v[44:47], v[156:159], v[202:205], v[44:47]
	v_mfma_f32_16x16x32_bf16 v[40:43], v[168:171], v[202:205], v[40:43]
	v_mfma_f32_16x16x32_bf16 v[28:31], v[156:159], v[210:213], v[28:31]
	v_mfma_f32_16x16x32_bf16 v[24:27], v[168:171], v[210:213], v[24:27]
	v_mfma_f32_16x16x32_bf16 v[12:15], v[156:159], v[218:221], v[12:15]
	v_mfma_f32_16x16x32_bf16 v[8:11], v[168:171], v[218:221], v[8:11]
	v_mfma_f32_16x16x32_bf16 v[52:55], v[172:175], v[190:193], v[52:55]
	v_mfma_f32_16x16x32_bf16 v[48:51], v[182:185], v[190:193], v[48:51]
	v_mfma_f32_16x16x32_bf16 v[36:39], v[172:175], v[198:201], v[36:39]
	v_mfma_f32_16x16x32_bf16 v[32:35], v[182:185], v[198:201], v[32:35]
	v_mfma_f32_16x16x32_bf16 v[20:23], v[172:175], v[206:209], v[20:23]
	v_mfma_f32_16x16x32_bf16 v[16:19], v[182:185], v[206:209], v[16:19]
	v_mfma_f32_16x16x32_bf16 v[4:7], v[172:175], v[214:217], v[4:7]
	v_mfma_f32_16x16x32_bf16 v[0:3], v[182:185], v[214:217], v[0:3]
	v_mfma_f32_16x16x32_bf16 v[52:55], v[178:181], v[194:197], v[52:55]
	v_mfma_f32_16x16x32_bf16 v[48:51], v[186:189], v[194:197], v[48:51]
	v_mfma_f32_16x16x32_bf16 v[36:39], v[178:181], v[202:205], v[36:39]
	v_mfma_f32_16x16x32_bf16 v[32:35], v[186:189], v[202:205], v[32:35]
	v_mfma_f32_16x16x32_bf16 v[20:23], v[178:181], v[210:213], v[20:23]
	v_mfma_f32_16x16x32_bf16 v[16:19], v[186:189], v[210:213], v[16:19]
	v_mfma_f32_16x16x32_bf16 v[4:7], v[178:181], v[218:221], v[4:7]
	v_mfma_f32_16x16x32_bf16 v[0:3], v[186:189], v[218:221], v[0:3]
	s_barrier
	s_add_i32 s42, s42, 2
	s_add_u32 s14, s14, 0x100
	s_addc_u32 s15, s15, 0
	s_cmp_gt_u32 s42, 41
	s_cbranch_scc0 .LBB0_2460
	s_add_u32 s14, s40, 0xffffff00
	s_addc_u32 s15, s41, -1
	s_and_b64 vcc, exec, s[6:7]
	s_cbranch_vccnz .LBB0_2447
	v_mov_b32_e32 v0, 0
	s_mov_b32 s2, s37
	s_mov_b32 s20, s38
	s_mov_b64 s[8:9], s[12:13]
	s_mov_b32 s34, s39
	v_mov_b32_e32 v1, v0
	v_mov_b32_e32 v2, v0
	v_mov_b32_e32 v3, v0
	v_mov_b32_e32 v4, v0
	v_mov_b32_e32 v5, v0
	v_mov_b32_e32 v6, v0
	v_mov_b32_e32 v7, v0
	v_mov_b32_e32 v16, v0
	v_mov_b32_e32 v17, v0
	v_mov_b32_e32 v18, v0
	v_mov_b32_e32 v19, v0
	v_mov_b32_e32 v20, v0
	v_mov_b32_e32 v21, v0
	v_mov_b32_e32 v22, v0
	v_mov_b32_e32 v23, v0
	v_mov_b32_e32 v32, v0
	v_mov_b32_e32 v33, v0
	v_mov_b32_e32 v34, v0
	v_mov_b32_e32 v35, v0
	v_mov_b32_e32 v36, v0
	v_mov_b32_e32 v37, v0
	v_mov_b32_e32 v38, v0
	v_mov_b32_e32 v39, v0
	v_mov_b32_e32 v48, v0
	v_mov_b32_e32 v49, v0
	v_mov_b32_e32 v50, v0
	v_mov_b32_e32 v51, v0
	v_mov_b32_e32 v52, v0
	v_mov_b32_e32 v53, v0
	v_mov_b32_e32 v54, v0
	v_mov_b32_e32 v55, v0
	v_mov_b32_e32 v8, v0
	v_mov_b32_e32 v9, v0
	v_mov_b32_e32 v10, v0
	v_mov_b32_e32 v11, v0
	v_mov_b32_e32 v12, v0
	v_mov_b32_e32 v13, v0
	v_mov_b32_e32 v14, v0
	v_mov_b32_e32 v15, v0
	v_mov_b32_e32 v24, v0
	v_mov_b32_e32 v25, v0
	v_mov_b32_e32 v26, v0
	v_mov_b32_e32 v27, v0
	v_mov_b32_e32 v28, v0
	v_mov_b32_e32 v29, v0
	v_mov_b32_e32 v30, v0
	v_mov_b32_e32 v31, v0
	v_mov_b32_e32 v40, v0
	v_mov_b32_e32 v41, v0
	v_mov_b32_e32 v42, v0
	v_mov_b32_e32 v43, v0
	v_mov_b32_e32 v44, v0
	v_mov_b32_e32 v45, v0
	v_mov_b32_e32 v46, v0
	v_mov_b32_e32 v47, v0
	v_mov_b32_e32 v56, v0
	v_mov_b32_e32 v57, v0
	v_mov_b32_e32 v58, v0
	v_mov_b32_e32 v59, v0
	v_mov_b32_e32 v60, v0
	v_mov_b32_e32 v61, v0
	v_mov_b32_e32 v62, v0
	v_mov_b32_e32 v63, v0
	v_mov_b32_e32 v64, v0
	v_mov_b32_e32 v65, v0
	v_mov_b32_e32 v66, v0
	v_mov_b32_e32 v67, v0
	v_mov_b32_e32 v68, v0
	v_mov_b32_e32 v69, v0
	v_mov_b32_e32 v70, v0
	v_mov_b32_e32 v71, v0
	v_mov_b32_e32 v76, v0
	v_mov_b32_e32 v77, v0
	v_mov_b32_e32 v78, v0
	v_mov_b32_e32 v79, v0
	v_mov_b32_e32 v84, v0
	v_mov_b32_e32 v85, v0
	v_mov_b32_e32 v86, v0
	v_mov_b32_e32 v87, v0
	v_mov_b32_e32 v92, v0
	v_mov_b32_e32 v93, v0
	v_mov_b32_e32 v94, v0
	v_mov_b32_e32 v95, v0
	v_mov_b32_e32 v100, v0
	v_mov_b32_e32 v101, v0
	v_mov_b32_e32 v102, v0
	v_mov_b32_e32 v103, v0
	v_mov_b32_e32 v108, v0
	v_mov_b32_e32 v109, v0
	v_mov_b32_e32 v110, v0
	v_mov_b32_e32 v111, v0
	v_mov_b32_e32 v116, v0
	v_mov_b32_e32 v117, v0
	v_mov_b32_e32 v118, v0
	v_mov_b32_e32 v119, v0
	v_mov_b32_e32 v72, v0
	v_mov_b32_e32 v73, v0
	v_mov_b32_e32 v74, v0
	v_mov_b32_e32 v75, v0
	v_mov_b32_e32 v80, v0
	v_mov_b32_e32 v81, v0
	v_mov_b32_e32 v82, v0
	v_mov_b32_e32 v83, v0
	v_mov_b32_e32 v88, v0
	v_mov_b32_e32 v89, v0
	v_mov_b32_e32 v90, v0
	v_mov_b32_e32 v91, v0
	v_mov_b32_e32 v96, v0
	v_mov_b32_e32 v97, v0
	v_mov_b32_e32 v98, v0
	v_mov_b32_e32 v99, v0
	v_mov_b32_e32 v104, v0
	v_mov_b32_e32 v105, v0
	v_mov_b32_e32 v106, v0
	v_mov_b32_e32 v107, v0
	v_mov_b32_e32 v112, v0
	v_mov_b32_e32 v113, v0
	v_mov_b32_e32 v114, v0
	v_mov_b32_e32 v115, v0
	v_mov_b32_e32 v120, v0
	v_mov_b32_e32 v121, v0
	v_mov_b32_e32 v122, v0
	v_mov_b32_e32 v123, v0
	v_mov_b32_e32 v124, v0
	v_mov_b32_e32 v125, v0
	v_mov_b32_e32 v126, v0
	v_mov_b32_e32 v127, v0
	s_andn2_b64 vcc, exec, s[0:1]
	s_cbranch_vccnz .LBB0_2448
